# GEMM epilogues: packed f32 VALU ops (v_pk_mul_f32 / v_pk_fma_f32) unpacked into scalar ops (bit-identical math, packed f32 is slow here)
# speedup vs baseline: 1.0516x; 1.0048x over previous
; __device__ __forceinline__ unsigned cvt_pk_bf16(float lo, float hi) { unsigned r; asm volatile("v_cvt_pk_bf16_f32 %0, %1, %2" : "=v"(r) : "v"(lo), "v"(hi)); return r; }
;     __device__ __forceinline__ void operator()(const f32x4 (&acc)[2][2][4][2], const Unit& u, int wr, int wc, int fr, int fq) const {
;         const int row0 = u.pm * BM + wr * 64 + fr; const int colt = u.pn * BM;
;         const float sc0 = (colt < qcols) ? qscale : 1.f;
;         const int col0 = colt + wc * 32 + 8 * fq;
; #pragma unroll
;         for (int ai = 0; ai < 2; ++ai)
; #pragma unroll
;             for (int m = 0; m < 4; ++m) { const int row = row0 + ai * HALF + m * 16; bf16_t* rowp = O + (size_t)row * ldc + col0;
;                 float sc = sc0; if (ROWSCALE) sc *= 1.0f / sqrtf(SS[row] * (1.0f / 1024.0f) + 1e-6f);
; #pragma unroll
;                 for (int bj = 0; bj < 2; ++bj) { const f32x4 v0 = acc[ai][bj][m][0] * sc, v1 = acc[ai][bj][m][1] * sc;
;                     u32x4 w; w.x = cvt_pk_bf16(v0[0], v0[1]); w.y = cvt_pk_bf16(v0[2], v0[3]); w.z = cvt_pk_bf16(v1[0], v1[1]); w.w = cvt_pk_bf16(v1[2], v1[3]);
;                     *(u32x4*)(rowp + bj * HALF) = w; } }
;     }
.LBB0_182:
	s_cmp_lt_i32 s79, 4
	v_lshl_or_b32 v148, s79, 8, v151
	v_lshl_add_u32 v161, s50, 8, v145
	s_cselect_b64 vcc, -1, 0
	v_ashrrev_i32_e32 v149, 31, v148
	v_mov_b64_e32 v[146:147], s[40:41]
	v_cndmask_b32_e32 v144, 1.0, v155, vcc
	v_mad_i64_i32 v[156:157], s[8:9], v161, s78, v[146:147]
	v_lshlrev_b64 v[148:149], 1, v[148:149]
	v_lshl_add_u64 v[156:157], v[156:157], 0, v[148:149]
	v_mul_f32_e32 v126, v144, v126
	v_mul_f32_e32 v127, v144, v127
	v_mul_f32_e32 v124, v144, v124
	v_mul_f32_e32 v125, v144, v125
	v_mul_f32_e32 v158, v144, v122
	v_mul_f32_e32 v159, v144, v123
	v_mul_f32_e32 v122, v144, v120
	v_mul_f32_e32 v123, v144, v121
	v_cvt_pk_bf16_f32 v120, v124, v125
	v_cvt_pk_bf16_f32 v121, v126, v127
	v_cvt_pk_bf16_f32 v122, v122, v123
	v_cvt_pk_bf16_f32 v123, v158, v159
	global_store_dwordx4 v[156:157], v[120:123], off
	v_mul_f32_e32 v116, v144, v116
	v_mul_f32_e32 v117, v144, v117
	v_mul_f32_e32 v118, v144, v118
	v_mul_f32_e32 v119, v144, v119
	v_mul_f32_e32 v120, v144, v110
	v_mul_f32_e32 v121, v144, v111
	v_mul_f32_e32 v110, v144, v108
	v_mul_f32_e32 v111, v144, v109
	v_cvt_pk_bf16_f32 v108, v116, v117
	v_cvt_pk_bf16_f32 v109, v118, v119
	v_cvt_pk_bf16_f32 v110, v110, v111
	v_cvt_pk_bf16_f32 v111, v120, v121
	global_store_dwordx4 v[156:157], v[108:111], off offset:256
	v_mul_f32_e32 v112, v144, v112
	v_mul_f32_e32 v113, v144, v113
	v_mul_f32_e32 v100, v144, v100
	v_mul_f32_e32 v101, v144, v101
	v_or_b32_e32 v108, 16, v161
	v_mad_i64_i32 v[108:109], s[8:9], v108, s78, v[146:147]
	v_lshl_add_u64 v[108:109], v[108:109], 0, v[148:149]
	v_mul_f32_e32 v110, v144, v114
	v_mul_f32_e32 v111, v144, v115
	v_mul_f32_e32 v114, v144, v106
	v_mul_f32_e32 v115, v144, v107
	v_mul_f32_e32 v106, v144, v104
	v_mul_f32_e32 v107, v144, v105
	v_cvt_pk_bf16_f32 v104, v112, v113
	v_cvt_pk_bf16_f32 v105, v110, v111
	v_cvt_pk_bf16_f32 v106, v106, v107
	v_cvt_pk_bf16_f32 v107, v114, v115
	global_store_dwordx4 v[108:109], v[104:107], off
	v_mul_f32_e32 v102, v144, v102
	v_mul_f32_e32 v103, v144, v103
	v_mul_f32_e32 v96, v144, v96
	v_mul_f32_e32 v97, v144, v97
	v_mul_f32_e32 v104, v144, v94
	v_mul_f32_e32 v105, v144, v95
	v_mul_f32_e32 v94, v144, v92
	v_mul_f32_e32 v95, v144, v93
	v_cvt_pk_bf16_f32 v92, v100, v101
	v_cvt_pk_bf16_f32 v93, v102, v103
	v_cvt_pk_bf16_f32 v94, v94, v95
	v_cvt_pk_bf16_f32 v95, v104, v105
	global_store_dwordx4 v[108:109], v[92:95], off offset:256
	v_mul_f32_e32 v84, v144, v84
	v_mul_f32_e32 v85, v144, v85
	v_mul_f32_e32 v86, v144, v86
	v_mul_f32_e32 v87, v144, v87
	v_or_b32_e32 v92, 32, v161
	v_mad_i64_i32 v[92:93], s[8:9], v92, s78, v[146:147]
	v_lshl_add_u64 v[92:93], v[92:93], 0, v[148:149]
	v_mul_f32_e32 v94, v144, v98
	v_mul_f32_e32 v95, v144, v99
	v_mul_f32_e32 v98, v144, v90
	v_mul_f32_e32 v99, v144, v91
	v_mul_f32_e32 v90, v144, v88
	v_mul_f32_e32 v91, v144, v89
	v_cvt_pk_bf16_f32 v88, v96, v97
	v_cvt_pk_bf16_f32 v89, v94, v95
	v_cvt_pk_bf16_f32 v90, v90, v91
	v_cvt_pk_bf16_f32 v91, v98, v99
	global_store_dwordx4 v[92:93], v[88:91], off
	v_mul_f32_e32 v80, v144, v80
	v_mul_f32_e32 v81, v144, v81
	v_mul_f32_e32 v68, v144, v68
	v_mul_f32_e32 v69, v144, v69
	v_mul_f32_e32 v88, v144, v78
	v_mul_f32_e32 v89, v144, v79
	v_mul_f32_e32 v78, v144, v76
	v_mul_f32_e32 v79, v144, v77
	v_cvt_pk_bf16_f32 v76, v84, v85
	v_cvt_pk_bf16_f32 v77, v86, v87
	v_cvt_pk_bf16_f32 v78, v78, v79
	v_cvt_pk_bf16_f32 v79, v88, v89
	global_store_dwordx4 v[92:93], v[76:79], off offset:256
	v_mul_f32_e32 v70, v144, v70
	v_mul_f32_e32 v71, v144, v71
	v_mul_f32_e32 v62, v144, v62
	v_mul_f32_e32 v63, v144, v63
	v_or_b32_e32 v76, 48, v161
	v_mad_i64_i32 v[76:77], s[8:9], v76, s78, v[146:147]
	v_lshl_add_u64 v[76:77], v[76:77], 0, v[148:149]
	v_mul_f32_e32 v78, v144, v82
	v_mul_f32_e32 v79, v144, v83
	v_mul_f32_e32 v82, v144, v74
	v_mul_f32_e32 v83, v144, v75
	v_mul_f32_e32 v74, v144, v72
	v_mul_f32_e32 v75, v144, v73
	v_cvt_pk_bf16_f32 v72, v80, v81
	v_cvt_pk_bf16_f32 v73, v78, v79
	v_cvt_pk_bf16_f32 v74, v74, v75
	v_cvt_pk_bf16_f32 v75, v82, v83
	global_store_dwordx4 v[76:77], v[72:75], off
	v_mul_f32_e32 v60, v144, v60
	v_mul_f32_e32 v61, v144, v61
	v_mul_f32_e32 v52, v144, v52
	v_mul_f32_e32 v53, v144, v53
	v_mul_f32_e32 v72, v144, v66
; __device__ __forceinline__ unsigned cvt_pk_bf16(float lo, float hi) { unsigned r; asm volatile("v_cvt_pk_bf16_f32 %0, %1, %2" : "=v"(r) : "v"(lo), "v"(hi)); return r; }
; #define PG8_BAR __builtin_amdgcn_s_barrier()
;     __device__ __forceinline__ void operator()(const f32x4 (&acc)[2][2][4][2], const Unit& u, int wr, int wc, int fr, int fq) const {
;     ...
;             for (int m = 0; m < 4; ++m) { const int row = row0 + ai * HALF + m * 16; bf16_t* rowp = O + (size_t)row * ldc + col0;
;                 float sc = sc0; if (ROWSCALE) sc *= 1.0f / sqrtf(SS[row] * (1.0f / 1024.0f) + 1e-6f);
; #pragma unroll
;                 for (int bj = 0; bj < 2; ++bj) { const f32x4 v0 = acc[ai][bj][m][0] * sc, v1 = acc[ai][bj][m][1] * sc;
;                     u32x4 w; w.x = cvt_pk_bf16(v0[0], v0[1]); w.y = cvt_pk_bf16(v0[2], v0[3]); w.z = cvt_pk_bf16(v1[0], v1[1]); w.w = cvt_pk_bf16(v1[2], v1[3]);
;                     *(u32x4*)(rowp + bj * HALF) = w; } }
; template <class Epi, class Sched, bool ALIGN_EPI = false, bool SP2 = false>
; __device__ __forceinline__ void gemm_phase(PG8_LAS unsigned char* lds, const Gemm g, const Sched& S, const Epi& E) {
;     ...
;         if constexpr (ALIGN_EPI) { if (wr == 0) PG8_BAR; }
;         if constexpr (!Epi::AFTER_DRAIN) { E(acc, cur, wr, wc, fr, fq); S.done(cur); }
;         if (!has_next) break;
; #pragma unroll
;         for (int a = 0; a < 2; ++a)
; #pragma unroll
;             for (int b = 0; b < 2; ++b)
; #pragma unroll
;                 for (int m = 0; m < 4; ++m)
; #pragma unroll
;                     for (int n = 0; n < 2; ++n) acc[a][b][m][n] = (f32x4){0.f, 0.f, 0.f, 0.f};
;         cur = nxt; cA = nA; cB = nB; ++ui;
;         if constexpr (ALIGN_EPI) { if (wr == 1) PG8_BAR; }
	v_mul_f32_e32 v73, v144, v67
	v_mul_f32_e32 v66, v144, v64
	v_mul_f32_e32 v67, v144, v65
	v_cvt_pk_bf16_f32 v64, v68, v69
	v_cvt_pk_bf16_f32 v65, v70, v71
	v_cvt_pk_bf16_f32 v66, v66, v67
	v_cvt_pk_bf16_f32 v67, v72, v73
	global_store_dwordx4 v[76:77], v[64:67], off offset:256
	v_mul_f32_e32 v54, v144, v54
	v_mul_f32_e32 v55, v144, v55
	v_mul_f32_e32 v48, v144, v48
	v_mul_f32_e32 v49, v144, v49
	v_add_u32_e32 v64, 0x80, v161
	v_mad_i64_i32 v[64:65], s[8:9], v64, s78, v[146:147]
	v_lshl_add_u64 v[64:65], v[64:65], 0, v[148:149]
	v_mul_f32_e32 v66, v144, v58
	v_mul_f32_e32 v67, v144, v59
	v_mul_f32_e32 v58, v144, v56
	v_mul_f32_e32 v59, v144, v57
	v_cvt_pk_bf16_f32 v56, v60, v61
	v_cvt_pk_bf16_f32 v57, v62, v63
	v_cvt_pk_bf16_f32 v58, v58, v59
	v_cvt_pk_bf16_f32 v59, v66, v67
	global_store_dwordx4 v[64:65], v[56:59], off
	v_mul_f32_e32 v36, v144, v36
	v_mul_f32_e32 v37, v144, v37
	v_mul_f32_e32 v38, v144, v38
	v_mul_f32_e32 v39, v144, v39
	v_mul_f32_e32 v56, v144, v46
	v_mul_f32_e32 v57, v144, v47
	v_mul_f32_e32 v46, v144, v44
	v_mul_f32_e32 v47, v144, v45
	v_cvt_pk_bf16_f32 v44, v52, v53
	v_cvt_pk_bf16_f32 v45, v54, v55
	v_cvt_pk_bf16_f32 v46, v46, v47
	v_cvt_pk_bf16_f32 v47, v56, v57
	global_store_dwordx4 v[64:65], v[44:47], off offset:256
	v_mul_f32_e32 v32, v144, v32
	v_mul_f32_e32 v33, v144, v33
	v_mul_f32_e32 v20, v144, v20
	v_mul_f32_e32 v21, v144, v21
	v_add_u32_e32 v44, 0x90, v161
	v_mad_i64_i32 v[44:45], s[8:9], v44, s78, v[146:147]
	v_lshl_add_u64 v[44:45], v[44:45], 0, v[148:149]
	v_mul_f32_e32 v46, v144, v50
	v_mul_f32_e32 v47, v144, v51
	v_mul_f32_e32 v50, v144, v42
	v_mul_f32_e32 v51, v144, v43
	v_mul_f32_e32 v42, v144, v40
	v_mul_f32_e32 v43, v144, v41
	v_cvt_pk_bf16_f32 v40, v48, v49
	v_cvt_pk_bf16_f32 v41, v46, v47
	v_cvt_pk_bf16_f32 v42, v42, v43
	v_cvt_pk_bf16_f32 v43, v50, v51
	global_store_dwordx4 v[44:45], v[40:43], off
	v_mul_f32_e32 v22, v144, v22
	v_mul_f32_e32 v23, v144, v23
	v_mul_f32_e32 v16, v144, v16
	v_mul_f32_e32 v17, v144, v17
	v_mul_f32_e32 v40, v144, v30
	v_mul_f32_e32 v41, v144, v31
	v_mul_f32_e32 v30, v144, v28
	v_mul_f32_e32 v31, v144, v29
	v_cvt_pk_bf16_f32 v28, v36, v37
	v_cvt_pk_bf16_f32 v29, v38, v39
	v_cvt_pk_bf16_f32 v30, v30, v31
	v_cvt_pk_bf16_f32 v31, v40, v41
	global_store_dwordx4 v[44:45], v[28:31], off offset:256
	s_andn2_b64 vcc, exec, s[4:5]
	s_mov_b64 s[4:5], -1
	v_add_u32_e32 v28, 0xa0, v161
	v_mad_i64_i32 v[28:29], s[8:9], v28, s78, v[146:147]
	v_lshl_add_u64 v[28:29], v[28:29], 0, v[148:149]
	v_mul_f32_e32 v30, v144, v34
	v_mul_f32_e32 v31, v144, v35
	v_mul_f32_e32 v34, v144, v26
	v_mul_f32_e32 v35, v144, v27
	v_mul_f32_e32 v26, v144, v24
	v_mul_f32_e32 v27, v144, v25
	v_cvt_pk_bf16_f32 v24, v32, v33
	v_cvt_pk_bf16_f32 v25, v30, v31
	v_cvt_pk_bf16_f32 v26, v26, v27
	v_cvt_pk_bf16_f32 v27, v34, v35
	global_store_dwordx4 v[28:29], v[24:27], off
	v_mul_f32_e32 v6, v144, v6
	v_mul_f32_e32 v7, v144, v7
	v_mul_f32_e32 v4, v144, v4
	v_mul_f32_e32 v5, v144, v5
	v_mul_f32_e32 v24, v144, v14
	v_mul_f32_e32 v25, v144, v15
	v_mul_f32_e32 v14, v144, v12
	v_mul_f32_e32 v15, v144, v13
	v_cvt_pk_bf16_f32 v12, v20, v21
	v_cvt_pk_bf16_f32 v13, v22, v23
	v_cvt_pk_bf16_f32 v14, v14, v15
	v_cvt_pk_bf16_f32 v15, v24, v25
	global_store_dwordx4 v[28:29], v[12:15], off offset:256
	s_nop 1
	v_add_u32_e32 v12, 0xb0, v161
	v_mad_i64_i32 v[12:13], s[8:9], v12, s78, v[146:147]
	v_lshl_add_u64 v[12:13], v[12:13], 0, v[148:149]
	v_mul_f32_e32 v14, v144, v18
	v_mul_f32_e32 v15, v144, v19
	v_mul_f32_e32 v18, v144, v10
	v_mul_f32_e32 v19, v144, v11
	v_mul_f32_e32 v10, v144, v8
	v_mul_f32_e32 v11, v144, v9
	v_cvt_pk_bf16_f32 v8, v16, v17
	v_cvt_pk_bf16_f32 v9, v14, v15
	v_cvt_pk_bf16_f32 v10, v10, v11
	v_cvt_pk_bf16_f32 v11, v18, v19
	global_store_dwordx4 v[12:13], v[8:11], off
	s_nop 1
	v_mul_f32_e32 v8, v144, v2
	v_mul_f32_e32 v9, v144, v3
	v_mul_f32_e32 v2, v144, v0
	v_mul_f32_e32 v3, v144, v1
	v_cvt_pk_bf16_f32 v0, v4, v5
	v_cvt_pk_bf16_f32 v1, v6, v7
	v_cvt_pk_bf16_f32 v2, v2, v3
	v_cvt_pk_bf16_f32 v3, v8, v9
	global_store_dwordx4 v[12:13], v[0:3], off offset:256
	s_cbranch_vccnz .LBB0_175
	s_andn2_b64 vcc, exec, s[0:1]
	s_cbranch_vccnz .LBB0_174
	s_barrier
	s_branch .LBB0_174

; __device__ __forceinline__ unsigned cvt_pk_bf16(float lo, float hi) { unsigned r; asm volatile("v_cvt_pk_bf16_f32 %0, %1, %2" : "=v"(r) : "v"(lo), "v"(hi)); return r; }
;     __device__ __forceinline__ void operator()(const f32x4 (&acc)[2][2][4][2], const Unit& u, int wr, int wc, int fr, int fq) const {
;         const int row0 = u.pm * BM + wr * 64 + fr; const int colt = u.pn * BM;
;         const float sc0 = (colt < qcols) ? qscale : 1.f;
;         const int col0 = colt + wc * 32 + 8 * fq;
; #pragma unroll
;         for (int ai = 0; ai < 2; ++ai)
; #pragma unroll
;             for (int m = 0; m < 4; ++m) { const int row = row0 + ai * HALF + m * 16; bf16_t* rowp = O + (size_t)row * ldc + col0;
;                 float sc = sc0; if (ROWSCALE) sc *= 1.0f / sqrtf(SS[row] * (1.0f / 1024.0f) + 1e-6f);
; #pragma unroll
;                 for (int bj = 0; bj < 2; ++bj) { const f32x4 v0 = acc[ai][bj][m][0] * sc, v1 = acc[ai][bj][m][1] * sc;
;                     u32x4 w; w.x = cvt_pk_bf16(v0[0], v0[1]); w.y = cvt_pk_bf16(v0[2], v0[3]); w.z = cvt_pk_bf16(v1[0], v1[1]); w.w = cvt_pk_bf16(v1[2], v1[3]);
;                     *(u32x4*)(rowp + bj * HALF) = w; } }
;     }
.LBB0_378:
	v_lshl_add_u32 v154, s66, 8, v145
	s_cmp_lt_i32 s92, 0
	v_lshl_or_b32 v146, s92, 8, v149
	v_ashrrev_i32_e32 v155, 31, v154
	s_cselect_b64 vcc, -1, 0
	v_ashrrev_i32_e32 v147, 31, v146
	v_lshlrev_b64 v[156:157], 11, v[154:155]
	v_cndmask_b32_e32 v144, 1.0, v153, vcc
	v_lshl_add_u64 v[156:157], s[58:59], 0, v[156:157]
	v_lshlrev_b64 v[158:159], 1, v[146:147]
	v_lshl_add_u64 v[146:147], v[156:157], 0, v[158:159]
	v_mul_f32_e32 v126, v144, v126
	v_mul_f32_e32 v127, v144, v127
	v_mul_f32_e32 v124, v144, v124
	v_mul_f32_e32 v125, v144, v125
	v_mul_f32_e32 v156, v144, v122
	v_mul_f32_e32 v157, v144, v123
	v_mul_f32_e32 v122, v144, v120
	v_mul_f32_e32 v123, v144, v121
	v_cvt_pk_bf16_f32 v120, v124, v125
	v_cvt_pk_bf16_f32 v121, v126, v127
	v_cvt_pk_bf16_f32 v122, v122, v123
	v_cvt_pk_bf16_f32 v123, v156, v157
	global_store_dwordx4 v[146:147], v[120:123], off
	v_mul_f32_e32 v116, v144, v116
	v_mul_f32_e32 v117, v144, v117
	v_mul_f32_e32 v118, v144, v118
	v_mul_f32_e32 v119, v144, v119
	v_mul_f32_e32 v120, v144, v110
	v_mul_f32_e32 v121, v144, v111
	v_mul_f32_e32 v110, v144, v108
	v_mul_f32_e32 v111, v144, v109
	v_cvt_pk_bf16_f32 v108, v116, v117
	v_cvt_pk_bf16_f32 v109, v118, v119
	v_cvt_pk_bf16_f32 v110, v110, v111
	v_cvt_pk_bf16_f32 v111, v120, v121
	global_store_dwordx4 v[146:147], v[108:111], off offset:256
	v_mul_f32_e32 v112, v144, v112
	v_mul_f32_e32 v113, v144, v113
	v_mul_f32_e32 v100, v144, v100
	v_mul_f32_e32 v101, v144, v101
	v_or_b32_e32 v108, 16, v154
	v_ashrrev_i32_e32 v109, 31, v108
	v_lshlrev_b64 v[108:109], 11, v[108:109]
	v_lshl_add_u64 v[108:109], s[58:59], 0, v[108:109]
	v_lshl_add_u64 v[108:109], v[108:109], 0, v[158:159]
	v_mul_f32_e32 v110, v144, v114
	v_mul_f32_e32 v111, v144, v115
	v_mul_f32_e32 v114, v144, v106
	v_mul_f32_e32 v115, v144, v107
	v_mul_f32_e32 v106, v144, v104
	v_mul_f32_e32 v107, v144, v105
	v_cvt_pk_bf16_f32 v104, v112, v113
	v_cvt_pk_bf16_f32 v105, v110, v111
	v_cvt_pk_bf16_f32 v106, v106, v107
	v_cvt_pk_bf16_f32 v107, v114, v115
	global_store_dwordx4 v[108:109], v[104:107], off
	v_mul_f32_e32 v102, v144, v102
	v_mul_f32_e32 v103, v144, v103
	v_mul_f32_e32 v96, v144, v96
	v_mul_f32_e32 v97, v144, v97
	v_mul_f32_e32 v104, v144, v94
	v_mul_f32_e32 v105, v144, v95
	v_mul_f32_e32 v94, v144, v92
	v_mul_f32_e32 v95, v144, v93
	v_cvt_pk_bf16_f32 v92, v100, v101
	v_cvt_pk_bf16_f32 v93, v102, v103
	v_cvt_pk_bf16_f32 v94, v94, v95
	v_cvt_pk_bf16_f32 v95, v104, v105
	global_store_dwordx4 v[108:109], v[92:95], off offset:256
	v_mul_f32_e32 v84, v144, v84
	v_mul_f32_e32 v85, v144, v85
	v_mul_f32_e32 v86, v144, v86
	v_mul_f32_e32 v87, v144, v87
	v_or_b32_e32 v92, 32, v154
	v_ashrrev_i32_e32 v93, 31, v92
	v_lshlrev_b64 v[92:93], 11, v[92:93]
	v_lshl_add_u64 v[92:93], s[58:59], 0, v[92:93]
	v_lshl_add_u64 v[92:93], v[92:93], 0, v[158:159]
	v_mul_f32_e32 v94, v144, v98
	v_mul_f32_e32 v95, v144, v99
	v_mul_f32_e32 v98, v144, v90
	v_mul_f32_e32 v99, v144, v91
	v_mul_f32_e32 v90, v144, v88
	v_mul_f32_e32 v91, v144, v89
	v_cvt_pk_bf16_f32 v88, v96, v97
	v_cvt_pk_bf16_f32 v89, v94, v95
	v_cvt_pk_bf16_f32 v90, v90, v91
	v_cvt_pk_bf16_f32 v91, v98, v99
	global_store_dwordx4 v[92:93], v[88:91], off
	v_mul_f32_e32 v80, v144, v80
	v_mul_f32_e32 v81, v144, v81
	v_mul_f32_e32 v70, v144, v70
	v_mul_f32_e32 v71, v144, v71
	v_mul_f32_e32 v88, v144, v78
	v_mul_f32_e32 v89, v144, v79
	v_mul_f32_e32 v78, v144, v76
	v_mul_f32_e32 v79, v144, v77
	v_cvt_pk_bf16_f32 v76, v84, v85
	v_cvt_pk_bf16_f32 v77, v86, v87
	v_cvt_pk_bf16_f32 v78, v78, v79
	v_cvt_pk_bf16_f32 v79, v88, v89
	global_store_dwordx4 v[92:93], v[76:79], off offset:256
	v_mul_f32_e32 v68, v144, v68
	v_mul_f32_e32 v69, v144, v69
	v_mul_f32_e32 v60, v144, v60
	v_mul_f32_e32 v61, v144, v61
	v_or_b32_e32 v76, 48, v154
	v_ashrrev_i32_e32 v77, 31, v76
	v_lshlrev_b64 v[76:77], 11, v[76:77]
	v_lshl_add_u64 v[76:77], s[58:59], 0, v[76:77]
	v_lshl_add_u64 v[76:77], v[76:77], 0, v[158:159]
	v_mul_f32_e32 v78, v144, v82
	v_mul_f32_e32 v79, v144, v83
	v_mul_f32_e32 v82, v144, v74
	v_mul_f32_e32 v83, v144, v75
	v_mul_f32_e32 v74, v144, v72
	v_mul_f32_e32 v75, v144, v73
	v_cvt_pk_bf16_f32 v72, v80, v81
	v_cvt_pk_bf16_f32 v73, v78, v79
	v_cvt_pk_bf16_f32 v74, v74, v75
	v_cvt_pk_bf16_f32 v75, v82, v83
	global_store_dwordx4 v[76:77], v[72:75], off
	v_mul_f32_e32 v62, v144, v62
; __device__ __forceinline__ unsigned cvt_pk_bf16(float lo, float hi) { unsigned r; asm volatile("v_cvt_pk_bf16_f32 %0, %1, %2" : "=v"(r) : "v"(lo), "v"(hi)); return r; }
; #define PG8_BAR __builtin_amdgcn_s_barrier()
;     __device__ __forceinline__ void operator()(const f32x4 (&acc)[2][2][4][2], const Unit& u, int wr, int wc, int fr, int fq) const {
;     ...
;             for (int m = 0; m < 4; ++m) { const int row = row0 + ai * HALF + m * 16; bf16_t* rowp = O + (size_t)row * ldc + col0;
;                 float sc = sc0; if (ROWSCALE) sc *= 1.0f / sqrtf(SS[row] * (1.0f / 1024.0f) + 1e-6f);
; #pragma unroll
;                 for (int bj = 0; bj < 2; ++bj) { const f32x4 v0 = acc[ai][bj][m][0] * sc, v1 = acc[ai][bj][m][1] * sc;
;                     u32x4 w; w.x = cvt_pk_bf16(v0[0], v0[1]); w.y = cvt_pk_bf16(v0[2], v0[3]); w.z = cvt_pk_bf16(v1[0], v1[1]); w.w = cvt_pk_bf16(v1[2], v1[3]);
;                     *(u32x4*)(rowp + bj * HALF) = w; } }
; template <class Epi, class Sched, bool ALIGN_EPI = false, bool SP2 = false>
; __device__ __forceinline__ void gemm_phase(PG8_LAS unsigned char* lds, const Gemm g, const Sched& S, const Epi& E) {
;     ...
;         if constexpr (ALIGN_EPI) { if (wr == 0) PG8_BAR; }
;         if constexpr (!Epi::AFTER_DRAIN) { E(acc, cur, wr, wc, fr, fq); S.done(cur); }
;         if (!has_next) break;
; #pragma unroll
;         for (int a = 0; a < 2; ++a)
; #pragma unroll
;             for (int b = 0; b < 2; ++b)
; #pragma unroll
;                 for (int m = 0; m < 4; ++m)
; #pragma unroll
;                     for (int n = 0; n < 2; ++n) acc[a][b][m][n] = (f32x4){0.f, 0.f, 0.f, 0.f};
;         cur = nxt; cA = nA; cB = nB; ++ui;
;         if constexpr (ALIGN_EPI) { if (wr == 1) PG8_BAR; }
	v_mul_f32_e32 v63, v144, v63
	v_mul_f32_e32 v54, v144, v54
	v_mul_f32_e32 v55, v144, v55
	v_mul_f32_e32 v72, v144, v66
	v_mul_f32_e32 v73, v144, v67
	v_mul_f32_e32 v66, v144, v64
	v_mul_f32_e32 v67, v144, v65
	v_cvt_pk_bf16_f32 v64, v68, v69
	v_cvt_pk_bf16_f32 v65, v70, v71
	v_cvt_pk_bf16_f32 v66, v66, v67
	v_cvt_pk_bf16_f32 v67, v72, v73
	global_store_dwordx4 v[76:77], v[64:67], off offset:256
	v_mul_f32_e32 v52, v144, v52
	v_mul_f32_e32 v53, v144, v53
	v_mul_f32_e32 v48, v144, v48
	v_mul_f32_e32 v49, v144, v49
	v_mul_f32_e32 v66, v144, v58
	v_mul_f32_e32 v67, v144, v59
	v_mul_f32_e32 v58, v144, v56
	v_mul_f32_e32 v59, v144, v57
	v_cvt_pk_bf16_f32 v56, v60, v61
	v_add_co_u32_e32 v60, vcc, s88, v146
	v_cvt_pk_bf16_f32 v57, v62, v63
	v_cvt_pk_bf16_f32 v58, v58, v59
	v_cvt_pk_bf16_f32 v59, v66, v67
	v_lshl_add_u64 v[64:65], v[146:147], 0, s[0:1]
	s_nop 0
	v_addc_co_u32_e32 v61, vcc, 0, v147, vcc
	global_store_dwordx4 v[60:61], v[56:59], off
	v_mul_f32_e32 v38, v144, v38
	v_mul_f32_e32 v39, v144, v39
	v_mul_f32_e32 v36, v144, v36
	v_mul_f32_e32 v37, v144, v37
	v_mul_f32_e32 v56, v144, v46
	v_mul_f32_e32 v57, v144, v47
	v_mul_f32_e32 v46, v144, v44
	v_mul_f32_e32 v47, v144, v45
	v_cvt_pk_bf16_f32 v44, v52, v53
	v_cvt_pk_bf16_f32 v45, v54, v55
	v_cvt_pk_bf16_f32 v46, v46, v47
	v_cvt_pk_bf16_f32 v47, v56, v57
	global_store_dwordx4 v[64:65], v[44:47], off offset:256
	v_mul_f32_e32 v32, v144, v32
	v_mul_f32_e32 v33, v144, v33
	v_mul_f32_e32 v22, v144, v22
	v_mul_f32_e32 v23, v144, v23
	v_mul_f32_e32 v46, v144, v50
	v_mul_f32_e32 v47, v144, v51
	v_mul_f32_e32 v50, v144, v42
	v_mul_f32_e32 v51, v144, v43
	v_mul_f32_e32 v42, v144, v40
	v_mul_f32_e32 v43, v144, v41
	v_cvt_pk_bf16_f32 v40, v48, v49
	v_cvt_pk_bf16_f32 v41, v46, v47
	v_add_co_u32_e32 v46, vcc, s89, v146
	v_cvt_pk_bf16_f32 v42, v42, v43
	v_cvt_pk_bf16_f32 v43, v50, v51
	v_lshl_add_u64 v[44:45], v[146:147], 0, s[38:39]
	s_nop 0
	v_addc_co_u32_e32 v47, vcc, 0, v147, vcc
	global_store_dwordx4 v[46:47], v[40:43], off
	v_mul_f32_e32 v20, v144, v20
	v_mul_f32_e32 v21, v144, v21
	v_mul_f32_e32 v16, v144, v16
	v_mul_f32_e32 v17, v144, v17
	v_mul_f32_e32 v40, v144, v30
	v_mul_f32_e32 v41, v144, v31
	v_mul_f32_e32 v30, v144, v28
	v_mul_f32_e32 v31, v144, v29
	v_cvt_pk_bf16_f32 v28, v36, v37
	v_cvt_pk_bf16_f32 v29, v38, v39
	v_cvt_pk_bf16_f32 v30, v30, v31
	v_cvt_pk_bf16_f32 v31, v40, v41
	global_store_dwordx4 v[44:45], v[28:31], off offset:256
	v_mul_f32_e32 v6, v144, v6
	v_mul_f32_e32 v7, v144, v7
	v_mul_f32_e32 v4, v144, v4
	v_mul_f32_e32 v5, v144, v5
	v_mul_f32_e32 v30, v144, v34
	v_mul_f32_e32 v31, v144, v35
	v_mul_f32_e32 v34, v144, v26
	v_mul_f32_e32 v35, v144, v27
	v_mul_f32_e32 v26, v144, v24
	v_mul_f32_e32 v27, v144, v25
	v_cvt_pk_bf16_f32 v24, v32, v33
	v_cvt_pk_bf16_f32 v25, v30, v31
	v_add_co_u32_e32 v30, vcc, s90, v146
	v_cvt_pk_bf16_f32 v26, v26, v27
	v_cvt_pk_bf16_f32 v27, v34, v35
	v_lshl_add_u64 v[28:29], v[146:147], 0, s[42:43]
	s_nop 0
	v_addc_co_u32_e32 v31, vcc, 0, v147, vcc
	global_store_dwordx4 v[30:31], v[24:27], off
	s_nop 1
	v_mul_f32_e32 v24, v144, v14
	v_mul_f32_e32 v25, v144, v15
	v_mul_f32_e32 v14, v144, v12
	v_mul_f32_e32 v15, v144, v13
	v_cvt_pk_bf16_f32 v12, v20, v21
	v_cvt_pk_bf16_f32 v13, v22, v23
	v_cvt_pk_bf16_f32 v14, v14, v15
	v_cvt_pk_bf16_f32 v15, v24, v25
	global_store_dwordx4 v[28:29], v[12:15], off offset:256
	s_nop 1
	v_mul_f32_e32 v14, v144, v18
	v_mul_f32_e32 v15, v144, v19
	v_mul_f32_e32 v18, v144, v10
	v_mul_f32_e32 v19, v144, v11
	v_mul_f32_e32 v10, v144, v8
	v_mul_f32_e32 v11, v144, v9
	v_cvt_pk_bf16_f32 v8, v16, v17
	v_cvt_pk_bf16_f32 v9, v14, v15
	v_add_co_u32_e32 v14, vcc, s91, v146
	v_lshl_add_u64 v[12:13], v[146:147], 0, s[48:49]
	s_nop 0
	v_addc_co_u32_e32 v15, vcc, 0, v147, vcc
	v_cvt_pk_bf16_f32 v10, v10, v11
	v_cvt_pk_bf16_f32 v11, v18, v19
	global_store_dwordx4 v[14:15], v[8:11], off
	s_andn2_b64 vcc, exec, s[4:5]
	s_mov_b64 s[4:5], -1
	v_mul_f32_e32 v8, v144, v2
	v_mul_f32_e32 v9, v144, v3
	v_mul_f32_e32 v2, v144, v0
	v_mul_f32_e32 v3, v144, v1
	v_cvt_pk_bf16_f32 v0, v4, v5
	v_cvt_pk_bf16_f32 v1, v6, v7
	v_cvt_pk_bf16_f32 v2, v2, v3
	v_cvt_pk_bf16_f32 v3, v8, v9
	global_store_dwordx4 v[12:13], v[0:3], off offset:256
	s_cbranch_vccnz .LBB0_367
	s_andn2_b64 vcc, exec, s[6:7]
	s_cbranch_vccnz .LBB0_366
	s_barrier
	s_branch .LBB0_366

; __device__ __forceinline__ unsigned cvt_pk_bf16(float lo, float hi) { unsigned r; asm volatile("v_cvt_pk_bf16_f32 %0, %1, %2" : "=v"(r) : "v"(lo), "v"(hi)); return r; }
;     __device__ __forceinline__ void operator()(const f32x4 (&acc)[2][2][4][2], const Unit& u, int wr, int wc, int fr, int fq) const {
;         const int row0 = u.pm * BM + wr * 64 + fr; const int colt = u.pn * BM;
;         const float sc0 = (colt < qcols) ? qscale : 1.f;
;         const int col0 = colt + wc * 32 + 8 * fq;
; #pragma unroll
;         for (int ai = 0; ai < 2; ++ai)
; #pragma unroll
;             for (int m = 0; m < 4; ++m) { const int row = row0 + ai * HALF + m * 16; bf16_t* rowp = O + (size_t)row * ldc + col0;
;                 float sc = sc0; if (ROWSCALE) sc *= 1.0f / sqrtf(SS[row] * (1.0f / 1024.0f) + 1e-6f);
; #pragma unroll
;                 for (int bj = 0; bj < 2; ++bj) { const f32x4 v0 = acc[ai][bj][m][0] * sc, v1 = acc[ai][bj][m][1] * sc;
;                     u32x4 w; w.x = cvt_pk_bf16(v0[0], v0[1]); w.y = cvt_pk_bf16(v0[2], v0[3]); w.z = cvt_pk_bf16(v1[0], v1[1]); w.w = cvt_pk_bf16(v1[2], v1[3]);
;                     *(u32x4*)(rowp + bj * HALF) = w; } }
;     }
.LBB0_643:
	v_lshl_add_u32 v164, s89, 8, v156
	s_cmp_lt_i32 s90, 0
	v_lshl_or_b32 v146, s90, 8, v158
	v_ashrrev_i32_e32 v165, 31, v164
	s_cselect_b64 vcc, -1, 0
	v_ashrrev_i32_e32 v147, 31, v146
	v_lshlrev_b64 v[166:167], 11, v[164:165]
	v_cndmask_b32_e32 v144, 1.0, v163, vcc
	v_lshl_add_u64 v[166:167], s[58:59], 0, v[166:167]
	v_lshlrev_b64 v[168:169], 1, v[146:147]
	v_lshl_add_u64 v[146:147], v[166:167], 0, v[168:169]
	v_mul_f32_e32 v126, v144, v126
	v_mul_f32_e32 v127, v144, v127
	v_mul_f32_e32 v124, v144, v124
	v_mul_f32_e32 v125, v144, v125
	v_mul_f32_e32 v166, v144, v122
	v_mul_f32_e32 v167, v144, v123
	v_mul_f32_e32 v122, v144, v120
	v_mul_f32_e32 v123, v144, v121
	v_cvt_pk_bf16_f32 v120, v124, v125
	v_cvt_pk_bf16_f32 v121, v126, v127
	v_cvt_pk_bf16_f32 v122, v122, v123
	v_cvt_pk_bf16_f32 v123, v166, v167
	global_store_dwordx4 v[146:147], v[120:123], off
	v_mul_f32_e32 v116, v144, v116
	v_mul_f32_e32 v117, v144, v117
	v_mul_f32_e32 v118, v144, v118
	v_mul_f32_e32 v119, v144, v119
	v_mul_f32_e32 v120, v144, v110
	v_mul_f32_e32 v121, v144, v111
	v_mul_f32_e32 v110, v144, v108
	v_mul_f32_e32 v111, v144, v109
	v_cvt_pk_bf16_f32 v108, v116, v117
	v_cvt_pk_bf16_f32 v109, v118, v119
	v_cvt_pk_bf16_f32 v110, v110, v111
	v_cvt_pk_bf16_f32 v111, v120, v121
	global_store_dwordx4 v[146:147], v[108:111], off offset:256
	v_mul_f32_e32 v112, v144, v112
	v_mul_f32_e32 v113, v144, v113
	v_mul_f32_e32 v100, v144, v100
	v_mul_f32_e32 v101, v144, v101
	v_or_b32_e32 v108, 16, v164
	v_ashrrev_i32_e32 v109, 31, v108
	v_lshlrev_b64 v[108:109], 11, v[108:109]
	v_lshl_add_u64 v[108:109], s[58:59], 0, v[108:109]
	v_lshl_add_u64 v[108:109], v[108:109], 0, v[168:169]
	v_mul_f32_e32 v110, v144, v114
	v_mul_f32_e32 v111, v144, v115
	v_mul_f32_e32 v114, v144, v106
	v_mul_f32_e32 v115, v144, v107
	v_mul_f32_e32 v106, v144, v104
	v_mul_f32_e32 v107, v144, v105
	v_cvt_pk_bf16_f32 v104, v112, v113
	v_cvt_pk_bf16_f32 v105, v110, v111
	v_cvt_pk_bf16_f32 v106, v106, v107
	v_cvt_pk_bf16_f32 v107, v114, v115
	global_store_dwordx4 v[108:109], v[104:107], off
	v_mul_f32_e32 v102, v144, v102
	v_mul_f32_e32 v103, v144, v103
	v_mul_f32_e32 v96, v144, v96
	v_mul_f32_e32 v97, v144, v97
	v_mul_f32_e32 v104, v144, v94
	v_mul_f32_e32 v105, v144, v95
	v_mul_f32_e32 v94, v144, v92
	v_mul_f32_e32 v95, v144, v93
	v_cvt_pk_bf16_f32 v92, v100, v101
	v_cvt_pk_bf16_f32 v93, v102, v103
	v_cvt_pk_bf16_f32 v94, v94, v95
	v_cvt_pk_bf16_f32 v95, v104, v105
	global_store_dwordx4 v[108:109], v[92:95], off offset:256
	v_mul_f32_e32 v84, v144, v84
	v_mul_f32_e32 v85, v144, v85
	v_mul_f32_e32 v86, v144, v86
	v_mul_f32_e32 v87, v144, v87
	v_or_b32_e32 v92, 32, v164
	v_ashrrev_i32_e32 v93, 31, v92
	v_lshlrev_b64 v[92:93], 11, v[92:93]
	v_lshl_add_u64 v[92:93], s[58:59], 0, v[92:93]
	v_lshl_add_u64 v[92:93], v[92:93], 0, v[168:169]
	v_mul_f32_e32 v94, v144, v98
	v_mul_f32_e32 v95, v144, v99
	v_mul_f32_e32 v98, v144, v90
	v_mul_f32_e32 v99, v144, v91
	v_mul_f32_e32 v90, v144, v88
	v_mul_f32_e32 v91, v144, v89
	v_cvt_pk_bf16_f32 v88, v96, v97
	v_cvt_pk_bf16_f32 v89, v94, v95
	v_cvt_pk_bf16_f32 v90, v90, v91
	v_cvt_pk_bf16_f32 v91, v98, v99
	global_store_dwordx4 v[92:93], v[88:91], off
	v_mul_f32_e32 v80, v144, v80
	v_mul_f32_e32 v81, v144, v81
	v_mul_f32_e32 v70, v144, v70
	v_mul_f32_e32 v71, v144, v71
	v_mul_f32_e32 v88, v144, v78
	v_mul_f32_e32 v89, v144, v79
	v_mul_f32_e32 v78, v144, v76
	v_mul_f32_e32 v79, v144, v77
	v_cvt_pk_bf16_f32 v76, v84, v85
	v_cvt_pk_bf16_f32 v77, v86, v87
	v_cvt_pk_bf16_f32 v78, v78, v79
	v_cvt_pk_bf16_f32 v79, v88, v89
	global_store_dwordx4 v[92:93], v[76:79], off offset:256
	v_mul_f32_e32 v68, v144, v68
	v_mul_f32_e32 v69, v144, v69
	v_mul_f32_e32 v60, v144, v60
	v_mul_f32_e32 v61, v144, v61
	v_or_b32_e32 v76, 48, v164
	v_ashrrev_i32_e32 v77, 31, v76
	v_lshlrev_b64 v[76:77], 11, v[76:77]
	v_lshl_add_u64 v[76:77], s[58:59], 0, v[76:77]
	v_lshl_add_u64 v[76:77], v[76:77], 0, v[168:169]
	v_mul_f32_e32 v78, v144, v82
	v_mul_f32_e32 v79, v144, v83
	v_mul_f32_e32 v82, v144, v74
	v_mul_f32_e32 v83, v144, v75
	v_mul_f32_e32 v74, v144, v72
	v_mul_f32_e32 v75, v144, v73
	v_cvt_pk_bf16_f32 v72, v80, v81
	v_cvt_pk_bf16_f32 v73, v78, v79
	v_cvt_pk_bf16_f32 v74, v74, v75
	v_cvt_pk_bf16_f32 v75, v82, v83
	global_store_dwordx4 v[76:77], v[72:75], off
	v_mul_f32_e32 v62, v144, v62
; __device__ __forceinline__ unsigned cvt_pk_bf16(float lo, float hi) { unsigned r; asm volatile("v_cvt_pk_bf16_f32 %0, %1, %2" : "=v"(r) : "v"(lo), "v"(hi)); return r; }
; #define PG8_BAR __builtin_amdgcn_s_barrier()
;     __device__ __forceinline__ void operator()(const f32x4 (&acc)[2][2][4][2], const Unit& u, int wr, int wc, int fr, int fq) const {
;     ...
;             for (int m = 0; m < 4; ++m) { const int row = row0 + ai * HALF + m * 16; bf16_t* rowp = O + (size_t)row * ldc + col0;
;                 float sc = sc0; if (ROWSCALE) sc *= 1.0f / sqrtf(SS[row] * (1.0f / 1024.0f) + 1e-6f);
; #pragma unroll
;                 for (int bj = 0; bj < 2; ++bj) { const f32x4 v0 = acc[ai][bj][m][0] * sc, v1 = acc[ai][bj][m][1] * sc;
;                     u32x4 w; w.x = cvt_pk_bf16(v0[0], v0[1]); w.y = cvt_pk_bf16(v0[2], v0[3]); w.z = cvt_pk_bf16(v1[0], v1[1]); w.w = cvt_pk_bf16(v1[2], v1[3]);
;                     *(u32x4*)(rowp + bj * HALF) = w; } }
; template <class Epi, class Sched, bool ALIGN_EPI = false, bool SP2 = false>
; __device__ __forceinline__ void gemm_phase(PG8_LAS unsigned char* lds, const Gemm g, const Sched& S, const Epi& E) {
;     ...
;         if constexpr (ALIGN_EPI) { if (wr == 0) PG8_BAR; }
;         if constexpr (!Epi::AFTER_DRAIN) { E(acc, cur, wr, wc, fr, fq); S.done(cur); }
;         if (!has_next) break;
; #pragma unroll
;         for (int a = 0; a < 2; ++a)
; #pragma unroll
;             for (int b = 0; b < 2; ++b)
; #pragma unroll
;                 for (int m = 0; m < 4; ++m)
; #pragma unroll
;                     for (int n = 0; n < 2; ++n) acc[a][b][m][n] = (f32x4){0.f, 0.f, 0.f, 0.f};
;         cur = nxt; cA = nA; cB = nB; ++ui;
;         if constexpr (ALIGN_EPI) { if (wr == 1) PG8_BAR; }
	v_mul_f32_e32 v63, v144, v63
	v_mul_f32_e32 v54, v144, v54
	v_mul_f32_e32 v55, v144, v55
	v_mul_f32_e32 v72, v144, v66
	v_mul_f32_e32 v73, v144, v67
	v_mul_f32_e32 v66, v144, v64
	v_mul_f32_e32 v67, v144, v65
	v_cvt_pk_bf16_f32 v64, v68, v69
	v_cvt_pk_bf16_f32 v65, v70, v71
	v_cvt_pk_bf16_f32 v66, v66, v67
	v_cvt_pk_bf16_f32 v67, v72, v73
	global_store_dwordx4 v[76:77], v[64:67], off offset:256
	v_mul_f32_e32 v52, v144, v52
	v_mul_f32_e32 v53, v144, v53
	v_mul_f32_e32 v48, v144, v48
	v_mul_f32_e32 v49, v144, v49
	v_mul_f32_e32 v66, v144, v58
	v_mul_f32_e32 v67, v144, v59
	v_mul_f32_e32 v58, v144, v56
	v_mul_f32_e32 v59, v144, v57
	v_cvt_pk_bf16_f32 v56, v60, v61
	v_add_co_u32_e32 v60, vcc, s81, v146
	v_cvt_pk_bf16_f32 v57, v62, v63
	v_cvt_pk_bf16_f32 v58, v58, v59
	v_cvt_pk_bf16_f32 v59, v66, v67
	v_lshl_add_u64 v[64:65], v[146:147], 0, s[38:39]
	s_nop 0
	v_addc_co_u32_e32 v61, vcc, 0, v147, vcc
	global_store_dwordx4 v[60:61], v[56:59], off
	v_mul_f32_e32 v38, v144, v38
	v_mul_f32_e32 v39, v144, v39
	v_mul_f32_e32 v36, v144, v36
	v_mul_f32_e32 v37, v144, v37
	v_mul_f32_e32 v56, v144, v46
	v_mul_f32_e32 v57, v144, v47
	v_mul_f32_e32 v46, v144, v44
	v_mul_f32_e32 v47, v144, v45
	v_cvt_pk_bf16_f32 v44, v52, v53
	v_cvt_pk_bf16_f32 v45, v54, v55
	v_cvt_pk_bf16_f32 v46, v46, v47
	v_cvt_pk_bf16_f32 v47, v56, v57
	global_store_dwordx4 v[64:65], v[44:47], off offset:256
	v_mul_f32_e32 v32, v144, v32
	v_mul_f32_e32 v33, v144, v33
	v_mul_f32_e32 v22, v144, v22
	v_mul_f32_e32 v23, v144, v23
	v_mul_f32_e32 v46, v144, v50
	v_mul_f32_e32 v47, v144, v51
	v_mul_f32_e32 v50, v144, v42
	v_mul_f32_e32 v51, v144, v43
	v_mul_f32_e32 v42, v144, v40
	v_mul_f32_e32 v43, v144, v41
	v_cvt_pk_bf16_f32 v40, v48, v49
	v_cvt_pk_bf16_f32 v41, v46, v47
	v_add_co_u32_e32 v46, vcc, s82, v146
	v_cvt_pk_bf16_f32 v42, v42, v43
	v_cvt_pk_bf16_f32 v43, v50, v51
	v_lshl_add_u64 v[44:45], v[146:147], 0, s[42:43]
	s_nop 0
	v_addc_co_u32_e32 v47, vcc, 0, v147, vcc
	global_store_dwordx4 v[46:47], v[40:43], off
	v_mul_f32_e32 v20, v144, v20
	v_mul_f32_e32 v21, v144, v21
	v_mul_f32_e32 v16, v144, v16
	v_mul_f32_e32 v17, v144, v17
	v_mul_f32_e32 v40, v144, v30
	v_mul_f32_e32 v41, v144, v31
	v_mul_f32_e32 v30, v144, v28
	v_mul_f32_e32 v31, v144, v29
	v_cvt_pk_bf16_f32 v28, v36, v37
	v_cvt_pk_bf16_f32 v29, v38, v39
	v_cvt_pk_bf16_f32 v30, v30, v31
	v_cvt_pk_bf16_f32 v31, v40, v41
	global_store_dwordx4 v[44:45], v[28:31], off offset:256
	v_mul_f32_e32 v6, v144, v6
	v_mul_f32_e32 v7, v144, v7
	v_mul_f32_e32 v4, v144, v4
	v_mul_f32_e32 v5, v144, v5
	v_mul_f32_e32 v30, v144, v34
	v_mul_f32_e32 v31, v144, v35
	v_mul_f32_e32 v34, v144, v26
	v_mul_f32_e32 v35, v144, v27
	v_mul_f32_e32 v26, v144, v24
	v_mul_f32_e32 v27, v144, v25
	v_cvt_pk_bf16_f32 v24, v32, v33
	v_cvt_pk_bf16_f32 v25, v30, v31
	v_add_co_u32_e32 v30, vcc, s83, v146
	v_cvt_pk_bf16_f32 v26, v26, v27
	v_cvt_pk_bf16_f32 v27, v34, v35
	v_lshl_add_u64 v[28:29], v[146:147], 0, s[48:49]
	s_nop 0
	v_addc_co_u32_e32 v31, vcc, 0, v147, vcc
	global_store_dwordx4 v[30:31], v[24:27], off
	s_nop 1
	v_mul_f32_e32 v24, v144, v14
	v_mul_f32_e32 v25, v144, v15
	v_mul_f32_e32 v14, v144, v12
	v_mul_f32_e32 v15, v144, v13
	v_cvt_pk_bf16_f32 v12, v20, v21
	v_cvt_pk_bf16_f32 v13, v22, v23
	v_cvt_pk_bf16_f32 v14, v14, v15
	v_cvt_pk_bf16_f32 v15, v24, v25
	global_store_dwordx4 v[28:29], v[12:15], off offset:256
	s_nop 1
	v_mul_f32_e32 v14, v144, v18
	v_mul_f32_e32 v15, v144, v19
	v_mul_f32_e32 v18, v144, v10
	v_mul_f32_e32 v19, v144, v11
	v_mul_f32_e32 v10, v144, v8
	v_mul_f32_e32 v11, v144, v9
	v_cvt_pk_bf16_f32 v8, v16, v17
	v_cvt_pk_bf16_f32 v9, v14, v15
	v_add_co_u32_e32 v14, vcc, s86, v146
	v_lshl_add_u64 v[12:13], v[146:147], 0, s[50:51]
	s_nop 0
	v_addc_co_u32_e32 v15, vcc, 0, v147, vcc
	v_cvt_pk_bf16_f32 v10, v10, v11
	v_cvt_pk_bf16_f32 v11, v18, v19
	global_store_dwordx4 v[14:15], v[8:11], off
	s_and_b64 vcc, exec, s[4:5]
	s_mov_b64 s[4:5], -1
	v_mul_f32_e32 v8, v144, v2
	v_mul_f32_e32 v9, v144, v3
	v_mul_f32_e32 v2, v144, v0
	v_mul_f32_e32 v3, v144, v1
	v_cvt_pk_bf16_f32 v0, v4, v5
	v_cvt_pk_bf16_f32 v1, v6, v7
	v_cvt_pk_bf16_f32 v2, v2, v3
	v_cvt_pk_bf16_f32 v3, v8, v9
	global_store_dwordx4 v[12:13], v[0:3], off offset:256
	s_cbranch_vccnz .LBB0_628
	s_andn2_b64 vcc, exec, s[12:13]
	s_cbranch_vccnz .LBB0_627
	s_barrier
	s_branch .LBB0_627

; __device__ __forceinline__ unsigned cvt_pk_bf16(float lo, float hi) { unsigned r; asm volatile("v_cvt_pk_bf16_f32 %0, %1, %2" : "=v"(r) : "v"(lo), "v"(hi)); return r; }
;     __device__ __forceinline__ void operator()(const f32x4 (&acc)[2][2][4][2], const Unit& u, int wr, int wc, int fr, int fq) const {
;         const int row0 = u.pm * BM + wr * 64 + fr; const int colt = u.pn * BM;
;         const float sc0 = (colt < qcols) ? qscale : 1.f;
;         const int col0 = colt + wc * 32 + 8 * fq;
; #pragma unroll
;         for (int ai = 0; ai < 2; ++ai)
; #pragma unroll
;             for (int m = 0; m < 4; ++m) { const int row = row0 + ai * HALF + m * 16; bf16_t* rowp = O + (size_t)row * ldc + col0;
;                 float sc = sc0; if (ROWSCALE) sc *= 1.0f / sqrtf(SS[row] * (1.0f / 1024.0f) + 1e-6f);
; #pragma unroll
;                 for (int bj = 0; bj < 2; ++bj) { const f32x4 v0 = acc[ai][bj][m][0] * sc, v1 = acc[ai][bj][m][1] * sc;
;                     u32x4 w; w.x = cvt_pk_bf16(v0[0], v0[1]); w.y = cvt_pk_bf16(v0[2], v0[3]); w.z = cvt_pk_bf16(v1[0], v1[1]); w.w = cvt_pk_bf16(v1[2], v1[3]);
;                     *(u32x4*)(rowp + bj * HALF) = w; } }
;     }
.LBB0_667:
	v_lshl_add_u32 v150, s48, 8, v141
	s_cmp_lt_i32 s90, 0
	v_lshl_or_b32 v142, s90, 8, v145
	v_ashrrev_i32_e32 v151, 31, v150
	s_cselect_b64 vcc, -1, 0
	v_ashrrev_i32_e32 v143, 31, v142
	v_lshlrev_b64 v[152:153], 11, v[150:151]
	v_cndmask_b32_e32 v140, 1.0, v149, vcc
	v_lshl_add_u64 v[152:153], s[36:37], 0, v[152:153]
	v_lshlrev_b64 v[154:155], 1, v[142:143]
	v_lshl_add_u64 v[142:143], v[152:153], 0, v[154:155]
	v_mul_f32_e32 v126, v140, v126
	v_mul_f32_e32 v127, v140, v127
	v_mul_f32_e32 v124, v140, v124
	v_mul_f32_e32 v125, v140, v125
	v_mul_f32_e32 v152, v140, v122
	v_mul_f32_e32 v153, v140, v123
	v_mul_f32_e32 v122, v140, v120
	v_mul_f32_e32 v123, v140, v121
	v_cvt_pk_bf16_f32 v120, v124, v125
	v_cvt_pk_bf16_f32 v121, v126, v127
	v_cvt_pk_bf16_f32 v122, v122, v123
	v_cvt_pk_bf16_f32 v123, v152, v153
	global_store_dwordx4 v[142:143], v[120:123], off
	v_mul_f32_e32 v116, v140, v116
	v_mul_f32_e32 v117, v140, v117
	v_mul_f32_e32 v118, v140, v118
	v_mul_f32_e32 v119, v140, v119
	v_mul_f32_e32 v120, v140, v110
	v_mul_f32_e32 v121, v140, v111
	v_mul_f32_e32 v110, v140, v108
	v_mul_f32_e32 v111, v140, v109
	v_cvt_pk_bf16_f32 v108, v116, v117
	v_cvt_pk_bf16_f32 v109, v118, v119
	v_cvt_pk_bf16_f32 v110, v110, v111
	v_cvt_pk_bf16_f32 v111, v120, v121
	global_store_dwordx4 v[142:143], v[108:111], off offset:256
	v_mul_f32_e32 v112, v140, v112
	v_mul_f32_e32 v113, v140, v113
	v_mul_f32_e32 v100, v140, v100
	v_mul_f32_e32 v101, v140, v101
	v_or_b32_e32 v108, 16, v150
	v_ashrrev_i32_e32 v109, 31, v108
	v_lshlrev_b64 v[108:109], 11, v[108:109]
	v_lshl_add_u64 v[108:109], s[36:37], 0, v[108:109]
	v_lshl_add_u64 v[108:109], v[108:109], 0, v[154:155]
	v_mul_f32_e32 v110, v140, v114
	v_mul_f32_e32 v111, v140, v115
	v_mul_f32_e32 v114, v140, v106
	v_mul_f32_e32 v115, v140, v107
	v_mul_f32_e32 v106, v140, v104
	v_mul_f32_e32 v107, v140, v105
	v_cvt_pk_bf16_f32 v104, v112, v113
	v_cvt_pk_bf16_f32 v105, v110, v111
	v_cvt_pk_bf16_f32 v106, v106, v107
	v_cvt_pk_bf16_f32 v107, v114, v115
	global_store_dwordx4 v[108:109], v[104:107], off
	v_mul_f32_e32 v102, v140, v102
	v_mul_f32_e32 v103, v140, v103
	v_mul_f32_e32 v96, v140, v96
	v_mul_f32_e32 v97, v140, v97
	v_mul_f32_e32 v104, v140, v94
	v_mul_f32_e32 v105, v140, v95
	v_mul_f32_e32 v94, v140, v92
	v_mul_f32_e32 v95, v140, v93
	v_cvt_pk_bf16_f32 v92, v100, v101
	v_cvt_pk_bf16_f32 v93, v102, v103
	v_cvt_pk_bf16_f32 v94, v94, v95
	v_cvt_pk_bf16_f32 v95, v104, v105
	global_store_dwordx4 v[108:109], v[92:95], off offset:256
	v_mul_f32_e32 v84, v140, v84
	v_mul_f32_e32 v85, v140, v85
	v_mul_f32_e32 v86, v140, v86
	v_mul_f32_e32 v87, v140, v87
	v_or_b32_e32 v92, 32, v150
	v_ashrrev_i32_e32 v93, 31, v92
	v_lshlrev_b64 v[92:93], 11, v[92:93]
	v_lshl_add_u64 v[92:93], s[36:37], 0, v[92:93]
	v_lshl_add_u64 v[92:93], v[92:93], 0, v[154:155]
	v_mul_f32_e32 v94, v140, v98
	v_mul_f32_e32 v95, v140, v99
	v_mul_f32_e32 v98, v140, v90
	v_mul_f32_e32 v99, v140, v91
	v_mul_f32_e32 v90, v140, v88
	v_mul_f32_e32 v91, v140, v89
	v_cvt_pk_bf16_f32 v88, v96, v97
	v_cvt_pk_bf16_f32 v89, v94, v95
	v_cvt_pk_bf16_f32 v90, v90, v91
	v_cvt_pk_bf16_f32 v91, v98, v99
	global_store_dwordx4 v[92:93], v[88:91], off
	v_mul_f32_e32 v80, v140, v80
	v_mul_f32_e32 v81, v140, v81
	v_mul_f32_e32 v70, v140, v70
	v_mul_f32_e32 v71, v140, v71
	v_mul_f32_e32 v88, v140, v78
	v_mul_f32_e32 v89, v140, v79
	v_mul_f32_e32 v78, v140, v76
	v_mul_f32_e32 v79, v140, v77
	v_cvt_pk_bf16_f32 v76, v84, v85
	v_cvt_pk_bf16_f32 v77, v86, v87
	v_cvt_pk_bf16_f32 v78, v78, v79
	v_cvt_pk_bf16_f32 v79, v88, v89
	global_store_dwordx4 v[92:93], v[76:79], off offset:256
	v_mul_f32_e32 v68, v140, v68
	v_mul_f32_e32 v69, v140, v69
	s_mov_b64 s[8:9], 0x40000
	v_or_b32_e32 v76, 48, v150
	v_ashrrev_i32_e32 v77, 31, v76
	v_lshlrev_b64 v[76:77], 11, v[76:77]
	v_lshl_add_u64 v[76:77], s[36:37], 0, v[76:77]
	v_lshl_add_u64 v[76:77], v[76:77], 0, v[154:155]
	v_mul_f32_e32 v78, v140, v82
	v_mul_f32_e32 v79, v140, v83
	v_mul_f32_e32 v82, v140, v74
	v_mul_f32_e32 v83, v140, v75
	v_mul_f32_e32 v74, v140, v72
	v_mul_f32_e32 v75, v140, v73
	v_cvt_pk_bf16_f32 v72, v80, v81
	v_cvt_pk_bf16_f32 v73, v78, v79
	v_cvt_pk_bf16_f32 v74, v74, v75
	v_cvt_pk_bf16_f32 v75, v82, v83
	global_store_dwordx4 v[76:77], v[72:75], off
	v_mul_f32_e32 v60, v140, v60
	v_mul_f32_e32 v61, v140, v61
	v_mul_f32_e32 v62, v140, v62
	v_mul_f32_e32 v63, v140, v63
	v_mul_f32_e32 v72, v140, v66
; __device__ __forceinline__ unsigned cvt_pk_bf16(float lo, float hi) { unsigned r; asm volatile("v_cvt_pk_bf16_f32 %0, %1, %2" : "=v"(r) : "v"(lo), "v"(hi)); return r; }
; #define PG8_BAR __builtin_amdgcn_s_barrier()
;     __device__ __forceinline__ void operator()(const f32x4 (&acc)[2][2][4][2], const Unit& u, int wr, int wc, int fr, int fq) const {
;     ...
;             for (int m = 0; m < 4; ++m) { const int row = row0 + ai * HALF + m * 16; bf16_t* rowp = O + (size_t)row * ldc + col0;
;                 float sc = sc0; if (ROWSCALE) sc *= 1.0f / sqrtf(SS[row] * (1.0f / 1024.0f) + 1e-6f);
; #pragma unroll
;                 for (int bj = 0; bj < 2; ++bj) { const f32x4 v0 = acc[ai][bj][m][0] * sc, v1 = acc[ai][bj][m][1] * sc;
;                     u32x4 w; w.x = cvt_pk_bf16(v0[0], v0[1]); w.y = cvt_pk_bf16(v0[2], v0[3]); w.z = cvt_pk_bf16(v1[0], v1[1]); w.w = cvt_pk_bf16(v1[2], v1[3]);
;                     *(u32x4*)(rowp + bj * HALF) = w; } }
; template <class Epi, class Sched, bool ALIGN_EPI = false, bool SP2 = false>
; __device__ __forceinline__ void gemm_phase(PG8_LAS unsigned char* lds, const Gemm g, const Sched& S, const Epi& E) {
;     ...
;         if constexpr (ALIGN_EPI) { if (wr == 0) PG8_BAR; }
;         if constexpr (!Epi::AFTER_DRAIN) { E(acc, cur, wr, wc, fr, fq); S.done(cur); }
;         if (!has_next) break;
; #pragma unroll
;         for (int a = 0; a < 2; ++a)
; #pragma unroll
;             for (int b = 0; b < 2; ++b)
; #pragma unroll
;                 for (int m = 0; m < 4; ++m)
; #pragma unroll
;                     for (int n = 0; n < 2; ++n) acc[a][b][m][n] = (f32x4){0.f, 0.f, 0.f, 0.f};
;         cur = nxt; cA = nA; cB = nB; ++ui;
;         if constexpr (ALIGN_EPI) { if (wr == 1) PG8_BAR; }
	v_mul_f32_e32 v73, v140, v67
	v_mul_f32_e32 v66, v140, v64
	v_mul_f32_e32 v67, v140, v65
	v_cvt_pk_bf16_f32 v64, v68, v69
	v_cvt_pk_bf16_f32 v65, v70, v71
	v_cvt_pk_bf16_f32 v66, v66, v67
	v_cvt_pk_bf16_f32 v67, v72, v73
	global_store_dwordx4 v[76:77], v[64:67], off offset:256
	v_mul_f32_e32 v54, v140, v54
	v_mul_f32_e32 v55, v140, v55
	v_mul_f32_e32 v52, v140, v52
	v_mul_f32_e32 v53, v140, v53
	v_lshl_add_u64 v[64:65], v[142:143], 0, s[8:9]
	s_mov_b32 s8, 0x40000
	v_mul_f32_e32 v66, v140, v58
	v_mul_f32_e32 v67, v140, v59
	v_mul_f32_e32 v58, v140, v56
	v_mul_f32_e32 v59, v140, v57
	v_cvt_pk_bf16_f32 v56, v60, v61
	v_add_co_u32_e32 v60, vcc, s8, v142
	v_cvt_pk_bf16_f32 v57, v62, v63
	v_cvt_pk_bf16_f32 v58, v58, v59
	v_cvt_pk_bf16_f32 v59, v66, v67
	s_mov_b64 s[8:9], 0x48000
	s_nop 0
	v_addc_co_u32_e32 v61, vcc, 0, v143, vcc
	global_store_dwordx4 v[60:61], v[56:59], off
	v_mul_f32_e32 v48, v140, v48
	v_mul_f32_e32 v49, v140, v49
	v_mul_f32_e32 v38, v140, v38
	v_mul_f32_e32 v39, v140, v39
	v_mul_f32_e32 v56, v140, v46
	v_mul_f32_e32 v57, v140, v47
	v_mul_f32_e32 v46, v140, v44
	v_mul_f32_e32 v47, v140, v45
	v_cvt_pk_bf16_f32 v44, v52, v53
	v_cvt_pk_bf16_f32 v45, v54, v55
	v_cvt_pk_bf16_f32 v46, v46, v47
	v_cvt_pk_bf16_f32 v47, v56, v57
	global_store_dwordx4 v[64:65], v[44:47], off offset:256
	v_mul_f32_e32 v36, v140, v36
	v_mul_f32_e32 v37, v140, v37
	v_mul_f32_e32 v32, v140, v32
	v_mul_f32_e32 v33, v140, v33
	v_lshl_add_u64 v[44:45], v[142:143], 0, s[8:9]
	v_mul_f32_e32 v46, v140, v50
	v_mul_f32_e32 v47, v140, v51
	s_mov_b32 s8, 0x48000
	v_mul_f32_e32 v50, v140, v42
	v_mul_f32_e32 v51, v140, v43
	v_mul_f32_e32 v42, v140, v40
	v_mul_f32_e32 v43, v140, v41
	v_cvt_pk_bf16_f32 v40, v48, v49
	v_cvt_pk_bf16_f32 v41, v46, v47
	v_add_co_u32_e32 v46, vcc, s8, v142
	v_cvt_pk_bf16_f32 v42, v42, v43
	v_cvt_pk_bf16_f32 v43, v50, v51
	s_mov_b64 s[8:9], 0x50000
	s_nop 0
	v_addc_co_u32_e32 v47, vcc, 0, v143, vcc
	global_store_dwordx4 v[46:47], v[40:43], off
	v_mul_f32_e32 v22, v140, v22
	v_mul_f32_e32 v23, v140, v23
	v_mul_f32_e32 v20, v140, v20
	v_mul_f32_e32 v21, v140, v21
	v_mul_f32_e32 v40, v140, v30
	v_mul_f32_e32 v41, v140, v31
	v_mul_f32_e32 v30, v140, v28
	v_mul_f32_e32 v31, v140, v29
	v_cvt_pk_bf16_f32 v28, v36, v37
	v_cvt_pk_bf16_f32 v29, v38, v39
	v_cvt_pk_bf16_f32 v30, v30, v31
	v_cvt_pk_bf16_f32 v31, v40, v41
	global_store_dwordx4 v[44:45], v[28:31], off offset:256
	v_mul_f32_e32 v16, v140, v16
	v_mul_f32_e32 v17, v140, v17
	v_mul_f32_e32 v6, v140, v6
	v_mul_f32_e32 v7, v140, v7
	v_lshl_add_u64 v[28:29], v[142:143], 0, s[8:9]
	v_mul_f32_e32 v30, v140, v34
	v_mul_f32_e32 v31, v140, v35
	s_mov_b32 s8, 0x50000
	v_mul_f32_e32 v34, v140, v26
	v_mul_f32_e32 v35, v140, v27
	v_mul_f32_e32 v26, v140, v24
	v_mul_f32_e32 v27, v140, v25
	v_cvt_pk_bf16_f32 v24, v32, v33
	v_cvt_pk_bf16_f32 v25, v30, v31
	v_add_co_u32_e32 v30, vcc, s8, v142
	v_cvt_pk_bf16_f32 v26, v26, v27
	v_cvt_pk_bf16_f32 v27, v34, v35
	s_mov_b64 s[8:9], 0x58000
	s_nop 0
	v_addc_co_u32_e32 v31, vcc, 0, v143, vcc
	global_store_dwordx4 v[30:31], v[24:27], off
	v_mul_f32_e32 v4, v140, v4
	v_mul_f32_e32 v5, v140, v5
	s_nop 0
	v_mul_f32_e32 v24, v140, v14
	v_mul_f32_e32 v25, v140, v15
	v_mul_f32_e32 v14, v140, v12
	v_mul_f32_e32 v15, v140, v13
	v_cvt_pk_bf16_f32 v12, v20, v21
	v_cvt_pk_bf16_f32 v13, v22, v23
	v_cvt_pk_bf16_f32 v14, v14, v15
	v_cvt_pk_bf16_f32 v15, v24, v25
	global_store_dwordx4 v[28:29], v[12:15], off offset:256
	s_nop 1
	v_lshl_add_u64 v[12:13], v[142:143], 0, s[8:9]
	v_mul_f32_e32 v14, v140, v18
	v_mul_f32_e32 v15, v140, v19
	s_mov_b32 s8, 0x58000
	v_mul_f32_e32 v18, v140, v10
	v_mul_f32_e32 v19, v140, v11
	v_mul_f32_e32 v10, v140, v8
	v_mul_f32_e32 v11, v140, v9
	v_cvt_pk_bf16_f32 v8, v16, v17
	v_cvt_pk_bf16_f32 v9, v14, v15
	v_add_co_u32_e32 v14, vcc, s8, v142
	v_cvt_pk_bf16_f32 v10, v10, v11
	v_cvt_pk_bf16_f32 v11, v18, v19
	s_nop 1
	v_addc_co_u32_e32 v15, vcc, 0, v143, vcc
	global_store_dwordx4 v[14:15], v[8:11], off
	s_andn2_b64 vcc, exec, s[4:5]
	s_mov_b64 s[4:5], -1
	v_mul_f32_e32 v8, v140, v2
	v_mul_f32_e32 v9, v140, v3
	v_mul_f32_e32 v2, v140, v0
	v_mul_f32_e32 v3, v140, v1
	v_cvt_pk_bf16_f32 v0, v4, v5
	v_cvt_pk_bf16_f32 v1, v6, v7
	v_cvt_pk_bf16_f32 v2, v2, v3
	v_cvt_pk_bf16_f32 v3, v8, v9
	global_store_dwordx4 v[12:13], v[0:3], off offset:256
	s_cbranch_vccnz .LBB0_656
	s_andn2_b64 vcc, exec, s[0:1]
	s_cbranch_vccnz .LBB0_655
	s_barrier
	s_branch .LBB0_655

; __device__ __forceinline__ unsigned cvt_pk_bf16(float lo, float hi) { unsigned r; asm volatile("v_cvt_pk_bf16_f32 %0, %1, %2" : "=v"(r) : "v"(lo), "v"(hi)); return r; }
;     __device__ __forceinline__ void operator()(const f32x4 (&acc)[2][2][4][2], const Unit& u, int wr, int wc, int fr, int fq) const {
;         const int row0 = u.pm * BM + wr * 64 + fr; const int colt = u.pn * BM;
;         const float sc0 = (colt < qcols) ? qscale : 1.f;
;         const int col0 = colt + wc * 32 + 8 * fq;
; #pragma unroll
;         for (int ai = 0; ai < 2; ++ai)
; #pragma unroll
;             for (int m = 0; m < 4; ++m) { const int row = row0 + ai * HALF + m * 16; bf16_t* rowp = O + (size_t)row * ldc + col0;
;                 float sc = sc0; if (ROWSCALE) sc *= 1.0f / sqrtf(SS[row] * (1.0f / 1024.0f) + 1e-6f);
; #pragma unroll
;                 for (int bj = 0; bj < 2; ++bj) { const f32x4 v0 = acc[ai][bj][m][0] * sc, v1 = acc[ai][bj][m][1] * sc;
;                     u32x4 w; w.x = cvt_pk_bf16(v0[0], v0[1]); w.y = cvt_pk_bf16(v0[2], v0[3]); w.z = cvt_pk_bf16(v1[0], v1[1]); w.w = cvt_pk_bf16(v1[2], v1[3]);
;                     *(u32x4*)(rowp + bj * HALF) = w; } }
;     }
.LBB0_937:
	v_lshl_add_u32 v148, s0, 8, v152
	v_ashrrev_i32_e32 v149, 31, v148
	v_lshl_add_u64 v[144:145], v[148:149], 2, s[12:13]
	global_load_dword v161, v[144:145], off
	v_lshl_or_b32 v146, s1, 8, v154
	v_ashrrev_i32_e32 v147, 31, v146
	v_lshlrev_b64 v[150:151], 1, v[146:147]
	v_lshlrev_b64 v[164:165], 12, v[148:149]
	v_or_b32_e32 v162, 16, v148
	v_ashrrev_i32_e32 v163, 31, v162
	s_waitcnt vmcnt(0)
	v_fmamk_f32 v146, v161, 0x3a800000, v158
	v_mul_f32_e32 v147, 0x4f800000, v146
	v_cmp_gt_f32_e32 vcc, s87, v146
	s_nop 1
	v_cndmask_b32_e32 v149, v146, v147, vcc
	v_sqrt_f32_e32 v161, v149
	v_lshl_add_u64 v[146:147], s[40:41], 0, v[164:165]
	v_lshl_add_u64 v[146:147], v[146:147], 0, v[150:151]
	v_lshl_add_u64 v[164:165], v[162:163], 2, s[12:13]
	v_add_u32_e32 v166, -1, v161
	v_add_u32_e32 v167, 1, v161
	v_fma_f32 v168, -v166, v161, v149
	v_fma_f32 v169, -v167, v161, v149
	v_cmp_ge_f32_e64 s[0:1], 0, v168
	s_nop 1
	v_cndmask_b32_e64 v161, v161, v166, s[0:1]
	v_cmp_lt_f32_e64 s[0:1], 0, v169
	s_nop 1
	v_cndmask_b32_e64 v161, v161, v167, s[0:1]
	v_mul_f32_e32 v166, 0x37800000, v161
	v_cndmask_b32_e32 v161, v161, v166, vcc
	v_cmp_class_f32_e32 vcc, v149, v159
	s_nop 1
	v_cndmask_b32_e32 v149, v161, v149, vcc
	v_div_scale_f32 v161, s[0:1], v149, v149, 1.0
	v_rcp_f32_e32 v166, v161
	v_div_scale_f32 v167, vcc, 1.0, v149, 1.0
	v_fma_f32 v168, -v161, v166, 1.0
	v_fmac_f32_e32 v166, v168, v166
	v_mul_f32_e32 v168, v167, v166
	v_fma_f32 v169, -v161, v168, v167
	v_fmac_f32_e32 v168, v169, v166
	v_fma_f32 v161, -v161, v168, v167
	v_div_fmas_f32 v161, v161, v166, v168
	v_div_fixup_f32 v166, v161, v149, 1.0
	v_mul_f32_e32 v126, v126, v166
	v_mul_f32_e32 v127, v127, v166
	v_mul_f32_e32 v124, v124, v166
	v_mul_f32_e32 v125, v125, v166
	v_mul_f32_e32 v122, v122, v166
	v_mul_f32_e32 v123, v123, v166
	v_mul_f32_e32 v120, v120, v166
	v_mul_f32_e32 v121, v121, v166
	v_mul_f32_e32 v118, v118, v166
	v_mul_f32_e32 v119, v119, v166
	v_mul_f32_e32 v116, v116, v166
	v_mul_f32_e32 v117, v117, v166
	v_mul_f32_e32 v168, v114, v166
	v_mul_f32_e32 v169, v115, v166
	v_mul_f32_e32 v167, v113, v166
	v_mul_f32_e32 v166, v112, v166
	v_cvt_pk_bf16_f32 v112, v124, v125
	v_cvt_pk_bf16_f32 v113, v126, v127
	v_cvt_pk_bf16_f32 v114, v120, v121
	v_cvt_pk_bf16_f32 v115, v122, v123
	global_store_dwordx4 v[146:147], v[112:115], off
	s_nop 1
	v_cvt_pk_bf16_f32 v112, v116, v117
	v_cvt_pk_bf16_f32 v113, v118, v119
	v_cvt_pk_bf16_f32 v114, v166, v167
	v_cvt_pk_bf16_f32 v115, v168, v169
	global_store_dwordx4 v[146:147], v[112:115], off offset:256
	global_load_dword v114, v[164:165], off
	s_nop 0
	v_or_b32_e32 v112, 32, v148
	v_ashrrev_i32_e32 v113, 31, v112
	v_lshl_add_u64 v[116:117], v[112:113], 2, s[12:13]
	s_waitcnt vmcnt(0)
	v_fmamk_f32 v114, v114, 0x3a800000, v158
	v_mul_f32_e32 v115, 0x4f800000, v114
	v_cmp_gt_f32_e32 vcc, s87, v114
	s_nop 1
	v_cndmask_b32_e32 v118, v114, v115, vcc
	v_sqrt_f32_e32 v119, v118
	v_lshlrev_b64 v[114:115], 12, v[162:163]
	v_lshl_add_u64 v[114:115], s[40:41], 0, v[114:115]
	v_lshl_add_u64 v[114:115], v[114:115], 0, v[150:151]
	v_add_u32_e32 v120, -1, v119
	v_add_u32_e32 v121, 1, v119
	v_fma_f32 v122, -v120, v119, v118
	v_fma_f32 v123, -v121, v119, v118
	v_cmp_ge_f32_e64 s[0:1], 0, v122
	s_nop 1
	v_cndmask_b32_e64 v119, v119, v120, s[0:1]
	v_cmp_lt_f32_e64 s[0:1], 0, v123
	s_nop 1
	v_cndmask_b32_e64 v119, v119, v121, s[0:1]
	v_mul_f32_e32 v120, 0x37800000, v119
	v_cndmask_b32_e32 v119, v119, v120, vcc
	v_cmp_class_f32_e32 vcc, v118, v159
	s_nop 1
	v_cndmask_b32_e32 v118, v119, v118, vcc
	v_div_scale_f32 v119, s[0:1], v118, v118, 1.0
	v_rcp_f32_e32 v120, v119
	v_div_scale_f32 v121, vcc, 1.0, v118, 1.0
	v_fma_f32 v122, -v119, v120, 1.0
	v_fmac_f32_e32 v120, v122, v120
	v_mul_f32_e32 v122, v121, v120
	v_fma_f32 v123, -v119, v122, v121
	v_fmac_f32_e32 v122, v123, v120
	v_fma_f32 v119, -v119, v122, v121
	v_div_fmas_f32 v119, v119, v120, v122
	v_div_fixup_f32 v118, v119, v118, 1.0
	v_mul_f32_e32 v110, v110, v118
	v_mul_f32_e32 v111, v111, v118
	v_mul_f32_e32 v108, v108, v118
	v_mul_f32_e32 v109, v109, v118
	v_mul_f32_e32 v106, v106, v118
	v_mul_f32_e32 v107, v107, v118
	v_mul_f32_e32 v104, v104, v118
	v_mul_f32_e32 v105, v105, v118
	v_mul_f32_e32 v102, v102, v118
	v_mul_f32_e32 v103, v103, v118
	v_mul_f32_e32 v100, v100, v118
	v_mul_f32_e32 v101, v101, v118
	v_mul_f32_e32 v120, v98, v118
	v_mul_f32_e32 v121, v99, v118
	v_mul_f32_e32 v119, v97, v118
	v_mul_f32_e32 v118, v96, v118
	v_cvt_pk_bf16_f32 v96, v108, v109
	v_cvt_pk_bf16_f32 v97, v110, v111
	v_cvt_pk_bf16_f32 v98, v104, v105
	v_cvt_pk_bf16_f32 v99, v106, v107
	global_store_dwordx4 v[114:115], v[96:99], off
	s_nop 1
	v_cvt_pk_bf16_f32 v96, v100, v101
	v_cvt_pk_bf16_f32 v97, v102, v103
	v_cvt_pk_bf16_f32 v98, v118, v119
	v_cvt_pk_bf16_f32 v99, v120, v121
	global_store_dwordx4 v[114:115], v[96:99], off offset:256
	global_load_dword v98, v[116:117], off
	s_nop 0
	v_or_b32_e32 v96, 48, v148
	v_ashrrev_i32_e32 v97, 31, v96
	v_lshl_add_u64 v[100:101], v[96:97], 2, s[12:13]
	s_waitcnt vmcnt(0)
; __device__ __forceinline__ unsigned cvt_pk_bf16(float lo, float hi) { unsigned r; asm volatile("v_cvt_pk_bf16_f32 %0, %1, %2" : "=v"(r) : "v"(lo), "v"(hi)); return r; }
;     __device__ __forceinline__ void operator()(const f32x4 (&acc)[2][2][4][2], const Unit& u, int wr, int wc, int fr, int fq) const {
;         const int row0 = u.pm * BM + wr * 64 + fr; const int colt = u.pn * BM;
;         const float sc0 = (colt < qcols) ? qscale : 1.f;
;         const int col0 = colt + wc * 32 + 8 * fq;
; #pragma unroll
;         for (int ai = 0; ai < 2; ++ai)
; #pragma unroll
;             for (int m = 0; m < 4; ++m) { const int row = row0 + ai * HALF + m * 16; bf16_t* rowp = O + (size_t)row * ldc + col0;
;                 float sc = sc0; if (ROWSCALE) sc *= 1.0f / sqrtf(SS[row] * (1.0f / 1024.0f) + 1e-6f);
; #pragma unroll
;                 for (int bj = 0; bj < 2; ++bj) { const f32x4 v0 = acc[ai][bj][m][0] * sc, v1 = acc[ai][bj][m][1] * sc;
;                     u32x4 w; w.x = cvt_pk_bf16(v0[0], v0[1]); w.y = cvt_pk_bf16(v0[2], v0[3]); w.z = cvt_pk_bf16(v1[0], v1[1]); w.w = cvt_pk_bf16(v1[2], v1[3]);
;                     *(u32x4*)(rowp + bj * HALF) = w; } }
;     }
	v_fmamk_f32 v98, v98, 0x3a800000, v158
	v_mul_f32_e32 v99, 0x4f800000, v98
	v_cmp_gt_f32_e32 vcc, s87, v98
	s_nop 1
	v_cndmask_b32_e32 v102, v98, v99, vcc
	v_sqrt_f32_e32 v103, v102
	v_lshlrev_b64 v[98:99], 12, v[112:113]
	v_lshl_add_u64 v[98:99], s[40:41], 0, v[98:99]
	v_lshl_add_u64 v[98:99], v[98:99], 0, v[150:151]
	v_add_u32_e32 v104, -1, v103
	v_add_u32_e32 v105, 1, v103
	v_fma_f32 v106, -v104, v103, v102
	v_fma_f32 v107, -v105, v103, v102
	v_cmp_ge_f32_e64 s[0:1], 0, v106
	s_nop 1
	v_cndmask_b32_e64 v103, v103, v104, s[0:1]
	v_cmp_lt_f32_e64 s[0:1], 0, v107
	s_nop 1
	v_cndmask_b32_e64 v103, v103, v105, s[0:1]
	v_mul_f32_e32 v104, 0x37800000, v103
	v_cndmask_b32_e32 v103, v103, v104, vcc
	v_cmp_class_f32_e32 vcc, v102, v159
	s_nop 1
	v_cndmask_b32_e32 v102, v103, v102, vcc
	v_div_scale_f32 v103, s[0:1], v102, v102, 1.0
	v_rcp_f32_e32 v104, v103
	v_div_scale_f32 v105, vcc, 1.0, v102, 1.0
	v_fma_f32 v106, -v103, v104, 1.0
	v_fmac_f32_e32 v104, v106, v104
	v_mul_f32_e32 v106, v105, v104
	v_fma_f32 v107, -v103, v106, v105
	v_fmac_f32_e32 v106, v107, v104
	v_fma_f32 v103, -v103, v106, v105
	v_div_fmas_f32 v103, v103, v104, v106
	v_div_fixup_f32 v102, v103, v102, 1.0
	v_mul_f32_e32 v94, v94, v102
	v_mul_f32_e32 v95, v95, v102
	v_mul_f32_e32 v92, v92, v102
	v_mul_f32_e32 v93, v93, v102
	v_mul_f32_e32 v90, v90, v102
	v_mul_f32_e32 v91, v91, v102
	v_mul_f32_e32 v88, v88, v102
	v_mul_f32_e32 v89, v89, v102
	v_mul_f32_e32 v86, v86, v102
	v_mul_f32_e32 v87, v87, v102
	v_mul_f32_e32 v84, v84, v102
	v_mul_f32_e32 v85, v85, v102
	v_mul_f32_e32 v104, v82, v102
	v_mul_f32_e32 v105, v83, v102
	v_mul_f32_e32 v103, v81, v102
	v_mul_f32_e32 v102, v80, v102
	v_cvt_pk_bf16_f32 v80, v92, v93
	v_cvt_pk_bf16_f32 v81, v94, v95
	v_cvt_pk_bf16_f32 v82, v88, v89
	v_cvt_pk_bf16_f32 v83, v90, v91
	global_store_dwordx4 v[98:99], v[80:83], off
	s_nop 1
	v_cvt_pk_bf16_f32 v80, v84, v85
	v_cvt_pk_bf16_f32 v81, v86, v87
	v_cvt_pk_bf16_f32 v82, v102, v103
	v_cvt_pk_bf16_f32 v83, v104, v105
	global_store_dwordx4 v[98:99], v[80:83], off offset:256
	global_load_dword v80, v[100:101], off
	s_waitcnt vmcnt(0)
	v_fmamk_f32 v80, v80, 0x3a800000, v158
	v_mul_f32_e32 v81, 0x4f800000, v80
	v_cmp_gt_f32_e32 vcc, s87, v80
	s_nop 1
	v_cndmask_b32_e32 v82, v80, v81, vcc
	v_sqrt_f32_e32 v83, v82
	v_lshlrev_b64 v[80:81], 12, v[96:97]
	v_lshl_add_u64 v[80:81], s[40:41], 0, v[80:81]
	v_lshl_add_u64 v[80:81], v[80:81], 0, v[150:151]
	v_add_u32_e32 v84, -1, v83
	v_add_u32_e32 v85, 1, v83
	v_fma_f32 v86, -v84, v83, v82
	v_fma_f32 v87, -v85, v83, v82
	v_cmp_ge_f32_e64 s[0:1], 0, v86
	s_nop 1
	v_cndmask_b32_e64 v83, v83, v84, s[0:1]
	v_cmp_lt_f32_e64 s[0:1], 0, v87
	s_nop 1
	v_cndmask_b32_e64 v83, v83, v85, s[0:1]
	v_mul_f32_e32 v84, 0x37800000, v83
	v_cndmask_b32_e32 v83, v83, v84, vcc
	v_cmp_class_f32_e32 vcc, v82, v159
	s_nop 1
	v_cndmask_b32_e32 v82, v83, v82, vcc
	v_div_scale_f32 v83, s[0:1], v82, v82, 1.0
	v_rcp_f32_e32 v84, v83
	v_div_scale_f32 v85, vcc, 1.0, v82, 1.0
	v_fma_f32 v86, -v83, v84, 1.0
	v_fmac_f32_e32 v84, v86, v84
	v_mul_f32_e32 v86, v85, v84
	v_fma_f32 v87, -v83, v86, v85
	v_fmac_f32_e32 v86, v87, v84
	v_fma_f32 v83, -v83, v86, v85
	v_div_fmas_f32 v83, v83, v84, v86
	v_div_fixup_f32 v82, v83, v82, 1.0
	v_mul_f32_e32 v78, v78, v82
	v_mul_f32_e32 v79, v79, v82
	v_mul_f32_e32 v76, v76, v82
	v_mul_f32_e32 v77, v77, v82
	v_mul_f32_e32 v74, v74, v82
	v_mul_f32_e32 v75, v75, v82
	v_mul_f32_e32 v72, v72, v82
	v_mul_f32_e32 v73, v73, v82
	v_mul_f32_e32 v70, v70, v82
	v_mul_f32_e32 v71, v71, v82
	v_mul_f32_e32 v68, v68, v82
	v_mul_f32_e32 v69, v69, v82
	v_mul_f32_e32 v84, v66, v82
	v_mul_f32_e32 v85, v67, v82
	v_mul_f32_e32 v83, v65, v82
	v_mul_f32_e32 v82, v64, v82
	v_cvt_pk_bf16_f32 v64, v76, v77
	v_cvt_pk_bf16_f32 v65, v78, v79
	v_cvt_pk_bf16_f32 v66, v72, v73
	v_cvt_pk_bf16_f32 v67, v74, v75
	global_store_dwordx4 v[80:81], v[64:67], off
	s_nop 1
	v_cvt_pk_bf16_f32 v64, v68, v69
	v_cvt_pk_bf16_f32 v65, v70, v71
	v_cvt_pk_bf16_f32 v66, v82, v83
	v_cvt_pk_bf16_f32 v67, v84, v85
	global_store_dwordx4 v[80:81], v[64:67], off offset:256
	global_load_dword v64, v[144:145], off offset:512
	s_waitcnt vmcnt(0)
	v_fmamk_f32 v64, v64, 0x3a800000, v158
	v_mul_f32_e32 v65, 0x4f800000, v64
	v_cmp_gt_f32_e32 vcc, s87, v64
	s_nop 1
	v_cndmask_b32_e32 v66, v64, v65, vcc
	v_sqrt_f32_e32 v67, v66
	v_lshl_add_u64 v[64:65], v[146:147], 0, s[20:21]
	v_add_u32_e32 v68, -1, v67
	v_add_u32_e32 v69, 1, v67
	v_fma_f32 v70, -v68, v67, v66
	v_fma_f32 v71, -v69, v67, v66
	v_cmp_ge_f32_e64 s[0:1], 0, v70
	s_nop 1
	v_cndmask_b32_e64 v67, v67, v68, s[0:1]
	v_cmp_lt_f32_e64 s[0:1], 0, v71
	s_nop 1
	v_cndmask_b32_e64 v67, v67, v69, s[0:1]
	v_mul_f32_e32 v68, 0x37800000, v67
	v_cndmask_b32_e32 v67, v67, v68, vcc
	v_cmp_class_f32_e32 vcc, v66, v159
	s_nop 1
	v_cndmask_b32_e32 v68, v67, v66, vcc
	v_div_scale_f32 v69, s[0:1], v68, v68, 1.0
	v_rcp_f32_e32 v70, v69
	v_add_co_u32_e32 v66, vcc, s88, v146
	v_fma_f32 v72, -v69, v70, 1.0
	s_nop 0
	v_addc_co_u32_e32 v67, vcc, 0, v147, vcc
	v_div_scale_f32 v71, vcc, 1.0, v68, 1.0
	v_fmac_f32_e32 v70, v72, v70
	v_mul_f32_e32 v72, v71, v70
	v_fma_f32 v73, -v69, v72, v71
	v_fmac_f32_e32 v72, v73, v70
	v_fma_f32 v69, -v69, v72, v71
	v_div_fmas_f32 v69, v69, v70, v72
	v_div_fixup_f32 v68, v69, v68, 1.0
	v_mul_f32_e32 v62, v62, v68
	v_mul_f32_e32 v63, v63, v68
	v_mul_f32_e32 v60, v60, v68
	v_mul_f32_e32 v61, v61, v68
	v_mul_f32_e32 v58, v58, v68
	v_mul_f32_e32 v59, v59, v68
	v_mul_f32_e32 v56, v56, v68
	v_mul_f32_e32 v57, v57, v68
	v_mul_f32_e32 v54, v54, v68
	v_mul_f32_e32 v55, v55, v68
	v_mul_f32_e32 v52, v52, v68
	v_mul_f32_e32 v53, v53, v68
	v_mul_f32_e32 v70, v50, v68
	v_mul_f32_e32 v71, v51, v68
	v_mul_f32_e32 v69, v49, v68
	v_mul_f32_e32 v68, v48, v68
	v_cvt_pk_bf16_f32 v48, v60, v61
	v_cvt_pk_bf16_f32 v49, v62, v63
	v_cvt_pk_bf16_f32 v50, v56, v57
	v_cvt_pk_bf16_f32 v51, v58, v59
	global_store_dwordx4 v[66:67], v[48:51], off
	s_nop 1
	v_cvt_pk_bf16_f32 v48, v52, v53
	v_cvt_pk_bf16_f32 v49, v54, v55
	v_cvt_pk_bf16_f32 v50, v68, v69
	v_cvt_pk_bf16_f32 v51, v70, v71
	global_store_dwordx4 v[64:65], v[48:51], off offset:256
	global_load_dword v48, v[144:145], off offset:576
	s_waitcnt vmcnt(0)
; __device__ __forceinline__ unsigned cvt_pk_bf16(float lo, float hi) { unsigned r; asm volatile("v_cvt_pk_bf16_f32 %0, %1, %2" : "=v"(r) : "v"(lo), "v"(hi)); return r; }
; #define PG8_BAR __builtin_amdgcn_s_barrier()
;     __device__ __forceinline__ void operator()(const f32x4 (&acc)[2][2][4][2], const Unit& u, int wr, int wc, int fr, int fq) const {
;         const int row0 = u.pm * BM + wr * 64 + fr; const int colt = u.pn * BM;
;         const float sc0 = (colt < qcols) ? qscale : 1.f;
;         const int col0 = colt + wc * 32 + 8 * fq;
; #pragma unroll
;         for (int ai = 0; ai < 2; ++ai)
; #pragma unroll
;             for (int m = 0; m < 4; ++m) { const int row = row0 + ai * HALF + m * 16; bf16_t* rowp = O + (size_t)row * ldc + col0;
;                 float sc = sc0; if (ROWSCALE) sc *= 1.0f / sqrtf(SS[row] * (1.0f / 1024.0f) + 1e-6f);
; #pragma unroll
;                 for (int bj = 0; bj < 2; ++bj) { const f32x4 v0 = acc[ai][bj][m][0] * sc, v1 = acc[ai][bj][m][1] * sc;
;                     u32x4 w; w.x = cvt_pk_bf16(v0[0], v0[1]); w.y = cvt_pk_bf16(v0[2], v0[3]); w.z = cvt_pk_bf16(v1[0], v1[1]); w.w = cvt_pk_bf16(v1[2], v1[3]);
;                     *(u32x4*)(rowp + bj * HALF) = w; } }
;     }
; template <class Epi, class Sched, bool ALIGN_EPI = false, bool SP2 = false>
; __device__ __forceinline__ void gemm_phase(PG8_LAS unsigned char* lds, const Gemm g, const Sched& S, const Epi& E) {
;     ...
;         if constexpr (ALIGN_EPI) { if (wr == 0) PG8_BAR; }
;         if constexpr (!Epi::AFTER_DRAIN) { E(acc, cur, wr, wc, fr, fq); S.done(cur); }
;         if (!has_next) break;
; #pragma unroll
;         for (int a = 0; a < 2; ++a)
; #pragma unroll
;             for (int b = 0; b < 2; ++b)
; #pragma unroll
;                 for (int m = 0; m < 4; ++m)
; #pragma unroll
;                     for (int n = 0; n < 2; ++n) acc[a][b][m][n] = (f32x4){0.f, 0.f, 0.f, 0.f};
;         cur = nxt; cA = nA; cB = nB; ++ui;
;         if constexpr (ALIGN_EPI) { if (wr == 1) PG8_BAR; }
	v_fmamk_f32 v48, v48, 0x3a800000, v158
	v_mul_f32_e32 v49, 0x4f800000, v48
	v_cmp_gt_f32_e32 vcc, s87, v48
	s_nop 1
	v_cndmask_b32_e32 v50, v48, v49, vcc
	v_sqrt_f32_e32 v51, v50
	v_lshl_add_u64 v[48:49], v[146:147], 0, s[38:39]
	v_add_u32_e32 v52, -1, v51
	v_add_u32_e32 v53, 1, v51
	v_fma_f32 v54, -v52, v51, v50
	v_fma_f32 v55, -v53, v51, v50
	v_cmp_ge_f32_e64 s[0:1], 0, v54
	s_nop 1
	v_cndmask_b32_e64 v51, v51, v52, s[0:1]
	v_cmp_lt_f32_e64 s[0:1], 0, v55
	s_nop 1
	v_cndmask_b32_e64 v51, v51, v53, s[0:1]
	v_mul_f32_e32 v52, 0x37800000, v51
	v_cndmask_b32_e32 v51, v51, v52, vcc
	v_cmp_class_f32_e32 vcc, v50, v159
	s_nop 1
	v_cndmask_b32_e32 v52, v51, v50, vcc
	v_div_scale_f32 v53, s[0:1], v52, v52, 1.0
	v_rcp_f32_e32 v54, v53
	v_add_co_u32_e32 v50, vcc, s89, v146
	v_fma_f32 v56, -v53, v54, 1.0
	s_nop 0
	v_addc_co_u32_e32 v51, vcc, 0, v147, vcc
	v_div_scale_f32 v55, vcc, 1.0, v52, 1.0
	v_fmac_f32_e32 v54, v56, v54
	v_mul_f32_e32 v56, v55, v54
	v_fma_f32 v57, -v53, v56, v55
	v_fmac_f32_e32 v56, v57, v54
	v_fma_f32 v53, -v53, v56, v55
	v_div_fmas_f32 v53, v53, v54, v56
	v_div_fixup_f32 v52, v53, v52, 1.0
	v_mul_f32_e32 v46, v46, v52
	v_mul_f32_e32 v47, v47, v52
	v_mul_f32_e32 v44, v44, v52
	v_mul_f32_e32 v45, v45, v52
	v_mul_f32_e32 v42, v42, v52
	v_mul_f32_e32 v43, v43, v52
	v_mul_f32_e32 v40, v40, v52
	v_mul_f32_e32 v41, v41, v52
	v_mul_f32_e32 v38, v38, v52
	v_mul_f32_e32 v39, v39, v52
	v_mul_f32_e32 v36, v36, v52
	v_mul_f32_e32 v37, v37, v52
	v_mul_f32_e32 v54, v34, v52
	v_mul_f32_e32 v55, v35, v52
	v_mul_f32_e32 v53, v33, v52
	v_mul_f32_e32 v52, v32, v52
	v_cvt_pk_bf16_f32 v32, v44, v45
	v_cvt_pk_bf16_f32 v33, v46, v47
	v_cvt_pk_bf16_f32 v34, v40, v41
	v_cvt_pk_bf16_f32 v35, v42, v43
	global_store_dwordx4 v[50:51], v[32:35], off
	s_nop 1
	v_cvt_pk_bf16_f32 v32, v36, v37
	v_cvt_pk_bf16_f32 v33, v38, v39
	v_cvt_pk_bf16_f32 v34, v52, v53
	v_cvt_pk_bf16_f32 v35, v54, v55
	global_store_dwordx4 v[48:49], v[32:35], off offset:256
	global_load_dword v32, v[144:145], off offset:640
	s_waitcnt vmcnt(0)
	v_fmamk_f32 v32, v32, 0x3a800000, v158
	v_mul_f32_e32 v33, 0x4f800000, v32
	v_cmp_gt_f32_e32 vcc, s87, v32
	s_nop 1
	v_cndmask_b32_e32 v34, v32, v33, vcc
	v_sqrt_f32_e32 v35, v34
	v_lshl_add_u64 v[32:33], v[146:147], 0, s[42:43]
	v_add_u32_e32 v36, -1, v35
	v_add_u32_e32 v37, 1, v35
	v_fma_f32 v38, -v36, v35, v34
	v_fma_f32 v39, -v37, v35, v34
	v_cmp_ge_f32_e64 s[0:1], 0, v38
	s_nop 1
	v_cndmask_b32_e64 v35, v35, v36, s[0:1]
	v_cmp_lt_f32_e64 s[0:1], 0, v39
	s_nop 1
	v_cndmask_b32_e64 v35, v35, v37, s[0:1]
	v_mul_f32_e32 v36, 0x37800000, v35
	v_cndmask_b32_e32 v35, v35, v36, vcc
	v_cmp_class_f32_e32 vcc, v34, v159
	s_nop 1
	v_cndmask_b32_e32 v36, v35, v34, vcc
	v_div_scale_f32 v37, s[0:1], v36, v36, 1.0
	v_rcp_f32_e32 v38, v37
	v_add_co_u32_e32 v34, vcc, s90, v146
	v_fma_f32 v40, -v37, v38, 1.0
	s_nop 0
	v_addc_co_u32_e32 v35, vcc, 0, v147, vcc
	v_div_scale_f32 v39, vcc, 1.0, v36, 1.0
	v_fmac_f32_e32 v38, v40, v38
	v_mul_f32_e32 v40, v39, v38
	v_fma_f32 v41, -v37, v40, v39
	v_fmac_f32_e32 v40, v41, v38
	v_fma_f32 v37, -v37, v40, v39
	v_div_fmas_f32 v37, v37, v38, v40
	v_div_fixup_f32 v36, v37, v36, 1.0
	v_mul_f32_e32 v30, v30, v36
	v_mul_f32_e32 v31, v31, v36
	v_mul_f32_e32 v28, v28, v36
	v_mul_f32_e32 v29, v29, v36
	v_mul_f32_e32 v26, v26, v36
	v_mul_f32_e32 v27, v27, v36
	v_mul_f32_e32 v24, v24, v36
	v_mul_f32_e32 v25, v25, v36
	v_mul_f32_e32 v22, v22, v36
	v_mul_f32_e32 v23, v23, v36
	v_mul_f32_e32 v20, v20, v36
	v_mul_f32_e32 v21, v21, v36
	v_mul_f32_e32 v38, v18, v36
	v_mul_f32_e32 v39, v19, v36
	v_mul_f32_e32 v37, v17, v36
	v_mul_f32_e32 v36, v16, v36
	v_cvt_pk_bf16_f32 v16, v28, v29
	v_cvt_pk_bf16_f32 v17, v30, v31
	v_cvt_pk_bf16_f32 v18, v24, v25
	v_cvt_pk_bf16_f32 v19, v26, v27
	global_store_dwordx4 v[34:35], v[16:19], off
	s_nop 1
	v_cvt_pk_bf16_f32 v16, v20, v21
	v_cvt_pk_bf16_f32 v17, v22, v23
	v_cvt_pk_bf16_f32 v18, v36, v37
	v_cvt_pk_bf16_f32 v19, v38, v39
	global_store_dwordx4 v[32:33], v[16:19], off offset:256
	global_load_dword v16, v[144:145], off offset:704
	s_waitcnt vmcnt(0)
	v_fmamk_f32 v16, v16, 0x3a800000, v158
	v_mul_f32_e32 v17, 0x4f800000, v16
	v_cmp_gt_f32_e32 vcc, s87, v16
	s_nop 1
	v_cndmask_b32_e32 v18, v16, v17, vcc
	v_sqrt_f32_e32 v19, v18
	v_lshl_add_u64 v[16:17], v[146:147], 0, s[48:49]
	v_add_u32_e32 v20, -1, v19
	v_add_u32_e32 v21, 1, v19
	v_fma_f32 v22, -v20, v19, v18
	v_fma_f32 v23, -v21, v19, v18
	v_cmp_ge_f32_e64 s[0:1], 0, v22
	s_nop 1
	v_cndmask_b32_e64 v19, v19, v20, s[0:1]
	v_cmp_lt_f32_e64 s[0:1], 0, v23
	s_nop 1
	v_cndmask_b32_e64 v19, v19, v21, s[0:1]
	v_mul_f32_e32 v20, 0x37800000, v19
	v_cndmask_b32_e32 v19, v19, v20, vcc
	v_cmp_class_f32_e32 vcc, v18, v159
	s_nop 1
	v_cndmask_b32_e32 v20, v19, v18, vcc
	v_div_scale_f32 v21, s[0:1], v20, v20, 1.0
	v_rcp_f32_e32 v22, v21
	v_add_co_u32_e32 v18, vcc, s91, v146
	s_mov_b64 s[0:1], -1
	s_nop 0
	v_addc_co_u32_e32 v19, vcc, 0, v147, vcc
	v_fma_f32 v24, -v21, v22, 1.0
	v_div_scale_f32 v23, vcc, 1.0, v20, 1.0
	v_fmac_f32_e32 v22, v24, v22
	v_mul_f32_e32 v24, v23, v22
	v_fma_f32 v25, -v21, v24, v23
	v_fmac_f32_e32 v24, v25, v22
	v_fma_f32 v21, -v21, v24, v23
	v_div_fmas_f32 v21, v21, v22, v24
	v_div_fixup_f32 v20, v21, v20, 1.0
	s_andn2_b64 vcc, exec, s[4:5]
	v_mul_f32_e32 v14, v14, v20
	v_mul_f32_e32 v15, v15, v20
	v_mul_f32_e32 v12, v12, v20
	v_mul_f32_e32 v13, v13, v20
	v_mul_f32_e32 v10, v10, v20
	v_mul_f32_e32 v11, v11, v20
	v_mul_f32_e32 v8, v8, v20
	v_mul_f32_e32 v9, v9, v20
	v_mul_f32_e32 v6, v6, v20
	v_mul_f32_e32 v7, v7, v20
	v_mul_f32_e32 v4, v4, v20
	v_mul_f32_e32 v5, v5, v20
	v_mul_f32_e32 v22, v2, v20
	v_mul_f32_e32 v23, v3, v20
	v_mul_f32_e32 v21, v1, v20
	v_mul_f32_e32 v20, v0, v20
	v_cvt_pk_bf16_f32 v0, v12, v13
	v_cvt_pk_bf16_f32 v1, v14, v15
	v_cvt_pk_bf16_f32 v2, v8, v9
	v_cvt_pk_bf16_f32 v3, v10, v11
	global_store_dwordx4 v[18:19], v[0:3], off
	s_nop 1
	v_cvt_pk_bf16_f32 v0, v4, v5
	v_cvt_pk_bf16_f32 v1, v6, v7
	v_cvt_pk_bf16_f32 v2, v20, v21
	v_cvt_pk_bf16_f32 v3, v22, v23
	global_store_dwordx4 v[16:17], v[0:3], off offset:256
	s_cbranch_vccnz .LBB0_926
	s_andn2_b64 vcc, exec, s[6:7]
	s_cbranch_vccnz .LBB0_925
	s_barrier
	s_branch .LBB0_925

; __device__ __forceinline__ unsigned cvt_pk_bf16(float lo, float hi) { unsigned r; asm volatile("v_cvt_pk_bf16_f32 %0, %1, %2" : "=v"(r) : "v"(lo), "v"(hi)); return r; }
;     __device__ __forceinline__ void operator()(const f32x4 (&acc)[2][2][4][2], const Unit& u, int wr, int wc, int fr, int fq) const {
;         const int row0 = u.pm * BM + wr * 64 + fr; const int colt = u.pn * BM;
;         const float sc0 = (colt < qcols) ? qscale : 1.f;
;         const int col0 = colt + wc * 32 + 8 * fq;
; #pragma unroll
;         for (int ai = 0; ai < 2; ++ai)
; #pragma unroll
;             for (int m = 0; m < 4; ++m) { const int row = row0 + ai * HALF + m * 16; bf16_t* rowp = O + (size_t)row * ldc + col0;
;                 float sc = sc0; if (ROWSCALE) sc *= 1.0f / sqrtf(SS[row] * (1.0f / 1024.0f) + 1e-6f);
; #pragma unroll
;                 for (int bj = 0; bj < 2; ++bj) { const f32x4 v0 = acc[ai][bj][m][0] * sc, v1 = acc[ai][bj][m][1] * sc;
;                     u32x4 w; w.x = cvt_pk_bf16(v0[0], v0[1]); w.y = cvt_pk_bf16(v0[2], v0[3]); w.z = cvt_pk_bf16(v1[0], v1[1]); w.w = cvt_pk_bf16(v1[2], v1[3]);
;                     *(u32x4*)(rowp + bj * HALF) = w; } }
;     }
.LBB0_1175:
	v_lshl_add_u32 v154, s50, 8, v145
	s_cmp_lt_i32 s80, 0
	v_lshl_or_b32 v146, s80, 8, v149
	v_ashrrev_i32_e32 v155, 31, v154
	s_cselect_b64 vcc, -1, 0
	v_ashrrev_i32_e32 v147, 31, v146
	v_lshlrev_b64 v[156:157], 11, v[154:155]
	v_cndmask_b32_e32 v144, 1.0, v153, vcc
	v_lshl_add_u64 v[156:157], s[58:59], 0, v[156:157]
	v_lshlrev_b64 v[158:159], 1, v[146:147]
	v_lshl_add_u64 v[146:147], v[156:157], 0, v[158:159]
	v_mul_f32_e32 v126, v144, v126
	v_mul_f32_e32 v127, v144, v127
	v_mul_f32_e32 v124, v144, v124
	v_mul_f32_e32 v125, v144, v125
	v_mul_f32_e32 v156, v144, v122
	v_mul_f32_e32 v157, v144, v123
	v_mul_f32_e32 v122, v144, v120
	v_mul_f32_e32 v123, v144, v121
	v_cvt_pk_bf16_f32 v120, v124, v125
	v_cvt_pk_bf16_f32 v121, v126, v127
	v_cvt_pk_bf16_f32 v122, v122, v123
	v_cvt_pk_bf16_f32 v123, v156, v157
	global_store_dwordx4 v[146:147], v[120:123], off
	v_mul_f32_e32 v116, v144, v116
	v_mul_f32_e32 v117, v144, v117
	v_mul_f32_e32 v118, v144, v118
	v_mul_f32_e32 v119, v144, v119
	v_mul_f32_e32 v120, v144, v110
	v_mul_f32_e32 v121, v144, v111
	v_mul_f32_e32 v110, v144, v108
	v_mul_f32_e32 v111, v144, v109
	v_cvt_pk_bf16_f32 v108, v116, v117
	v_cvt_pk_bf16_f32 v109, v118, v119
	v_cvt_pk_bf16_f32 v110, v110, v111
	v_cvt_pk_bf16_f32 v111, v120, v121
	global_store_dwordx4 v[146:147], v[108:111], off offset:256
	v_mul_f32_e32 v112, v144, v112
	v_mul_f32_e32 v113, v144, v113
	v_mul_f32_e32 v100, v144, v100
	v_mul_f32_e32 v101, v144, v101
	v_or_b32_e32 v108, 16, v154
	v_ashrrev_i32_e32 v109, 31, v108
	v_lshlrev_b64 v[108:109], 11, v[108:109]
	v_lshl_add_u64 v[108:109], s[58:59], 0, v[108:109]
	v_lshl_add_u64 v[108:109], v[108:109], 0, v[158:159]
	v_mul_f32_e32 v110, v144, v114
	v_mul_f32_e32 v111, v144, v115
	v_mul_f32_e32 v114, v144, v106
	v_mul_f32_e32 v115, v144, v107
	v_mul_f32_e32 v106, v144, v104
	v_mul_f32_e32 v107, v144, v105
	v_cvt_pk_bf16_f32 v104, v112, v113
	v_cvt_pk_bf16_f32 v105, v110, v111
	v_cvt_pk_bf16_f32 v106, v106, v107
	v_cvt_pk_bf16_f32 v107, v114, v115
	global_store_dwordx4 v[108:109], v[104:107], off
	v_mul_f32_e32 v102, v144, v102
	v_mul_f32_e32 v103, v144, v103
	v_mul_f32_e32 v96, v144, v96
	v_mul_f32_e32 v97, v144, v97
	v_mul_f32_e32 v104, v144, v94
	v_mul_f32_e32 v105, v144, v95
	v_mul_f32_e32 v94, v144, v92
	v_mul_f32_e32 v95, v144, v93
	v_cvt_pk_bf16_f32 v92, v100, v101
	v_cvt_pk_bf16_f32 v93, v102, v103
	v_cvt_pk_bf16_f32 v94, v94, v95
	v_cvt_pk_bf16_f32 v95, v104, v105
	global_store_dwordx4 v[108:109], v[92:95], off offset:256
	v_mul_f32_e32 v84, v144, v84
	v_mul_f32_e32 v85, v144, v85
	v_mul_f32_e32 v86, v144, v86
	v_mul_f32_e32 v87, v144, v87
	v_or_b32_e32 v92, 32, v154
	v_ashrrev_i32_e32 v93, 31, v92
	v_lshlrev_b64 v[92:93], 11, v[92:93]
	v_lshl_add_u64 v[92:93], s[58:59], 0, v[92:93]
	v_lshl_add_u64 v[92:93], v[92:93], 0, v[158:159]
	v_mul_f32_e32 v94, v144, v98
	v_mul_f32_e32 v95, v144, v99
	v_mul_f32_e32 v98, v144, v90
	v_mul_f32_e32 v99, v144, v91
	v_mul_f32_e32 v90, v144, v88
	v_mul_f32_e32 v91, v144, v89
	v_cvt_pk_bf16_f32 v88, v96, v97
	v_cvt_pk_bf16_f32 v89, v94, v95
	v_cvt_pk_bf16_f32 v90, v90, v91
	v_cvt_pk_bf16_f32 v91, v98, v99
	global_store_dwordx4 v[92:93], v[88:91], off
	v_mul_f32_e32 v80, v144, v80
	v_mul_f32_e32 v81, v144, v81
	v_mul_f32_e32 v70, v144, v70
	v_mul_f32_e32 v71, v144, v71
	v_mul_f32_e32 v88, v144, v78
	v_mul_f32_e32 v89, v144, v79
	v_mul_f32_e32 v78, v144, v76
	v_mul_f32_e32 v79, v144, v77
	v_cvt_pk_bf16_f32 v76, v84, v85
	v_cvt_pk_bf16_f32 v77, v86, v87
	v_cvt_pk_bf16_f32 v78, v78, v79
	v_cvt_pk_bf16_f32 v79, v88, v89
	global_store_dwordx4 v[92:93], v[76:79], off offset:256
	v_mul_f32_e32 v68, v144, v68
	v_mul_f32_e32 v69, v144, v69
	v_mul_f32_e32 v60, v144, v60
	v_mul_f32_e32 v61, v144, v61
	v_or_b32_e32 v76, 48, v154
	v_ashrrev_i32_e32 v77, 31, v76
	v_lshlrev_b64 v[76:77], 11, v[76:77]
	v_lshl_add_u64 v[76:77], s[58:59], 0, v[76:77]
	v_lshl_add_u64 v[76:77], v[76:77], 0, v[158:159]
	v_mul_f32_e32 v78, v144, v82
	v_mul_f32_e32 v79, v144, v83
	v_mul_f32_e32 v82, v144, v74
	v_mul_f32_e32 v83, v144, v75
	v_mul_f32_e32 v74, v144, v72
	v_mul_f32_e32 v75, v144, v73
	v_cvt_pk_bf16_f32 v72, v80, v81
	v_cvt_pk_bf16_f32 v73, v78, v79
	v_cvt_pk_bf16_f32 v74, v74, v75
	v_cvt_pk_bf16_f32 v75, v82, v83
	global_store_dwordx4 v[76:77], v[72:75], off
	v_mul_f32_e32 v62, v144, v62
; __device__ __forceinline__ unsigned cvt_pk_bf16(float lo, float hi) { unsigned r; asm volatile("v_cvt_pk_bf16_f32 %0, %1, %2" : "=v"(r) : "v"(lo), "v"(hi)); return r; }
; #define PG8_BAR __builtin_amdgcn_s_barrier()
;     __device__ __forceinline__ void operator()(const f32x4 (&acc)[2][2][4][2], const Unit& u, int wr, int wc, int fr, int fq) const {
;     ...
;             for (int m = 0; m < 4; ++m) { const int row = row0 + ai * HALF + m * 16; bf16_t* rowp = O + (size_t)row * ldc + col0;
;                 float sc = sc0; if (ROWSCALE) sc *= 1.0f / sqrtf(SS[row] * (1.0f / 1024.0f) + 1e-6f);
; #pragma unroll
;                 for (int bj = 0; bj < 2; ++bj) { const f32x4 v0 = acc[ai][bj][m][0] * sc, v1 = acc[ai][bj][m][1] * sc;
;                     u32x4 w; w.x = cvt_pk_bf16(v0[0], v0[1]); w.y = cvt_pk_bf16(v0[2], v0[3]); w.z = cvt_pk_bf16(v1[0], v1[1]); w.w = cvt_pk_bf16(v1[2], v1[3]);
;                     *(u32x4*)(rowp + bj * HALF) = w; } }
; template <class Epi, class Sched, bool ALIGN_EPI = false, bool SP2 = false>
; __device__ __forceinline__ void gemm_phase(PG8_LAS unsigned char* lds, const Gemm g, const Sched& S, const Epi& E) {
;     ...
;         if constexpr (ALIGN_EPI) { if (wr == 0) PG8_BAR; }
;         if constexpr (!Epi::AFTER_DRAIN) { E(acc, cur, wr, wc, fr, fq); S.done(cur); }
;         if (!has_next) break;
; #pragma unroll
;         for (int a = 0; a < 2; ++a)
; #pragma unroll
;             for (int b = 0; b < 2; ++b)
; #pragma unroll
;                 for (int m = 0; m < 4; ++m)
; #pragma unroll
;                     for (int n = 0; n < 2; ++n) acc[a][b][m][n] = (f32x4){0.f, 0.f, 0.f, 0.f};
;         cur = nxt; cA = nA; cB = nB; ++ui;
;         if constexpr (ALIGN_EPI) { if (wr == 1) PG8_BAR; }
	v_mul_f32_e32 v63, v144, v63
	v_mul_f32_e32 v54, v144, v54
	v_mul_f32_e32 v55, v144, v55
	v_mul_f32_e32 v72, v144, v66
	v_mul_f32_e32 v73, v144, v67
	v_mul_f32_e32 v66, v144, v64
	v_mul_f32_e32 v67, v144, v65
	v_cvt_pk_bf16_f32 v64, v68, v69
	v_cvt_pk_bf16_f32 v65, v70, v71
	v_cvt_pk_bf16_f32 v66, v66, v67
	v_cvt_pk_bf16_f32 v67, v72, v73
	global_store_dwordx4 v[76:77], v[64:67], off offset:256
	v_mul_f32_e32 v52, v144, v52
	v_mul_f32_e32 v53, v144, v53
	v_mul_f32_e32 v48, v144, v48
	v_mul_f32_e32 v49, v144, v49
	v_mul_f32_e32 v66, v144, v58
	v_mul_f32_e32 v67, v144, v59
	v_mul_f32_e32 v58, v144, v56
	v_mul_f32_e32 v59, v144, v57
	v_cvt_pk_bf16_f32 v56, v60, v61
	v_add_co_u32_e32 v60, vcc, s76, v146
	v_cvt_pk_bf16_f32 v57, v62, v63
	v_cvt_pk_bf16_f32 v58, v58, v59
	v_cvt_pk_bf16_f32 v59, v66, v67
	v_lshl_add_u64 v[64:65], v[146:147], 0, s[0:1]
	s_nop 0
	v_addc_co_u32_e32 v61, vcc, 0, v147, vcc
	global_store_dwordx4 v[60:61], v[56:59], off
	v_mul_f32_e32 v38, v144, v38
	v_mul_f32_e32 v39, v144, v39
	v_mul_f32_e32 v36, v144, v36
	v_mul_f32_e32 v37, v144, v37
	v_mul_f32_e32 v56, v144, v46
	v_mul_f32_e32 v57, v144, v47
	v_mul_f32_e32 v46, v144, v44
	v_mul_f32_e32 v47, v144, v45
	v_cvt_pk_bf16_f32 v44, v52, v53
	v_cvt_pk_bf16_f32 v45, v54, v55
	v_cvt_pk_bf16_f32 v46, v46, v47
	v_cvt_pk_bf16_f32 v47, v56, v57
	global_store_dwordx4 v[64:65], v[44:47], off offset:256
	v_mul_f32_e32 v32, v144, v32
	v_mul_f32_e32 v33, v144, v33
	v_mul_f32_e32 v22, v144, v22
	v_mul_f32_e32 v23, v144, v23
	v_mul_f32_e32 v46, v144, v50
	v_mul_f32_e32 v47, v144, v51
	v_mul_f32_e32 v50, v144, v42
	v_mul_f32_e32 v51, v144, v43
	v_mul_f32_e32 v42, v144, v40
	v_mul_f32_e32 v43, v144, v41
	v_cvt_pk_bf16_f32 v40, v48, v49
	v_cvt_pk_bf16_f32 v41, v46, v47
	v_add_co_u32_e32 v46, vcc, s77, v146
	v_cvt_pk_bf16_f32 v42, v42, v43
	v_cvt_pk_bf16_f32 v43, v50, v51
	v_lshl_add_u64 v[44:45], v[146:147], 0, s[18:19]
	s_nop 0
	v_addc_co_u32_e32 v47, vcc, 0, v147, vcc
	global_store_dwordx4 v[46:47], v[40:43], off
	v_mul_f32_e32 v20, v144, v20
	v_mul_f32_e32 v21, v144, v21
	v_mul_f32_e32 v16, v144, v16
	v_mul_f32_e32 v17, v144, v17
	v_mul_f32_e32 v40, v144, v30
	v_mul_f32_e32 v41, v144, v31
	v_mul_f32_e32 v30, v144, v28
	v_mul_f32_e32 v31, v144, v29
	v_cvt_pk_bf16_f32 v28, v36, v37
	v_cvt_pk_bf16_f32 v29, v38, v39
	v_cvt_pk_bf16_f32 v30, v30, v31
	v_cvt_pk_bf16_f32 v31, v40, v41
	global_store_dwordx4 v[44:45], v[28:31], off offset:256
	v_mul_f32_e32 v6, v144, v6
	v_mul_f32_e32 v7, v144, v7
	v_mul_f32_e32 v4, v144, v4
	v_mul_f32_e32 v5, v144, v5
	v_mul_f32_e32 v30, v144, v34
	v_mul_f32_e32 v31, v144, v35
	v_mul_f32_e32 v34, v144, v26
	v_mul_f32_e32 v35, v144, v27
	v_mul_f32_e32 v26, v144, v24
	v_mul_f32_e32 v27, v144, v25
	v_cvt_pk_bf16_f32 v24, v32, v33
	v_cvt_pk_bf16_f32 v25, v30, v31
	v_add_co_u32_e32 v30, vcc, s78, v146
	v_cvt_pk_bf16_f32 v26, v26, v27
	v_cvt_pk_bf16_f32 v27, v34, v35
	v_lshl_add_u64 v[28:29], v[146:147], 0, s[20:21]
	s_nop 0
	v_addc_co_u32_e32 v31, vcc, 0, v147, vcc
	global_store_dwordx4 v[30:31], v[24:27], off
	s_nop 1
	v_mul_f32_e32 v24, v144, v14
	v_mul_f32_e32 v25, v144, v15
	v_mul_f32_e32 v14, v144, v12
	v_mul_f32_e32 v15, v144, v13
	v_cvt_pk_bf16_f32 v12, v20, v21
	v_cvt_pk_bf16_f32 v13, v22, v23
	v_cvt_pk_bf16_f32 v14, v14, v15
	v_cvt_pk_bf16_f32 v15, v24, v25
	global_store_dwordx4 v[28:29], v[12:15], off offset:256
	s_nop 1
	v_mul_f32_e32 v14, v144, v18
	v_mul_f32_e32 v15, v144, v19
	v_mul_f32_e32 v18, v144, v10
	v_mul_f32_e32 v19, v144, v11
	v_mul_f32_e32 v10, v144, v8
	v_mul_f32_e32 v11, v144, v9
	v_cvt_pk_bf16_f32 v8, v16, v17
	v_cvt_pk_bf16_f32 v9, v14, v15
	v_add_co_u32_e32 v14, vcc, s79, v146
	v_lshl_add_u64 v[12:13], v[146:147], 0, s[38:39]
	s_nop 0
	v_addc_co_u32_e32 v15, vcc, 0, v147, vcc
	v_cvt_pk_bf16_f32 v10, v10, v11
	v_cvt_pk_bf16_f32 v11, v18, v19
	global_store_dwordx4 v[14:15], v[8:11], off
	s_andn2_b64 vcc, exec, s[4:5]
	s_mov_b64 s[4:5], -1
	v_mul_f32_e32 v8, v144, v2
	v_mul_f32_e32 v9, v144, v3
	v_mul_f32_e32 v2, v144, v0
	v_mul_f32_e32 v3, v144, v1
	v_cvt_pk_bf16_f32 v0, v4, v5
	v_cvt_pk_bf16_f32 v1, v6, v7
	v_cvt_pk_bf16_f32 v2, v2, v3
	v_cvt_pk_bf16_f32 v3, v8, v9
	global_store_dwordx4 v[12:13], v[0:3], off offset:256
	s_cbranch_vccnz .LBB0_1164
	s_andn2_b64 vcc, exec, s[6:7]
	s_cbranch_vccnz .LBB0_1163
	s_barrier
	s_branch .LBB0_1163

; __device__ __forceinline__ unsigned cvt_pk_bf16(float lo, float hi) { unsigned r; asm volatile("v_cvt_pk_bf16_f32 %0, %1, %2" : "=v"(r) : "v"(lo), "v"(hi)); return r; }
;     __device__ __forceinline__ void operator()(const f32x4 (&acc)[2][2][4][2], const Unit& u, int wr, int wc, int fr, int fq) const {
;         const int row0 = u.pm * BM + wr * 64 + fr; const int colt = u.pn * BM;
;         const float sc0 = (colt < qcols) ? qscale : 1.f;
;         const int col0 = colt + wc * 32 + 8 * fq;
; #pragma unroll
;         for (int ai = 0; ai < 2; ++ai)
; #pragma unroll
;             for (int m = 0; m < 4; ++m) { const int row = row0 + ai * HALF + m * 16; bf16_t* rowp = O + (size_t)row * ldc + col0;
;                 float sc = sc0; if (ROWSCALE) sc *= 1.0f / sqrtf(SS[row] * (1.0f / 1024.0f) + 1e-6f);
; #pragma unroll
;                 for (int bj = 0; bj < 2; ++bj) { const f32x4 v0 = acc[ai][bj][m][0] * sc, v1 = acc[ai][bj][m][1] * sc;
;                     u32x4 w; w.x = cvt_pk_bf16(v0[0], v0[1]); w.y = cvt_pk_bf16(v0[2], v0[3]); w.z = cvt_pk_bf16(v1[0], v1[1]); w.w = cvt_pk_bf16(v1[2], v1[3]);
;                     *(u32x4*)(rowp + bj * HALF) = w; } }
.LBB0_1423:
	v_lshl_add_u32 v164, s75, 8, v156
	s_cmp_lt_i32 s76, 0
	v_lshl_or_b32 v146, s76, 8, v158
	v_ashrrev_i32_e32 v165, 31, v164
	s_cselect_b64 vcc, -1, 0
	v_ashrrev_i32_e32 v147, 31, v146
	v_lshlrev_b64 v[166:167], 11, v[164:165]
	v_cndmask_b32_e32 v144, 1.0, v163, vcc
	v_lshl_add_u64 v[166:167], s[58:59], 0, v[166:167]
	v_lshlrev_b64 v[168:169], 1, v[146:147]
	v_lshl_add_u64 v[146:147], v[166:167], 0, v[168:169]
	v_mul_f32_e32 v126, v144, v126
	v_mul_f32_e32 v127, v144, v127
	v_mul_f32_e32 v124, v144, v124
	v_mul_f32_e32 v125, v144, v125
	v_mul_f32_e32 v166, v144, v122
	v_mul_f32_e32 v167, v144, v123
	v_mul_f32_e32 v122, v144, v120
	v_mul_f32_e32 v123, v144, v121
	v_cvt_pk_bf16_f32 v120, v124, v125
	v_cvt_pk_bf16_f32 v121, v126, v127
	v_cvt_pk_bf16_f32 v122, v122, v123
	v_cvt_pk_bf16_f32 v123, v166, v167
	global_store_dwordx4 v[146:147], v[120:123], off
	v_mul_f32_e32 v116, v144, v116
	v_mul_f32_e32 v117, v144, v117
	v_mul_f32_e32 v118, v144, v118
	v_mul_f32_e32 v119, v144, v119
	v_mul_f32_e32 v120, v144, v110
	v_mul_f32_e32 v121, v144, v111
	v_mul_f32_e32 v110, v144, v108
	v_mul_f32_e32 v111, v144, v109
	v_cvt_pk_bf16_f32 v108, v116, v117
	v_cvt_pk_bf16_f32 v109, v118, v119
	v_cvt_pk_bf16_f32 v110, v110, v111
	v_cvt_pk_bf16_f32 v111, v120, v121
	global_store_dwordx4 v[146:147], v[108:111], off offset:256
	v_mul_f32_e32 v112, v144, v112
	v_mul_f32_e32 v113, v144, v113
	v_mul_f32_e32 v100, v144, v100
	v_mul_f32_e32 v101, v144, v101
	v_or_b32_e32 v108, 16, v164
	v_ashrrev_i32_e32 v109, 31, v108
	v_lshlrev_b64 v[108:109], 11, v[108:109]
	v_lshl_add_u64 v[108:109], s[58:59], 0, v[108:109]
	v_lshl_add_u64 v[108:109], v[108:109], 0, v[168:169]
	v_mul_f32_e32 v110, v144, v114
	v_mul_f32_e32 v111, v144, v115
	v_mul_f32_e32 v114, v144, v106
	v_mul_f32_e32 v115, v144, v107
	v_mul_f32_e32 v106, v144, v104
	v_mul_f32_e32 v107, v144, v105
	v_cvt_pk_bf16_f32 v104, v112, v113
	v_cvt_pk_bf16_f32 v105, v110, v111
	v_cvt_pk_bf16_f32 v106, v106, v107
	v_cvt_pk_bf16_f32 v107, v114, v115
	global_store_dwordx4 v[108:109], v[104:107], off
	v_mul_f32_e32 v102, v144, v102
	v_mul_f32_e32 v103, v144, v103
	v_mul_f32_e32 v96, v144, v96
	v_mul_f32_e32 v97, v144, v97
	v_mul_f32_e32 v104, v144, v94
	v_mul_f32_e32 v105, v144, v95
	v_mul_f32_e32 v94, v144, v92
	v_mul_f32_e32 v95, v144, v93
	v_cvt_pk_bf16_f32 v92, v100, v101
	v_cvt_pk_bf16_f32 v93, v102, v103
	v_cvt_pk_bf16_f32 v94, v94, v95
	v_cvt_pk_bf16_f32 v95, v104, v105
	global_store_dwordx4 v[108:109], v[92:95], off offset:256
	v_mul_f32_e32 v84, v144, v84
	v_mul_f32_e32 v85, v144, v85
	v_mul_f32_e32 v86, v144, v86
	v_mul_f32_e32 v87, v144, v87
	v_or_b32_e32 v92, 32, v164
	v_ashrrev_i32_e32 v93, 31, v92
	v_lshlrev_b64 v[92:93], 11, v[92:93]
	v_lshl_add_u64 v[92:93], s[58:59], 0, v[92:93]
	v_lshl_add_u64 v[92:93], v[92:93], 0, v[168:169]
	v_mul_f32_e32 v94, v144, v98
	v_mul_f32_e32 v95, v144, v99
	v_mul_f32_e32 v98, v144, v90
	v_mul_f32_e32 v99, v144, v91
	v_mul_f32_e32 v90, v144, v88
	v_mul_f32_e32 v91, v144, v89
	v_cvt_pk_bf16_f32 v88, v96, v97
	v_cvt_pk_bf16_f32 v89, v94, v95
	v_cvt_pk_bf16_f32 v90, v90, v91
	v_cvt_pk_bf16_f32 v91, v98, v99
	global_store_dwordx4 v[92:93], v[88:91], off
	v_mul_f32_e32 v80, v144, v80
	v_mul_f32_e32 v81, v144, v81
	v_mul_f32_e32 v70, v144, v70
	v_mul_f32_e32 v71, v144, v71
	v_mul_f32_e32 v88, v144, v78
	v_mul_f32_e32 v89, v144, v79
	v_mul_f32_e32 v78, v144, v76
	v_mul_f32_e32 v79, v144, v77
	v_cvt_pk_bf16_f32 v76, v84, v85
	v_cvt_pk_bf16_f32 v77, v86, v87
	v_cvt_pk_bf16_f32 v78, v78, v79
	v_cvt_pk_bf16_f32 v79, v88, v89
	global_store_dwordx4 v[92:93], v[76:79], off offset:256
	v_mul_f32_e32 v68, v144, v68
	v_mul_f32_e32 v69, v144, v69
	v_mul_f32_e32 v60, v144, v60
	v_mul_f32_e32 v61, v144, v61
	v_or_b32_e32 v76, 48, v164
	v_ashrrev_i32_e32 v77, 31, v76
	v_lshlrev_b64 v[76:77], 11, v[76:77]
	v_lshl_add_u64 v[76:77], s[58:59], 0, v[76:77]
	v_lshl_add_u64 v[76:77], v[76:77], 0, v[168:169]
	v_mul_f32_e32 v78, v144, v82
	v_mul_f32_e32 v79, v144, v83
	v_mul_f32_e32 v82, v144, v74
	v_mul_f32_e32 v83, v144, v75
	v_mul_f32_e32 v74, v144, v72
	v_mul_f32_e32 v75, v144, v73
	v_cvt_pk_bf16_f32 v72, v80, v81
	v_cvt_pk_bf16_f32 v73, v78, v79
	v_cvt_pk_bf16_f32 v74, v74, v75
	v_cvt_pk_bf16_f32 v75, v82, v83
	global_store_dwordx4 v[76:77], v[72:75], off
	v_mul_f32_e32 v62, v144, v62
; __device__ __forceinline__ unsigned cvt_pk_bf16(float lo, float hi) { unsigned r; asm volatile("v_cvt_pk_bf16_f32 %0, %1, %2" : "=v"(r) : "v"(lo), "v"(hi)); return r; }
;     __device__ __forceinline__ void operator()(const f32x4 (&acc)[2][2][4][2], const Unit& u, int wr, int wc, int fr, int fq) const {
;     ...
;             for (int m = 0; m < 4; ++m) { const int row = row0 + ai * HALF + m * 16; bf16_t* rowp = O + (size_t)row * ldc + col0;
;                 float sc = sc0; if (ROWSCALE) sc *= 1.0f / sqrtf(SS[row] * (1.0f / 1024.0f) + 1e-6f);
; #pragma unroll
;                 for (int bj = 0; bj < 2; ++bj) { const f32x4 v0 = acc[ai][bj][m][0] * sc, v1 = acc[ai][bj][m][1] * sc;
;                     u32x4 w; w.x = cvt_pk_bf16(v0[0], v0[1]); w.y = cvt_pk_bf16(v0[2], v0[3]); w.z = cvt_pk_bf16(v1[0], v1[1]); w.w = cvt_pk_bf16(v1[2], v1[3]);
;                     *(u32x4*)(rowp + bj * HALF) = w; } }
	v_mul_f32_e32 v63, v144, v63
	v_mul_f32_e32 v54, v144, v54
	v_mul_f32_e32 v55, v144, v55
	v_mul_f32_e32 v72, v144, v66
	v_mul_f32_e32 v73, v144, v67
	v_mul_f32_e32 v66, v144, v64
	v_mul_f32_e32 v67, v144, v65
	v_cvt_pk_bf16_f32 v64, v68, v69
	v_cvt_pk_bf16_f32 v65, v70, v71
	v_cvt_pk_bf16_f32 v66, v66, v67
	v_cvt_pk_bf16_f32 v67, v72, v73
	global_store_dwordx4 v[76:77], v[64:67], off offset:256
	v_mul_f32_e32 v52, v144, v52
	v_mul_f32_e32 v53, v144, v53
	v_mul_f32_e32 v48, v144, v48
	v_mul_f32_e32 v49, v144, v49
	v_mul_f32_e32 v66, v144, v58
	v_mul_f32_e32 v67, v144, v59
	v_mul_f32_e32 v58, v144, v56
	v_mul_f32_e32 v59, v144, v57
	v_cvt_pk_bf16_f32 v56, v60, v61
	v_add_co_u32_e32 v60, vcc, s69, v146
	v_cvt_pk_bf16_f32 v57, v62, v63
	v_cvt_pk_bf16_f32 v58, v58, v59
	v_cvt_pk_bf16_f32 v59, v66, v67
	v_lshl_add_u64 v[64:65], v[146:147], 0, s[20:21]
	s_nop 0
	v_addc_co_u32_e32 v61, vcc, 0, v147, vcc
	global_store_dwordx4 v[60:61], v[56:59], off
	v_mul_f32_e32 v38, v144, v38
	v_mul_f32_e32 v39, v144, v39
	v_mul_f32_e32 v36, v144, v36
	v_mul_f32_e32 v37, v144, v37
	v_mul_f32_e32 v56, v144, v46
	v_mul_f32_e32 v57, v144, v47
	v_mul_f32_e32 v46, v144, v44
	v_mul_f32_e32 v47, v144, v45
	v_cvt_pk_bf16_f32 v44, v52, v53
	v_cvt_pk_bf16_f32 v45, v54, v55
	v_cvt_pk_bf16_f32 v46, v46, v47
	v_cvt_pk_bf16_f32 v47, v56, v57
	global_store_dwordx4 v[64:65], v[44:47], off offset:256
	v_mul_f32_e32 v32, v144, v32
	v_mul_f32_e32 v33, v144, v33
	v_mul_f32_e32 v22, v144, v22
	v_mul_f32_e32 v23, v144, v23
	v_mul_f32_e32 v46, v144, v50
	v_mul_f32_e32 v47, v144, v51
	v_mul_f32_e32 v50, v144, v42
	v_mul_f32_e32 v51, v144, v43
	v_mul_f32_e32 v42, v144, v40
	v_mul_f32_e32 v43, v144, v41
	v_cvt_pk_bf16_f32 v40, v48, v49
	v_cvt_pk_bf16_f32 v41, v46, v47
	v_add_co_u32_e32 v46, vcc, s70, v146
	v_cvt_pk_bf16_f32 v42, v42, v43
	v_cvt_pk_bf16_f32 v43, v50, v51
	v_lshl_add_u64 v[44:45], v[146:147], 0, s[22:23]
	s_nop 0
	v_addc_co_u32_e32 v47, vcc, 0, v147, vcc
	global_store_dwordx4 v[46:47], v[40:43], off
	v_mul_f32_e32 v20, v144, v20
	v_mul_f32_e32 v21, v144, v21
	v_mul_f32_e32 v16, v144, v16
	v_mul_f32_e32 v17, v144, v17
	v_mul_f32_e32 v40, v144, v30
	v_mul_f32_e32 v41, v144, v31
	v_mul_f32_e32 v30, v144, v28
	v_mul_f32_e32 v31, v144, v29
	v_cvt_pk_bf16_f32 v28, v36, v37
	v_cvt_pk_bf16_f32 v29, v38, v39
	v_cvt_pk_bf16_f32 v30, v30, v31
	v_cvt_pk_bf16_f32 v31, v40, v41
	global_store_dwordx4 v[44:45], v[28:31], off offset:256
	v_mul_f32_e32 v6, v144, v6
	v_mul_f32_e32 v7, v144, v7
	v_mul_f32_e32 v4, v144, v4
	v_mul_f32_e32 v5, v144, v5
	v_mul_f32_e32 v30, v144, v34
	v_mul_f32_e32 v31, v144, v35
	v_mul_f32_e32 v34, v144, v26
	v_mul_f32_e32 v35, v144, v27
	v_mul_f32_e32 v26, v144, v24
	v_mul_f32_e32 v27, v144, v25
	v_cvt_pk_bf16_f32 v24, v32, v33
	v_cvt_pk_bf16_f32 v25, v30, v31
	v_add_co_u32_e32 v30, vcc, s71, v146
	v_cvt_pk_bf16_f32 v26, v26, v27
	v_cvt_pk_bf16_f32 v27, v34, v35
	v_lshl_add_u64 v[28:29], v[146:147], 0, s[24:25]
	s_nop 0
	v_addc_co_u32_e32 v31, vcc, 0, v147, vcc
	global_store_dwordx4 v[30:31], v[24:27], off
	s_nop 1
	v_mul_f32_e32 v24, v144, v14
	v_mul_f32_e32 v25, v144, v15
	v_mul_f32_e32 v14, v144, v12
	v_mul_f32_e32 v15, v144, v13
	v_cvt_pk_bf16_f32 v12, v20, v21
	v_cvt_pk_bf16_f32 v13, v22, v23
	v_cvt_pk_bf16_f32 v14, v14, v15
	v_cvt_pk_bf16_f32 v15, v24, v25
	global_store_dwordx4 v[28:29], v[12:15], off offset:256
	s_nop 1
	v_mul_f32_e32 v14, v144, v18
	v_mul_f32_e32 v15, v144, v19
	v_mul_f32_e32 v18, v144, v10
	v_mul_f32_e32 v19, v144, v11
	v_mul_f32_e32 v10, v144, v8
	v_mul_f32_e32 v11, v144, v9
	v_cvt_pk_bf16_f32 v8, v16, v17
	v_cvt_pk_bf16_f32 v9, v14, v15
	v_add_co_u32_e32 v14, vcc, s72, v146
	v_lshl_add_u64 v[12:13], v[146:147], 0, s[38:39]
	s_nop 0
	v_addc_co_u32_e32 v15, vcc, 0, v147, vcc
	v_cvt_pk_bf16_f32 v10, v10, v11
	v_cvt_pk_bf16_f32 v11, v18, v19
	global_store_dwordx4 v[14:15], v[8:11], off
	s_and_b64 vcc, exec, s[4:5]
	s_mov_b64 s[4:5], -1
	v_mul_f32_e32 v8, v144, v2
	v_mul_f32_e32 v9, v144, v3
	v_mul_f32_e32 v2, v144, v0
	v_mul_f32_e32 v3, v144, v1
	v_cvt_pk_bf16_f32 v0, v4, v5
	v_cvt_pk_bf16_f32 v1, v6, v7
	v_cvt_pk_bf16_f32 v2, v2, v3
	v_cvt_pk_bf16_f32 v3, v8, v9
	global_store_dwordx4 v[12:13], v[0:3], off offset:256
	s_cbranch_vccnz .LBB0_1408
	s_andn2_b64 vcc, exec, s[12:13]
	s_cbranch_vccnz .LBB0_1407
	s_barrier
	s_branch .LBB0_1407

; __device__ __forceinline__ unsigned cvt_pk_bf16(float lo, float hi) { unsigned r; asm volatile("v_cvt_pk_bf16_f32 %0, %1, %2" : "=v"(r) : "v"(lo), "v"(hi)); return r; }
;     __device__ __forceinline__ void operator()(const f32x4 (&acc)[2][2][4][2], const Unit& u, int wr, int wc, int fr, int fq) const {
;         const int row0 = u.pm * BM + wr * 64 + fr; const int colt = u.pn * BM;
;         const float sc0 = (colt < qcols) ? qscale : 1.f;
;         const int col0 = colt + wc * 32 + 8 * fq;
; #pragma unroll
;         for (int ai = 0; ai < 2; ++ai)
; #pragma unroll
;             for (int m = 0; m < 4; ++m) { const int row = row0 + ai * HALF + m * 16; bf16_t* rowp = O + (size_t)row * ldc + col0;
;                 float sc = sc0; if (ROWSCALE) sc *= 1.0f / sqrtf(SS[row] * (1.0f / 1024.0f) + 1e-6f);
; #pragma unroll
;                 for (int bj = 0; bj < 2; ++bj) { const f32x4 v0 = acc[ai][bj][m][0] * sc, v1 = acc[ai][bj][m][1] * sc;
;                     u32x4 w; w.x = cvt_pk_bf16(v0[0], v0[1]); w.y = cvt_pk_bf16(v0[2], v0[3]); w.z = cvt_pk_bf16(v1[0], v1[1]); w.w = cvt_pk_bf16(v1[2], v1[3]);
;                     *(u32x4*)(rowp + bj * HALF) = w; } }
.LBB0_1447:
	v_lshl_add_u32 v150, s42, 8, v141
	s_cmp_lt_i32 s88, 0
	v_lshl_or_b32 v142, s88, 8, v145
	v_ashrrev_i32_e32 v151, 31, v150
	s_cselect_b64 vcc, -1, 0
	v_ashrrev_i32_e32 v143, 31, v142
	v_lshlrev_b64 v[152:153], 11, v[150:151]
	v_cndmask_b32_e32 v140, 1.0, v149, vcc
	v_lshl_add_u64 v[152:153], s[36:37], 0, v[152:153]
	v_lshlrev_b64 v[154:155], 1, v[142:143]
	v_lshl_add_u64 v[142:143], v[152:153], 0, v[154:155]
	v_mul_f32_e32 v126, v140, v126
	v_mul_f32_e32 v127, v140, v127
	v_mul_f32_e32 v124, v140, v124
	v_mul_f32_e32 v125, v140, v125
	v_mul_f32_e32 v152, v140, v122
	v_mul_f32_e32 v153, v140, v123
	v_mul_f32_e32 v122, v140, v120
	v_mul_f32_e32 v123, v140, v121
	v_cvt_pk_bf16_f32 v120, v124, v125
	v_cvt_pk_bf16_f32 v121, v126, v127
	v_cvt_pk_bf16_f32 v122, v122, v123
	v_cvt_pk_bf16_f32 v123, v152, v153
	global_store_dwordx4 v[142:143], v[120:123], off
	v_mul_f32_e32 v116, v140, v116
	v_mul_f32_e32 v117, v140, v117
	v_mul_f32_e32 v118, v140, v118
	v_mul_f32_e32 v119, v140, v119
	v_mul_f32_e32 v120, v140, v110
	v_mul_f32_e32 v121, v140, v111
	v_mul_f32_e32 v110, v140, v108
	v_mul_f32_e32 v111, v140, v109
	v_cvt_pk_bf16_f32 v108, v116, v117
	v_cvt_pk_bf16_f32 v109, v118, v119
	v_cvt_pk_bf16_f32 v110, v110, v111
	v_cvt_pk_bf16_f32 v111, v120, v121
	global_store_dwordx4 v[142:143], v[108:111], off offset:256
	v_mul_f32_e32 v112, v140, v112
	v_mul_f32_e32 v113, v140, v113
	v_mul_f32_e32 v100, v140, v100
	v_mul_f32_e32 v101, v140, v101
	v_or_b32_e32 v108, 16, v150
	v_ashrrev_i32_e32 v109, 31, v108
	v_lshlrev_b64 v[108:109], 11, v[108:109]
	v_lshl_add_u64 v[108:109], s[36:37], 0, v[108:109]
	v_lshl_add_u64 v[108:109], v[108:109], 0, v[154:155]
	v_mul_f32_e32 v110, v140, v114
	v_mul_f32_e32 v111, v140, v115
	v_mul_f32_e32 v114, v140, v106
	v_mul_f32_e32 v115, v140, v107
	v_mul_f32_e32 v106, v140, v104
	v_mul_f32_e32 v107, v140, v105
	v_cvt_pk_bf16_f32 v104, v112, v113
	v_cvt_pk_bf16_f32 v105, v110, v111
	v_cvt_pk_bf16_f32 v106, v106, v107
	v_cvt_pk_bf16_f32 v107, v114, v115
	global_store_dwordx4 v[108:109], v[104:107], off
	v_mul_f32_e32 v102, v140, v102
	v_mul_f32_e32 v103, v140, v103
	v_mul_f32_e32 v96, v140, v96
	v_mul_f32_e32 v97, v140, v97
	v_mul_f32_e32 v104, v140, v94
	v_mul_f32_e32 v105, v140, v95
	v_mul_f32_e32 v94, v140, v92
	v_mul_f32_e32 v95, v140, v93
	v_cvt_pk_bf16_f32 v92, v100, v101
	v_cvt_pk_bf16_f32 v93, v102, v103
	v_cvt_pk_bf16_f32 v94, v94, v95
	v_cvt_pk_bf16_f32 v95, v104, v105
	global_store_dwordx4 v[108:109], v[92:95], off offset:256
	v_mul_f32_e32 v84, v140, v84
	v_mul_f32_e32 v85, v140, v85
	v_mul_f32_e32 v86, v140, v86
	v_mul_f32_e32 v87, v140, v87
	v_or_b32_e32 v92, 32, v150
	v_ashrrev_i32_e32 v93, 31, v92
	v_lshlrev_b64 v[92:93], 11, v[92:93]
	v_lshl_add_u64 v[92:93], s[36:37], 0, v[92:93]
	v_lshl_add_u64 v[92:93], v[92:93], 0, v[154:155]
	v_mul_f32_e32 v94, v140, v98
	v_mul_f32_e32 v95, v140, v99
	v_mul_f32_e32 v98, v140, v90
	v_mul_f32_e32 v99, v140, v91
	v_mul_f32_e32 v90, v140, v88
	v_mul_f32_e32 v91, v140, v89
	v_cvt_pk_bf16_f32 v88, v96, v97
	v_cvt_pk_bf16_f32 v89, v94, v95
	v_cvt_pk_bf16_f32 v90, v90, v91
	v_cvt_pk_bf16_f32 v91, v98, v99
	global_store_dwordx4 v[92:93], v[88:91], off
	v_mul_f32_e32 v80, v140, v80
	v_mul_f32_e32 v81, v140, v81
	v_mul_f32_e32 v70, v140, v70
	v_mul_f32_e32 v71, v140, v71
	v_mul_f32_e32 v88, v140, v78
	v_mul_f32_e32 v89, v140, v79
	v_mul_f32_e32 v78, v140, v76
	v_mul_f32_e32 v79, v140, v77
	v_cvt_pk_bf16_f32 v76, v84, v85
	v_cvt_pk_bf16_f32 v77, v86, v87
	v_cvt_pk_bf16_f32 v78, v78, v79
	v_cvt_pk_bf16_f32 v79, v88, v89
	global_store_dwordx4 v[92:93], v[76:79], off offset:256
	v_mul_f32_e32 v68, v140, v68
	v_mul_f32_e32 v69, v140, v69
	v_mul_f32_e32 v60, v140, v60
	v_mul_f32_e32 v61, v140, v61
	v_or_b32_e32 v76, 48, v150
	v_ashrrev_i32_e32 v77, 31, v76
	v_lshlrev_b64 v[76:77], 11, v[76:77]
	v_lshl_add_u64 v[76:77], s[36:37], 0, v[76:77]
	v_lshl_add_u64 v[76:77], v[76:77], 0, v[154:155]
	v_mul_f32_e32 v78, v140, v82
	v_mul_f32_e32 v79, v140, v83
	v_mul_f32_e32 v82, v140, v74
	v_mul_f32_e32 v83, v140, v75
	v_mul_f32_e32 v74, v140, v72
	v_mul_f32_e32 v75, v140, v73
	v_cvt_pk_bf16_f32 v72, v80, v81
	v_cvt_pk_bf16_f32 v73, v78, v79
	v_cvt_pk_bf16_f32 v74, v74, v75
	v_cvt_pk_bf16_f32 v75, v82, v83
	global_store_dwordx4 v[76:77], v[72:75], off
	v_mul_f32_e32 v62, v140, v62
	v_mul_f32_e32 v63, v140, v63
; __device__ __forceinline__ unsigned cvt_pk_bf16(float lo, float hi) { unsigned r; asm volatile("v_cvt_pk_bf16_f32 %0, %1, %2" : "=v"(r) : "v"(lo), "v"(hi)); return r; }
;     __device__ __forceinline__ void operator()(const f32x4 (&acc)[2][2][4][2], const Unit& u, int wr, int wc, int fr, int fq) const {
;     ...
;             for (int m = 0; m < 4; ++m) { const int row = row0 + ai * HALF + m * 16; bf16_t* rowp = O + (size_t)row * ldc + col0;
;                 float sc = sc0; if (ROWSCALE) sc *= 1.0f / sqrtf(SS[row] * (1.0f / 1024.0f) + 1e-6f);
; #pragma unroll
;                 for (int bj = 0; bj < 2; ++bj) { const f32x4 v0 = acc[ai][bj][m][0] * sc, v1 = acc[ai][bj][m][1] * sc;
;                     u32x4 w; w.x = cvt_pk_bf16(v0[0], v0[1]); w.y = cvt_pk_bf16(v0[2], v0[3]); w.z = cvt_pk_bf16(v1[0], v1[1]); w.w = cvt_pk_bf16(v1[2], v1[3]);
;                     *(u32x4*)(rowp + bj * HALF) = w; } }
	s_mov_b64 s[8:9], 0x40000
	v_mul_f32_e32 v72, v140, v66
	v_mul_f32_e32 v73, v140, v67
	v_mul_f32_e32 v66, v140, v64
	v_mul_f32_e32 v67, v140, v65
	v_cvt_pk_bf16_f32 v64, v68, v69
	v_cvt_pk_bf16_f32 v65, v70, v71
	v_cvt_pk_bf16_f32 v66, v66, v67
	v_cvt_pk_bf16_f32 v67, v72, v73
	global_store_dwordx4 v[76:77], v[64:67], off offset:256
	v_mul_f32_e32 v54, v140, v54
	v_mul_f32_e32 v55, v140, v55
	v_mul_f32_e32 v52, v140, v52
	v_mul_f32_e32 v53, v140, v53
	v_mul_f32_e32 v66, v140, v58
	v_mul_f32_e32 v67, v140, v59
	v_mul_f32_e32 v58, v140, v56
	v_mul_f32_e32 v59, v140, v57
	v_cvt_pk_bf16_f32 v56, v60, v61
	v_add_co_u32_e32 v60, vcc, s82, v142
	v_cvt_pk_bf16_f32 v57, v62, v63
	v_cvt_pk_bf16_f32 v58, v58, v59
	v_cvt_pk_bf16_f32 v59, v66, v67
	v_lshl_add_u64 v[64:65], v[142:143], 0, s[8:9]
	s_nop 0
	v_addc_co_u32_e32 v61, vcc, 0, v143, vcc
	global_store_dwordx4 v[60:61], v[56:59], off
	v_mul_f32_e32 v48, v140, v48
	v_mul_f32_e32 v49, v140, v49
	v_mul_f32_e32 v38, v140, v38
	v_mul_f32_e32 v39, v140, v39
	v_mul_f32_e32 v56, v140, v46
	v_mul_f32_e32 v57, v140, v47
	v_mul_f32_e32 v46, v140, v44
	v_mul_f32_e32 v47, v140, v45
	v_cvt_pk_bf16_f32 v44, v52, v53
	v_cvt_pk_bf16_f32 v45, v54, v55
	v_cvt_pk_bf16_f32 v46, v46, v47
	v_cvt_pk_bf16_f32 v47, v56, v57
	global_store_dwordx4 v[64:65], v[44:47], off offset:256
	v_mul_f32_e32 v36, v140, v36
	v_mul_f32_e32 v37, v140, v37
	v_mul_f32_e32 v32, v140, v32
	v_mul_f32_e32 v33, v140, v33
	v_mul_f32_e32 v46, v140, v50
	v_mul_f32_e32 v47, v140, v51
	v_mul_f32_e32 v50, v140, v42
	v_mul_f32_e32 v51, v140, v43
	v_mul_f32_e32 v42, v140, v40
	v_mul_f32_e32 v43, v140, v41
	v_cvt_pk_bf16_f32 v40, v48, v49
	v_cvt_pk_bf16_f32 v41, v46, v47
	v_add_co_u32_e32 v46, vcc, s83, v142
	v_cvt_pk_bf16_f32 v42, v42, v43
	v_cvt_pk_bf16_f32 v43, v50, v51
	v_lshl_add_u64 v[44:45], v[142:143], 0, s[14:15]
	s_nop 0
	v_addc_co_u32_e32 v47, vcc, 0, v143, vcc
	global_store_dwordx4 v[46:47], v[40:43], off
	v_mul_f32_e32 v22, v140, v22
	v_mul_f32_e32 v23, v140, v23
	v_mul_f32_e32 v20, v140, v20
	v_mul_f32_e32 v21, v140, v21
	v_mul_f32_e32 v40, v140, v30
	v_mul_f32_e32 v41, v140, v31
	v_mul_f32_e32 v30, v140, v28
	v_mul_f32_e32 v31, v140, v29
	v_cvt_pk_bf16_f32 v28, v36, v37
	v_cvt_pk_bf16_f32 v29, v38, v39
	v_cvt_pk_bf16_f32 v30, v30, v31
	v_cvt_pk_bf16_f32 v31, v40, v41
	global_store_dwordx4 v[44:45], v[28:31], off offset:256
	v_mul_f32_e32 v16, v140, v16
	v_mul_f32_e32 v17, v140, v17
	v_mul_f32_e32 v6, v140, v6
	v_mul_f32_e32 v7, v140, v7
	v_mul_f32_e32 v30, v140, v34
	v_mul_f32_e32 v31, v140, v35
	v_mul_f32_e32 v34, v140, v26
	v_mul_f32_e32 v35, v140, v27
	v_mul_f32_e32 v26, v140, v24
	v_mul_f32_e32 v27, v140, v25
	v_cvt_pk_bf16_f32 v24, v32, v33
	v_cvt_pk_bf16_f32 v25, v30, v31
	v_add_co_u32_e32 v30, vcc, s86, v142
	v_cvt_pk_bf16_f32 v26, v26, v27
	v_cvt_pk_bf16_f32 v27, v34, v35
	v_lshl_add_u64 v[28:29], v[142:143], 0, s[18:19]
	s_nop 0
	v_addc_co_u32_e32 v31, vcc, 0, v143, vcc
	global_store_dwordx4 v[30:31], v[24:27], off
	v_mul_f32_e32 v4, v140, v4
	v_mul_f32_e32 v5, v140, v5
	s_nop 0
	v_mul_f32_e32 v24, v140, v14
	v_mul_f32_e32 v25, v140, v15
	v_mul_f32_e32 v14, v140, v12
	v_mul_f32_e32 v15, v140, v13
	v_cvt_pk_bf16_f32 v12, v20, v21
	v_cvt_pk_bf16_f32 v13, v22, v23
	v_cvt_pk_bf16_f32 v14, v14, v15
	v_cvt_pk_bf16_f32 v15, v24, v25
	global_store_dwordx4 v[28:29], v[12:15], off offset:256
	s_nop 1
	v_mul_f32_e32 v14, v140, v18
	v_mul_f32_e32 v15, v140, v19
	v_mul_f32_e32 v18, v140, v10
	v_mul_f32_e32 v19, v140, v11
	v_mul_f32_e32 v10, v140, v8
	v_mul_f32_e32 v11, v140, v9
	v_cvt_pk_bf16_f32 v8, v16, v17
	v_cvt_pk_bf16_f32 v9, v14, v15
	v_add_co_u32_e32 v14, vcc, s87, v142
	v_lshl_add_u64 v[12:13], v[142:143], 0, s[20:21]
	s_nop 0
	v_addc_co_u32_e32 v15, vcc, 0, v143, vcc
	v_cvt_pk_bf16_f32 v10, v10, v11
	v_cvt_pk_bf16_f32 v11, v18, v19
	global_store_dwordx4 v[14:15], v[8:11], off
	s_andn2_b64 vcc, exec, s[4:5]
	s_mov_b64 s[4:5], -1
	v_mul_f32_e32 v8, v140, v2
	v_mul_f32_e32 v9, v140, v3
	v_mul_f32_e32 v2, v140, v0
	v_mul_f32_e32 v3, v140, v1
	v_cvt_pk_bf16_f32 v0, v4, v5
	v_cvt_pk_bf16_f32 v1, v6, v7
	v_cvt_pk_bf16_f32 v2, v2, v3
	v_cvt_pk_bf16_f32 v3, v8, v9
	global_store_dwordx4 v[12:13], v[0:3], off offset:256
	s_cbranch_vccnz .LBB0_1436
	s_andn2_b64 vcc, exec, s[0:1]
	s_cbranch_vccnz .LBB0_1435
	s_barrier
	s_branch .LBB0_1435

; __device__ __forceinline__ float bf_lo(unsigned w) { return __uint_as_float(w << 16); }
; __device__ __forceinline__ float bf_hi(unsigned w) { return __uint_as_float(w & 0xffff0000u); }
; __device__ __forceinline__ float sigmoid_f(float x) { return __builtin_amdgcn_rcpf(1.0f + __builtin_amdgcn_exp2f(-1.4426950408889634f * x)); }
;     __device__ __forceinline__ void operator()(const f32x4 (&acc)[2][2][4][2], const Unit& u, int wr, int wc, int fr, int fq) const {
;     ...
;             for (int m = 0; m < 4; ++m) { const int row = row0 + ai * HALF + m * 16; const size_t off = (size_t)row * 1024 + col0; float rs = 0.f;
; #pragma unroll
;                 for (int bj = 0; bj < 2; ++bj) { const size_t c = off + bj * HALF;
;                     const u32x4 hw = *(const u32x4*)(Hin + c); const u32x4 pw = *(const u32x4*)(PP + c);
;                     float o[8];
; #pragma unroll
;                     for (int n = 0; n < 2; ++n)
; #pragma unroll
;                         for (int w = 0; w < 2; ++w) { const unsigned hh = hw[2 * n + w], pp = pw[2 * n + w]; const f32x4 a = acc[ai][bj][m][n];
;                             o[4 * n + 2 * w] = bf_lo(hh) + bf_lo(pp) * sigmoid_f(a[2 * w]); o[4 * n + 2 * w + 1] = bf_hi(hh) + bf_hi(pp) * sigmoid_f(a[2 * w + 1]); }
;                     if (MODE == 1) { *(f32x4*)(Fout + c) = (f32x4){o[0], o[1], o[2], o[3]}; *(f32x4*)(Fout + c + 4) = (f32x4){o[4], o[5], o[6], o[7]}; }
.LBB0_1620:
	v_lshl_add_u32 v148, s30, 8, v150
	v_lshl_or_b32 v146, s54, 8, v152
	v_ashrrev_i32_e32 v149, 31, v148
	v_ashrrev_i32_e32 v147, 31, v146
	v_lshlrev_b64 v[144:145], 10, v[148:149]
	v_lshl_add_u64 v[144:145], v[144:145], 0, v[146:147]
	v_lshlrev_b64 v[164:165], 1, v[144:145]
	v_lshl_add_u64 v[156:157], s[16:17], 0, v[164:165]
	v_lshl_add_u64 v[160:161], s[36:37], 0, v[164:165]
	global_load_dwordx4 v[156:159], v[156:157], off
	v_mul_f32_e32 v124, 0xbfb8aa3b, v124
	global_load_dwordx4 v[160:163], v[160:161], off
	v_mul_f32_e32 v125, 0xbfb8aa3b, v125
	v_mul_f32_e32 v126, 0xbfb8aa3b, v126
	v_mul_f32_e32 v127, 0xbfb8aa3b, v127
	v_mul_f32_e32 v120, 0xbfb8aa3b, v120
	v_mul_f32_e32 v121, 0xbfb8aa3b, v121
	v_mul_f32_e32 v122, 0xbfb8aa3b, v122
	v_mul_f32_e32 v123, 0xbfb8aa3b, v123
	v_exp_f32_e32 v124, v124
	v_exp_f32_e32 v125, v125
	v_exp_f32_e32 v126, v126
	v_exp_f32_e32 v127, v127
	v_exp_f32_e32 v120, v120
	v_exp_f32_e32 v121, v121
	v_exp_f32_e32 v122, v122
	v_exp_f32_e32 v123, v123
	v_add_f32_e32 v124, 1.0, v124
	v_add_f32_e32 v125, 1.0, v125
	v_add_f32_e32 v126, 1.0, v126
	v_add_f32_e32 v127, 1.0, v127
	v_add_f32_e32 v149, 1.0, v120
	v_add_f32_e32 v168, 1.0, v121
	v_add_f32_e32 v169, 1.0, v122
	v_add_f32_e32 v170, 1.0, v123
	v_rcp_f32_e32 v120, v124
	v_rcp_f32_e32 v121, v125
	v_rcp_f32_e32 v122, v126
	v_rcp_f32_e32 v123, v127
	v_rcp_f32_e32 v124, v149
	v_rcp_f32_e32 v125, v168
	v_rcp_f32_e32 v126, v169
	v_rcp_f32_e32 v127, v170
	v_lshl_add_u64 v[166:167], v[144:145], 2, s[58:59]
	v_or_b32_e32 v164, 0x100, v164
	v_lshl_add_u64 v[168:169], s[16:17], 0, v[164:165]
	v_mul_f32_e32 v116, 0xbfb8aa3b, v116
	v_mul_f32_e32 v117, 0xbfb8aa3b, v117
	v_mul_f32_e32 v118, 0xbfb8aa3b, v118
	v_mul_f32_e32 v119, 0xbfb8aa3b, v119
	v_mul_f32_e32 v112, 0xbfb8aa3b, v112
	v_mul_f32_e32 v113, 0xbfb8aa3b, v113
	v_mul_f32_e32 v114, 0xbfb8aa3b, v114
	v_mul_f32_e32 v115, 0xbfb8aa3b, v115
	v_exp_f32_e32 v116, v116
	v_exp_f32_e32 v117, v117
	v_exp_f32_e32 v118, v118
	v_exp_f32_e32 v119, v119
	v_exp_f32_e32 v149, v112
	v_exp_f32_e32 v114, v114
	v_exp_f32_e32 v115, v115
	v_or_b32_e32 v112, 16, v148
	v_mul_f32_e32 v108, 0xbfb8aa3b, v108
	v_mul_f32_e32 v109, 0xbfb8aa3b, v109
	v_mul_f32_e32 v110, 0xbfb8aa3b, v110
	v_mul_f32_e32 v111, 0xbfb8aa3b, v111
	v_mul_f32_e32 v104, 0xbfb8aa3b, v104
	v_mul_f32_e32 v105, 0xbfb8aa3b, v105
	v_mul_f32_e32 v106, 0xbfb8aa3b, v106
	v_mul_f32_e32 v107, 0xbfb8aa3b, v107
	v_exp_f32_e32 v108, v108
	v_exp_f32_e32 v109, v109
	v_exp_f32_e32 v110, v110
	v_exp_f32_e32 v111, v111
	v_exp_f32_e32 v104, v104
	v_exp_f32_e32 v105, v105
	v_exp_f32_e32 v106, v106
	v_exp_f32_e32 v107, v107
	v_add_f32_e32 v108, 1.0, v108
	v_add_f32_e32 v109, 1.0, v109
	v_add_f32_e32 v110, 1.0, v110
	v_add_f32_e32 v111, 1.0, v111
	v_mul_f32_e32 v100, 0xbfb8aa3b, v100
	v_mul_f32_e32 v101, 0xbfb8aa3b, v101
	v_mul_f32_e32 v102, 0xbfb8aa3b, v102
	v_mul_f32_e32 v103, 0xbfb8aa3b, v103
	v_mul_f32_e32 v96, 0xbfb8aa3b, v96
	v_mul_f32_e32 v97, 0xbfb8aa3b, v97
	v_mul_f32_e32 v98, 0xbfb8aa3b, v98
	s_waitcnt vmcnt(0)
	v_lshlrev_b32_e32 v170, 16, v156
	v_and_b32_e32 v171, 0xffff0000, v156
	v_lshlrev_b32_e32 v172, 16, v160
	v_and_b32_e32 v173, 0xffff0000, v160
	v_lshlrev_b32_e32 v156, 16, v157
	v_and_b32_e32 v157, 0xffff0000, v157
	v_lshlrev_b32_e32 v160, 16, v161
	v_and_b32_e32 v161, 0xffff0000, v161
	v_lshlrev_b32_e32 v174, 16, v158
	v_and_b32_e32 v175, 0xffff0000, v158
	v_lshlrev_b32_e32 v176, 16, v162
	v_and_b32_e32 v177, 0xffff0000, v162
	v_lshlrev_b32_e32 v158, 16, v159
	v_and_b32_e32 v159, 0xffff0000, v159
	v_lshlrev_b32_e32 v162, 16, v163
	v_and_b32_e32 v163, 0xffff0000, v163
	v_fma_f32 v120, v120, v172, v170
	v_fma_f32 v121, v121, v173, v171
	v_fma_f32 v122, v122, v160, v156
	v_fma_f32 v123, v123, v161, v157
	v_fma_f32 v124, v124, v176, v174
	v_fma_f32 v125, v125, v177, v175
	v_fma_f32 v126, v126, v162, v158
	v_fma_f32 v127, v127, v163, v159
	global_store_dwordx4 v[166:167], v[120:123], off
	global_store_dwordx4 v[166:167], v[124:127], off offset:16
	global_load_dwordx4 v[120:123], v[168:169], off
	v_exp_f32_e32 v158, v113
	v_lshl_add_u64 v[124:125], s[36:37], 0, v[164:165]
	global_load_dwordx4 v[124:127], v[124:125], off
	v_ashrrev_i32_e32 v113, 31, v112
	v_lshlrev_b64 v[112:113], 10, v[112:113]
	v_lshl_add_u64 v[156:157], v[112:113], 0, v[146:147]
	v_add_f32_e32 v112, 1.0, v116
	v_add_f32_e32 v113, 1.0, v117
	v_add_f32_e32 v116, 1.0, v118
	v_add_f32_e32 v117, 1.0, v119
	v_add_f32_e32 v118, 1.0, v149
	v_add_f32_e32 v119, 1.0, v158
	v_add_f32_e32 v149, 1.0, v114
	v_add_f32_e32 v160, 1.0, v115
	v_rcp_f32_e32 v112, v112
	v_rcp_f32_e32 v113, v113
	v_rcp_f32_e32 v114, v116
	v_rcp_f32_e32 v115, v117
	v_rcp_f32_e32 v116, v118
	v_rcp_f32_e32 v117, v119
	v_rcp_f32_e32 v118, v149
	v_rcp_f32_e32 v119, v160
	v_lshlrev_b64 v[158:159], 1, v[156:157]
	v_lshl_add_u64 v[160:161], s[16:17], 0, v[158:159]
	v_mul_f32_e32 v99, 0xbfb8aa3b, v99
	v_exp_f32_e32 v100, v100
	v_exp_f32_e32 v101, v101
	v_exp_f32_e32 v102, v102
	v_exp_f32_e32 v103, v103
	v_exp_f32_e32 v98, v98
	v_exp_f32_e32 v99, v99
	v_mul_f32_e32 v92, 0xbfb8aa3b, v92
	v_mul_f32_e32 v93, 0xbfb8aa3b, v93
	v_mul_f32_e32 v94, 0xbfb8aa3b, v94
	v_mul_f32_e32 v95, 0xbfb8aa3b, v95
	v_mul_f32_e32 v88, 0xbfb8aa3b, v88
	v_mul_f32_e32 v89, 0xbfb8aa3b, v89
	v_mul_f32_e32 v90, 0xbfb8aa3b, v90
	v_mul_f32_e32 v91, 0xbfb8aa3b, v91
	v_exp_f32_e32 v92, v92
	v_exp_f32_e32 v93, v93
	v_exp_f32_e32 v94, v94
	v_exp_f32_e32 v95, v95
	v_exp_f32_e32 v88, v88
	v_exp_f32_e32 v89, v89
	v_exp_f32_e32 v90, v90
	v_exp_f32_e32 v91, v91
	v_add_f32_e32 v92, 1.0, v92
	v_add_f32_e32 v93, 1.0, v93
	v_add_f32_e32 v94, 1.0, v94
	v_add_f32_e32 v95, 1.0, v95
	v_mul_f32_e32 v84, 0xbfb8aa3b, v84
	v_mul_f32_e32 v85, 0xbfb8aa3b, v85
	v_mul_f32_e32 v86, 0xbfb8aa3b, v86
	v_mul_f32_e32 v87, 0xbfb8aa3b, v87
	v_mul_f32_e32 v80, 0xbfb8aa3b, v80
	v_mul_f32_e32 v81, 0xbfb8aa3b, v81
	v_mul_f32_e32 v82, 0xbfb8aa3b, v82
	v_mul_f32_e32 v83, 0xbfb8aa3b, v83
	v_exp_f32_e32 v84, v84
	v_exp_f32_e32 v85, v85
	v_exp_f32_e32 v86, v86
	v_exp_f32_e32 v87, v87
	v_exp_f32_e32 v82, v82
	v_exp_f32_e32 v83, v83
	v_mul_f32_e32 v76, 0xbfb8aa3b, v76
	v_mul_f32_e32 v77, 0xbfb8aa3b, v77
	v_mul_f32_e32 v78, 0xbfb8aa3b, v78
	v_mul_f32_e32 v79, 0xbfb8aa3b, v79
	v_mul_f32_e32 v72, 0xbfb8aa3b, v72
	v_mul_f32_e32 v73, 0xbfb8aa3b, v73
	v_mul_f32_e32 v74, 0xbfb8aa3b, v74
	v_mul_f32_e32 v75, 0xbfb8aa3b, v75
	v_exp_f32_e32 v76, v76
	v_exp_f32_e32 v77, v77
	v_exp_f32_e32 v78, v78
	v_exp_f32_e32 v79, v79
	v_exp_f32_e32 v72, v72
	v_exp_f32_e32 v73, v73
	s_waitcnt vmcnt(1)
; __device__ __forceinline__ float bf_lo(unsigned w) { return __uint_as_float(w << 16); }
; __device__ __forceinline__ float bf_hi(unsigned w) { return __uint_as_float(w & 0xffff0000u); }
; __device__ __forceinline__ float sigmoid_f(float x) { return __builtin_amdgcn_rcpf(1.0f + __builtin_amdgcn_exp2f(-1.4426950408889634f * x)); }
;     __device__ __forceinline__ void operator()(const f32x4 (&acc)[2][2][4][2], const Unit& u, int wr, int wc, int fr, int fq) const {
;     ...
;             for (int m = 0; m < 4; ++m) { const int row = row0 + ai * HALF + m * 16; const size_t off = (size_t)row * 1024 + col0; float rs = 0.f;
; #pragma unroll
;                 for (int bj = 0; bj < 2; ++bj) { const size_t c = off + bj * HALF;
;                     const u32x4 hw = *(const u32x4*)(Hin + c); const u32x4 pw = *(const u32x4*)(PP + c);
;                     float o[8];
; #pragma unroll
;                     for (int n = 0; n < 2; ++n)
; #pragma unroll
;                         for (int w = 0; w < 2; ++w) { const unsigned hh = hw[2 * n + w], pp = pw[2 * n + w]; const f32x4 a = acc[ai][bj][m][n];
;                             o[4 * n + 2 * w] = bf_lo(hh) + bf_lo(pp) * sigmoid_f(a[2 * w]); o[4 * n + 2 * w + 1] = bf_hi(hh) + bf_hi(pp) * sigmoid_f(a[2 * w + 1]); }
;                     if (MODE == 1) { *(f32x4*)(Fout + c) = (f32x4){o[0], o[1], o[2], o[3]}; *(f32x4*)(Fout + c + 4) = (f32x4){o[4], o[5], o[6], o[7]}; }
	v_lshlrev_b32_e32 v162, 16, v120
	v_and_b32_e32 v163, 0xffff0000, v120
	v_lshlrev_b32_e32 v120, 16, v121
	s_waitcnt vmcnt(0)
	v_lshlrev_b32_e32 v164, 16, v124
	v_and_b32_e32 v165, 0xffff0000, v124
	v_and_b32_e32 v121, 0xffff0000, v121
	v_lshlrev_b32_e32 v124, 16, v125
	v_and_b32_e32 v125, 0xffff0000, v125
	v_lshlrev_b32_e32 v168, 16, v122
	v_and_b32_e32 v169, 0xffff0000, v122
	v_lshlrev_b32_e32 v170, 16, v126
	v_and_b32_e32 v171, 0xffff0000, v126
	v_lshlrev_b32_e32 v122, 16, v123
	v_and_b32_e32 v123, 0xffff0000, v123
	v_lshlrev_b32_e32 v126, 16, v127
	v_and_b32_e32 v127, 0xffff0000, v127
	v_fma_f32 v112, v112, v164, v162
	v_fma_f32 v113, v113, v165, v163
	v_fma_f32 v114, v114, v124, v120
	v_fma_f32 v115, v115, v125, v121
	v_fma_f32 v116, v116, v170, v168
	v_fma_f32 v117, v117, v171, v169
	v_fma_f32 v118, v118, v126, v122
	v_fma_f32 v119, v119, v127, v123
	global_store_dwordx4 v[166:167], v[112:115], off offset:512
	global_store_dwordx4 v[166:167], v[116:119], off offset:528
	global_load_dwordx4 v[112:115], v[160:161], off
	v_add_f32_e32 v122, 1.0, v104
	v_lshl_add_u64 v[116:117], s[36:37], 0, v[158:159]
	global_load_dwordx4 v[116:119], v[116:117], off
	v_add_f32_e32 v123, 1.0, v105
	v_add_f32_e32 v124, 1.0, v106
	v_add_f32_e32 v125, 1.0, v107
	v_rcp_f32_e32 v104, v108
	v_rcp_f32_e32 v105, v109
	v_rcp_f32_e32 v106, v110
	v_rcp_f32_e32 v107, v111
	v_rcp_f32_e32 v108, v122
	v_rcp_f32_e32 v109, v123
	v_rcp_f32_e32 v110, v124
	v_rcp_f32_e32 v111, v125
	v_lshl_add_u64 v[120:121], v[156:157], 2, s[58:59]
	v_or_b32_e32 v158, 0x100, v158
	v_lshl_add_u64 v[122:123], s[16:17], 0, v[158:159]
	v_exp_f32_e32 v74, v74
	v_exp_f32_e32 v75, v75
	v_add_f32_e32 v76, 1.0, v76
	v_add_f32_e32 v77, 1.0, v77
	v_add_f32_e32 v78, 1.0, v78
	v_add_f32_e32 v79, 1.0, v79
	v_mul_f32_e32 v68, 0xbfb8aa3b, v68
	v_mul_f32_e32 v69, 0xbfb8aa3b, v69
	v_mul_f32_e32 v70, 0xbfb8aa3b, v70
	v_mul_f32_e32 v71, 0xbfb8aa3b, v71
	v_mul_f32_e32 v64, 0xbfb8aa3b, v64
	v_mul_f32_e32 v65, 0xbfb8aa3b, v65
	v_mul_f32_e32 v66, 0xbfb8aa3b, v66
	v_mul_f32_e32 v67, 0xbfb8aa3b, v67
	v_exp_f32_e32 v68, v68
	v_exp_f32_e32 v69, v69
	v_exp_f32_e32 v70, v70
	v_exp_f32_e32 v71, v71
	v_exp_f32_e32 v64, v64
	v_exp_f32_e32 v65, v65
	v_exp_f32_e32 v66, v66
	v_exp_f32_e32 v67, v67
	v_add_f32_e32 v68, 1.0, v68
	v_add_f32_e32 v69, 1.0, v69
	v_add_f32_e32 v70, 1.0, v70
	v_add_f32_e32 v71, 1.0, v71
	v_mul_f32_e32 v60, 0xbfb8aa3b, v60
	v_mul_f32_e32 v61, 0xbfb8aa3b, v61
	v_mul_f32_e32 v62, 0xbfb8aa3b, v62
	v_mul_f32_e32 v63, 0xbfb8aa3b, v63
	v_mul_f32_e32 v56, 0xbfb8aa3b, v56
	v_mul_f32_e32 v57, 0xbfb8aa3b, v57
	v_mul_f32_e32 v58, 0xbfb8aa3b, v58
	v_mul_f32_e32 v59, 0xbfb8aa3b, v59
	v_exp_f32_e32 v60, v60
	v_exp_f32_e32 v61, v61
	v_exp_f32_e32 v62, v62
	v_exp_f32_e32 v63, v63
	v_exp_f32_e32 v56, v56
	v_exp_f32_e32 v57, v57
	v_exp_f32_e32 v58, v58
	v_exp_f32_e32 v59, v59
	v_add_f32_e32 v60, 1.0, v60
	v_add_f32_e32 v61, 1.0, v61
	v_add_f32_e32 v62, 1.0, v62
	v_add_f32_e32 v63, 1.0, v63
	v_mul_f32_e32 v52, 0xbfb8aa3b, v52
	v_mul_f32_e32 v53, 0xbfb8aa3b, v53
	v_mul_f32_e32 v54, 0xbfb8aa3b, v54
	v_mul_f32_e32 v55, 0xbfb8aa3b, v55
	v_mul_f32_e32 v48, 0xbfb8aa3b, v48
	v_mul_f32_e32 v49, 0xbfb8aa3b, v49
	v_mul_f32_e32 v50, 0xbfb8aa3b, v50
	v_mul_f32_e32 v51, 0xbfb8aa3b, v51
	v_exp_f32_e32 v52, v52
	v_exp_f32_e32 v53, v53
	v_exp_f32_e32 v54, v54
	v_exp_f32_e32 v55, v55
	v_exp_f32_e32 v48, v48
	v_exp_f32_e32 v49, v49
	v_exp_f32_e32 v50, v50
	v_exp_f32_e32 v51, v51
	s_waitcnt vmcnt(1)
	v_lshlrev_b32_e32 v124, 16, v112
	v_and_b32_e32 v125, 0xffff0000, v112
	v_lshlrev_b32_e32 v112, 16, v113
	s_waitcnt vmcnt(0)
	v_lshlrev_b32_e32 v126, 16, v116
	v_and_b32_e32 v127, 0xffff0000, v116
	v_and_b32_e32 v113, 0xffff0000, v113
	v_lshlrev_b32_e32 v116, 16, v117
	v_and_b32_e32 v117, 0xffff0000, v117
	v_lshlrev_b32_e32 v156, 16, v114
	v_and_b32_e32 v157, 0xffff0000, v114
	v_lshlrev_b32_e32 v160, 16, v118
	v_and_b32_e32 v161, 0xffff0000, v118
	v_lshlrev_b32_e32 v114, 16, v115
	v_and_b32_e32 v115, 0xffff0000, v115
	v_lshlrev_b32_e32 v118, 16, v119
	v_and_b32_e32 v119, 0xffff0000, v119
	v_fma_f32 v104, v104, v126, v124
	v_fma_f32 v105, v105, v127, v125
	v_fma_f32 v106, v106, v116, v112
	v_fma_f32 v107, v107, v117, v113
	v_fma_f32 v108, v108, v160, v156
	v_fma_f32 v109, v109, v161, v157
	v_fma_f32 v110, v110, v118, v114
	v_fma_f32 v111, v111, v119, v115
	global_store_dwordx4 v[120:121], v[104:107], off
	global_store_dwordx4 v[120:121], v[108:111], off offset:16
	global_load_dwordx4 v[104:107], v[122:123], off
	v_exp_f32_e32 v114, v96
	v_lshl_add_u64 v[108:109], s[36:37], 0, v[158:159]
	global_load_dwordx4 v[108:111], v[108:109], off
	v_exp_f32_e32 v115, v97
	v_or_b32_e32 v96, 32, v148
	v_ashrrev_i32_e32 v97, 31, v96
	v_lshlrev_b64 v[96:97], 10, v[96:97]
	v_lshl_add_u64 v[112:113], v[96:97], 0, v[146:147]
	v_add_f32_e32 v96, 1.0, v100
	v_add_f32_e32 v97, 1.0, v101
	v_add_f32_e32 v100, 1.0, v102
	v_add_f32_e32 v101, 1.0, v103
	v_add_f32_e32 v102, 1.0, v114
	v_add_f32_e32 v103, 1.0, v115
	v_add_f32_e32 v116, 1.0, v98
	v_add_f32_e32 v117, 1.0, v99
	v_rcp_f32_e32 v96, v96
	v_rcp_f32_e32 v97, v97
	v_rcp_f32_e32 v98, v100
	v_rcp_f32_e32 v99, v101
	v_rcp_f32_e32 v100, v102
	v_rcp_f32_e32 v101, v103
	v_rcp_f32_e32 v102, v116
	v_rcp_f32_e32 v103, v117
	v_lshlrev_b64 v[114:115], 1, v[112:113]
	v_lshl_add_u64 v[116:117], s[16:17], 0, v[114:115]
	v_add_f32_e32 v52, 1.0, v52
	v_add_f32_e32 v53, 1.0, v53
	v_add_f32_e32 v54, 1.0, v54
	v_add_f32_e32 v55, 1.0, v55
	v_mul_f32_e32 v44, 0xbfb8aa3b, v44
	v_mul_f32_e32 v45, 0xbfb8aa3b, v45
	v_mul_f32_e32 v46, 0xbfb8aa3b, v46
	v_mul_f32_e32 v47, 0xbfb8aa3b, v47
	v_mul_f32_e32 v40, 0xbfb8aa3b, v40
	v_mul_f32_e32 v41, 0xbfb8aa3b, v41
	v_mul_f32_e32 v42, 0xbfb8aa3b, v42
	v_mul_f32_e32 v43, 0xbfb8aa3b, v43
	v_exp_f32_e32 v44, v44
	v_exp_f32_e32 v45, v45
	v_exp_f32_e32 v46, v46
	v_exp_f32_e32 v47, v47
	v_exp_f32_e32 v40, v40
	v_exp_f32_e32 v41, v41
	v_exp_f32_e32 v42, v42
	v_exp_f32_e32 v43, v43
	v_add_f32_e32 v44, 1.0, v44
	v_add_f32_e32 v45, 1.0, v45
	v_add_f32_e32 v46, 1.0, v46
	v_add_f32_e32 v47, 1.0, v47
	v_mul_f32_e32 v36, 0xbfb8aa3b, v36
	v_mul_f32_e32 v37, 0xbfb8aa3b, v37
	v_mul_f32_e32 v38, 0xbfb8aa3b, v38
	v_mul_f32_e32 v39, 0xbfb8aa3b, v39
	v_mul_f32_e32 v32, 0xbfb8aa3b, v32
	v_mul_f32_e32 v33, 0xbfb8aa3b, v33
	v_mul_f32_e32 v34, 0xbfb8aa3b, v34
	v_mul_f32_e32 v35, 0xbfb8aa3b, v35
	v_exp_f32_e32 v36, v36
	v_exp_f32_e32 v37, v37
	v_exp_f32_e32 v38, v38
	v_exp_f32_e32 v39, v39
	v_exp_f32_e32 v32, v32
	v_exp_f32_e32 v33, v33
	v_exp_f32_e32 v34, v34
	v_exp_f32_e32 v35, v35
	v_add_f32_e32 v36, 1.0, v36
	v_add_f32_e32 v37, 1.0, v37
	v_add_f32_e32 v38, 1.0, v38
	v_add_f32_e32 v39, 1.0, v39
	v_mul_f32_e32 v28, 0xbfb8aa3b, v28
	v_mul_f32_e32 v29, 0xbfb8aa3b, v29
	v_mul_f32_e32 v30, 0xbfb8aa3b, v30
	v_mul_f32_e32 v31, 0xbfb8aa3b, v31
	v_mul_f32_e32 v24, 0xbfb8aa3b, v24
	v_mul_f32_e32 v25, 0xbfb8aa3b, v25
	v_mul_f32_e32 v26, 0xbfb8aa3b, v26
	v_mul_f32_e32 v27, 0xbfb8aa3b, v27
	v_exp_f32_e32 v28, v28
	s_waitcnt vmcnt(1)
; __device__ __forceinline__ float bf_lo(unsigned w) { return __uint_as_float(w << 16); }
; __device__ __forceinline__ float bf_hi(unsigned w) { return __uint_as_float(w & 0xffff0000u); }
; __device__ __forceinline__ float sigmoid_f(float x) { return __builtin_amdgcn_rcpf(1.0f + __builtin_amdgcn_exp2f(-1.4426950408889634f * x)); }
;     __device__ __forceinline__ void operator()(const f32x4 (&acc)[2][2][4][2], const Unit& u, int wr, int wc, int fr, int fq) const {
;     ...
;             for (int m = 0; m < 4; ++m) { const int row = row0 + ai * HALF + m * 16; const size_t off = (size_t)row * 1024 + col0; float rs = 0.f;
; #pragma unroll
;                 for (int bj = 0; bj < 2; ++bj) { const size_t c = off + bj * HALF;
;                     const u32x4 hw = *(const u32x4*)(Hin + c); const u32x4 pw = *(const u32x4*)(PP + c);
;                     float o[8];
; #pragma unroll
;                     for (int n = 0; n < 2; ++n)
; #pragma unroll
;                         for (int w = 0; w < 2; ++w) { const unsigned hh = hw[2 * n + w], pp = pw[2 * n + w]; const f32x4 a = acc[ai][bj][m][n];
;                             o[4 * n + 2 * w] = bf_lo(hh) + bf_lo(pp) * sigmoid_f(a[2 * w]); o[4 * n + 2 * w + 1] = bf_hi(hh) + bf_hi(pp) * sigmoid_f(a[2 * w + 1]); }
;                     if (MODE == 1) { *(f32x4*)(Fout + c) = (f32x4){o[0], o[1], o[2], o[3]}; *(f32x4*)(Fout + c + 4) = (f32x4){o[4], o[5], o[6], o[7]}; }
	v_lshlrev_b32_e32 v118, 16, v104
	v_and_b32_e32 v119, 0xffff0000, v104
	v_lshlrev_b32_e32 v104, 16, v105
	s_waitcnt vmcnt(0)
	v_lshlrev_b32_e32 v122, 16, v108
	v_and_b32_e32 v123, 0xffff0000, v108
	v_and_b32_e32 v105, 0xffff0000, v105
	v_lshlrev_b32_e32 v108, 16, v109
	v_and_b32_e32 v109, 0xffff0000, v109
	v_lshlrev_b32_e32 v124, 16, v106
	v_and_b32_e32 v125, 0xffff0000, v106
	v_lshlrev_b32_e32 v126, 16, v110
	v_and_b32_e32 v127, 0xffff0000, v110
	v_lshlrev_b32_e32 v106, 16, v107
	v_and_b32_e32 v107, 0xffff0000, v107
	v_lshlrev_b32_e32 v110, 16, v111
	v_and_b32_e32 v111, 0xffff0000, v111
	v_fma_f32 v96, v96, v122, v118
	v_fma_f32 v97, v97, v123, v119
	v_fma_f32 v98, v98, v108, v104
	v_fma_f32 v99, v99, v109, v105
	v_fma_f32 v100, v100, v126, v124
	v_fma_f32 v101, v101, v127, v125
	v_fma_f32 v102, v102, v110, v106
	v_fma_f32 v103, v103, v111, v107
	global_store_dwordx4 v[120:121], v[96:99], off offset:512
	global_store_dwordx4 v[120:121], v[100:103], off offset:528
	global_load_dwordx4 v[96:99], v[116:117], off
	v_add_f32_e32 v106, 1.0, v88
	v_lshl_add_u64 v[100:101], s[36:37], 0, v[114:115]
	global_load_dwordx4 v[100:103], v[100:101], off
	v_add_f32_e32 v107, 1.0, v89
	v_add_f32_e32 v108, 1.0, v90
	v_add_f32_e32 v109, 1.0, v91
	v_rcp_f32_e32 v88, v92
	v_rcp_f32_e32 v89, v93
	v_rcp_f32_e32 v90, v94
	v_rcp_f32_e32 v91, v95
	v_rcp_f32_e32 v92, v106
	v_rcp_f32_e32 v93, v107
	v_rcp_f32_e32 v94, v108
	v_rcp_f32_e32 v95, v109
	v_lshl_add_u64 v[104:105], v[112:113], 2, s[58:59]
	v_or_b32_e32 v114, 0x100, v114
	v_lshl_add_u64 v[106:107], s[16:17], 0, v[114:115]
	v_exp_f32_e32 v29, v29
	v_exp_f32_e32 v30, v30
	v_exp_f32_e32 v31, v31
	v_exp_f32_e32 v24, v24
	v_exp_f32_e32 v25, v25
	v_exp_f32_e32 v26, v26
	v_exp_f32_e32 v27, v27
	v_add_f32_e32 v28, 1.0, v28
	v_add_f32_e32 v29, 1.0, v29
	v_add_f32_e32 v30, 1.0, v30
	v_add_f32_e32 v31, 1.0, v31
	v_mul_f32_e32 v20, 0xbfb8aa3b, v20
	v_mul_f32_e32 v21, 0xbfb8aa3b, v21
	v_mul_f32_e32 v22, 0xbfb8aa3b, v22
	v_mul_f32_e32 v23, 0xbfb8aa3b, v23
	v_mul_f32_e32 v16, 0xbfb8aa3b, v16
	v_mul_f32_e32 v17, 0xbfb8aa3b, v17
	v_mul_f32_e32 v18, 0xbfb8aa3b, v18
	v_mul_f32_e32 v19, 0xbfb8aa3b, v19
	v_exp_f32_e32 v20, v20
	v_exp_f32_e32 v21, v21
	v_exp_f32_e32 v22, v22
	v_exp_f32_e32 v23, v23
	v_exp_f32_e32 v16, v16
	v_exp_f32_e32 v17, v17
	v_exp_f32_e32 v18, v18
	v_exp_f32_e32 v19, v19
	v_add_f32_e32 v20, 1.0, v20
	v_add_f32_e32 v21, 1.0, v21
	v_add_f32_e32 v22, 1.0, v22
	v_add_f32_e32 v23, 1.0, v23
	v_mul_f32_e32 v12, 0xbfb8aa3b, v12
	v_mul_f32_e32 v13, 0xbfb8aa3b, v13
	v_mul_f32_e32 v14, 0xbfb8aa3b, v14
	v_mul_f32_e32 v15, 0xbfb8aa3b, v15
	v_mul_f32_e32 v8, 0xbfb8aa3b, v8
	v_mul_f32_e32 v9, 0xbfb8aa3b, v9
	v_mul_f32_e32 v10, 0xbfb8aa3b, v10
	v_mul_f32_e32 v11, 0xbfb8aa3b, v11
	v_exp_f32_e32 v12, v12
	v_exp_f32_e32 v13, v13
	v_exp_f32_e32 v14, v14
	v_exp_f32_e32 v15, v15
	v_exp_f32_e32 v8, v8
	v_exp_f32_e32 v9, v9
	v_exp_f32_e32 v10, v10
	v_exp_f32_e32 v11, v11
	v_add_f32_e32 v12, 1.0, v12
	v_add_f32_e32 v13, 1.0, v13
	v_add_f32_e32 v14, 1.0, v14
	v_add_f32_e32 v15, 1.0, v15
	v_mul_f32_e32 v4, 0xbfb8aa3b, v4
	v_mul_f32_e32 v5, 0xbfb8aa3b, v5
	v_mul_f32_e32 v6, 0xbfb8aa3b, v6
	v_mul_f32_e32 v7, 0xbfb8aa3b, v7
	v_mul_f32_e32 v0, 0xbfb8aa3b, v0
	v_mul_f32_e32 v1, 0xbfb8aa3b, v1
	v_mul_f32_e32 v2, 0xbfb8aa3b, v2
	v_mul_f32_e32 v3, 0xbfb8aa3b, v3
	v_exp_f32_e32 v4, v4
	v_exp_f32_e32 v5, v5
	v_exp_f32_e32 v6, v6
	s_waitcnt vmcnt(1)
	v_lshlrev_b32_e32 v108, 16, v96
	v_and_b32_e32 v109, 0xffff0000, v96
	v_lshlrev_b32_e32 v96, 16, v97
	s_waitcnt vmcnt(0)
	v_lshlrev_b32_e32 v110, 16, v100
	v_and_b32_e32 v111, 0xffff0000, v100
	v_and_b32_e32 v97, 0xffff0000, v97
	v_lshlrev_b32_e32 v100, 16, v101
	v_and_b32_e32 v101, 0xffff0000, v101
	v_lshlrev_b32_e32 v112, 16, v98
	v_and_b32_e32 v113, 0xffff0000, v98
	v_lshlrev_b32_e32 v116, 16, v102
	v_and_b32_e32 v117, 0xffff0000, v102
	v_lshlrev_b32_e32 v98, 16, v99
	v_and_b32_e32 v99, 0xffff0000, v99
	v_lshlrev_b32_e32 v102, 16, v103
	v_and_b32_e32 v103, 0xffff0000, v103
	v_fma_f32 v88, v88, v110, v108
	v_fma_f32 v89, v89, v111, v109
	v_fma_f32 v90, v90, v100, v96
	v_fma_f32 v91, v91, v101, v97
	v_fma_f32 v92, v92, v116, v112
	v_fma_f32 v93, v93, v117, v113
	v_fma_f32 v94, v94, v102, v98
	v_fma_f32 v95, v95, v103, v99
	global_store_dwordx4 v[104:105], v[88:91], off
	global_store_dwordx4 v[104:105], v[92:95], off offset:16
	global_load_dwordx4 v[88:91], v[106:107], off
	v_exp_f32_e32 v98, v80
	v_lshl_add_u64 v[92:93], s[36:37], 0, v[114:115]
	global_load_dwordx4 v[92:95], v[92:93], off
	v_exp_f32_e32 v99, v81
	v_or_b32_e32 v80, 48, v148
	v_ashrrev_i32_e32 v81, 31, v80
	v_lshlrev_b64 v[80:81], 10, v[80:81]
	v_lshl_add_u64 v[96:97], v[80:81], 0, v[146:147]
	v_add_f32_e32 v80, 1.0, v84
	v_add_f32_e32 v81, 1.0, v85
	v_add_f32_e32 v84, 1.0, v86
	v_add_f32_e32 v85, 1.0, v87
	v_add_f32_e32 v86, 1.0, v98
	v_add_f32_e32 v87, 1.0, v99
	v_add_f32_e32 v100, 1.0, v82
	v_add_f32_e32 v101, 1.0, v83
	v_rcp_f32_e32 v80, v80
	v_rcp_f32_e32 v81, v81
	v_rcp_f32_e32 v82, v84
	v_rcp_f32_e32 v83, v85
	v_rcp_f32_e32 v84, v86
	v_rcp_f32_e32 v85, v87
	v_rcp_f32_e32 v86, v100
	v_rcp_f32_e32 v87, v101
	v_lshlrev_b64 v[98:99], 1, v[96:97]
	v_lshl_add_u64 v[100:101], s[16:17], 0, v[98:99]
	v_exp_f32_e32 v7, v7
	v_exp_f32_e32 v0, v0
	v_exp_f32_e32 v1, v1
	v_exp_f32_e32 v2, v2
	v_exp_f32_e32 v3, v3
	v_add_f32_e32 v4, 1.0, v4
	v_add_f32_e32 v5, 1.0, v5
	v_add_f32_e32 v6, 1.0, v6
	v_add_f32_e32 v7, 1.0, v7
	s_andn2_b64 vcc, exec, s[0:1]
	s_mov_b64 s[0:1], -1
	s_waitcnt vmcnt(1)
	v_lshlrev_b32_e32 v102, 16, v88
	v_and_b32_e32 v103, 0xffff0000, v88
	v_lshlrev_b32_e32 v88, 16, v89
	s_waitcnt vmcnt(0)
; __device__ __forceinline__ float bf_lo(unsigned w) { return __uint_as_float(w << 16); }
; __device__ __forceinline__ float bf_hi(unsigned w) { return __uint_as_float(w & 0xffff0000u); }
; __device__ __forceinline__ float sigmoid_f(float x) { return __builtin_amdgcn_rcpf(1.0f + __builtin_amdgcn_exp2f(-1.4426950408889634f * x)); }
;     __device__ __forceinline__ void operator()(const f32x4 (&acc)[2][2][4][2], const Unit& u, int wr, int wc, int fr, int fq) const {
;     ...
;             for (int m = 0; m < 4; ++m) { const int row = row0 + ai * HALF + m * 16; const size_t off = (size_t)row * 1024 + col0; float rs = 0.f;
; #pragma unroll
;                 for (int bj = 0; bj < 2; ++bj) { const size_t c = off + bj * HALF;
;                     const u32x4 hw = *(const u32x4*)(Hin + c); const u32x4 pw = *(const u32x4*)(PP + c);
;                     float o[8];
; #pragma unroll
;                     for (int n = 0; n < 2; ++n)
; #pragma unroll
;                         for (int w = 0; w < 2; ++w) { const unsigned hh = hw[2 * n + w], pp = pw[2 * n + w]; const f32x4 a = acc[ai][bj][m][n];
;                             o[4 * n + 2 * w] = bf_lo(hh) + bf_lo(pp) * sigmoid_f(a[2 * w]); o[4 * n + 2 * w + 1] = bf_hi(hh) + bf_hi(pp) * sigmoid_f(a[2 * w + 1]); }
;                     if (MODE == 1) { *(f32x4*)(Fout + c) = (f32x4){o[0], o[1], o[2], o[3]}; *(f32x4*)(Fout + c + 4) = (f32x4){o[4], o[5], o[6], o[7]}; }
	v_lshlrev_b32_e32 v106, 16, v92
	v_and_b32_e32 v107, 0xffff0000, v92
	v_and_b32_e32 v89, 0xffff0000, v89
	v_lshlrev_b32_e32 v92, 16, v93
	v_and_b32_e32 v93, 0xffff0000, v93
	v_lshlrev_b32_e32 v108, 16, v90
	v_and_b32_e32 v109, 0xffff0000, v90
	v_lshlrev_b32_e32 v110, 16, v94
	v_and_b32_e32 v111, 0xffff0000, v94
	v_lshlrev_b32_e32 v90, 16, v91
	v_and_b32_e32 v91, 0xffff0000, v91
	v_lshlrev_b32_e32 v94, 16, v95
	v_and_b32_e32 v95, 0xffff0000, v95
	v_fma_f32 v80, v80, v106, v102
	v_fma_f32 v81, v81, v107, v103
	v_fma_f32 v82, v82, v92, v88
	v_fma_f32 v83, v83, v93, v89
	v_fma_f32 v84, v84, v110, v108
	v_fma_f32 v85, v85, v111, v109
	v_fma_f32 v86, v86, v94, v90
	v_fma_f32 v87, v87, v95, v91
	global_store_dwordx4 v[104:105], v[80:83], off offset:512
	global_store_dwordx4 v[104:105], v[84:87], off offset:528
	global_load_dwordx4 v[80:83], v[100:101], off
	v_add_f32_e32 v90, 1.0, v72
	v_lshl_add_u64 v[84:85], s[36:37], 0, v[98:99]
	global_load_dwordx4 v[84:87], v[84:85], off
	v_add_f32_e32 v91, 1.0, v73
	v_add_f32_e32 v92, 1.0, v74
	v_add_f32_e32 v93, 1.0, v75
	v_rcp_f32_e32 v72, v76
	v_rcp_f32_e32 v73, v77
	v_rcp_f32_e32 v74, v78
	v_rcp_f32_e32 v75, v79
	v_rcp_f32_e32 v76, v90
	v_rcp_f32_e32 v77, v91
	v_rcp_f32_e32 v78, v92
	v_rcp_f32_e32 v79, v93
	v_lshl_add_u64 v[88:89], v[96:97], 2, s[58:59]
	v_or_b32_e32 v98, 0x100, v98
	v_lshl_add_u64 v[90:91], s[16:17], 0, v[98:99]
	s_waitcnt vmcnt(1)
	v_lshlrev_b32_e32 v92, 16, v80
	v_and_b32_e32 v93, 0xffff0000, v80
	v_lshlrev_b32_e32 v80, 16, v81
	s_waitcnt vmcnt(0)
	v_lshlrev_b32_e32 v94, 16, v84
	v_and_b32_e32 v95, 0xffff0000, v84
	v_and_b32_e32 v81, 0xffff0000, v81
	v_lshlrev_b32_e32 v84, 16, v85
	v_and_b32_e32 v85, 0xffff0000, v85
	v_lshlrev_b32_e32 v96, 16, v82
	v_and_b32_e32 v97, 0xffff0000, v82
	v_lshlrev_b32_e32 v100, 16, v86
	v_and_b32_e32 v101, 0xffff0000, v86
	v_lshlrev_b32_e32 v82, 16, v83
	v_and_b32_e32 v83, 0xffff0000, v83
	v_lshlrev_b32_e32 v86, 16, v87
	v_and_b32_e32 v87, 0xffff0000, v87
	v_fma_f32 v72, v72, v94, v92
	v_fma_f32 v73, v73, v95, v93
	v_fma_f32 v74, v74, v84, v80
	v_fma_f32 v75, v75, v85, v81
	v_fma_f32 v76, v76, v100, v96
	v_fma_f32 v77, v77, v101, v97
	v_fma_f32 v78, v78, v86, v82
	v_fma_f32 v79, v79, v87, v83
	global_store_dwordx4 v[88:89], v[72:75], off
	global_store_dwordx4 v[88:89], v[76:79], off offset:16
	global_load_dwordx4 v[72:75], v[90:91], off
	v_add_f32_e32 v84, 1.0, v64
	v_lshl_add_u64 v[76:77], s[36:37], 0, v[98:99]
	global_load_dwordx4 v[76:79], v[76:77], off
	v_add_f32_e32 v85, 1.0, v65
	v_add_f32_e32 v86, 1.0, v66
	v_add_f32_e32 v87, 1.0, v67
	v_rcp_f32_e32 v64, v68
	v_rcp_f32_e32 v65, v69
	v_rcp_f32_e32 v66, v70
	v_rcp_f32_e32 v67, v71
	v_rcp_f32_e32 v68, v84
	v_rcp_f32_e32 v69, v85
	v_rcp_f32_e32 v70, v86
	v_rcp_f32_e32 v71, v87
	v_lshl_add_u64 v[80:81], v[144:145], 0, s[12:13]
	v_lshlrev_b64 v[82:83], 1, v[80:81]
	v_lshl_add_u64 v[84:85], s[16:17], 0, v[82:83]
	s_waitcnt vmcnt(1)
	v_lshlrev_b32_e32 v86, 16, v72
	v_and_b32_e32 v87, 0xffff0000, v72
	v_lshlrev_b32_e32 v72, 16, v73
	s_waitcnt vmcnt(0)
	v_lshlrev_b32_e32 v90, 16, v76
	v_and_b32_e32 v91, 0xffff0000, v76
	v_and_b32_e32 v73, 0xffff0000, v73
	v_lshlrev_b32_e32 v76, 16, v77
	v_and_b32_e32 v77, 0xffff0000, v77
	v_lshlrev_b32_e32 v92, 16, v74
	v_and_b32_e32 v93, 0xffff0000, v74
	v_lshlrev_b32_e32 v94, 16, v78
	v_and_b32_e32 v95, 0xffff0000, v78
	v_lshlrev_b32_e32 v74, 16, v75
	v_and_b32_e32 v75, 0xffff0000, v75
	v_lshlrev_b32_e32 v78, 16, v79
	v_and_b32_e32 v79, 0xffff0000, v79
	v_fma_f32 v64, v64, v90, v86
	v_fma_f32 v65, v65, v91, v87
	v_fma_f32 v66, v66, v76, v72
	v_fma_f32 v67, v67, v77, v73
	v_fma_f32 v68, v68, v94, v92
	v_fma_f32 v69, v69, v95, v93
	v_fma_f32 v70, v70, v78, v74
	v_fma_f32 v71, v71, v79, v75
	global_store_dwordx4 v[88:89], v[64:67], off offset:512
	global_store_dwordx4 v[88:89], v[68:71], off offset:528
	global_load_dwordx4 v[64:67], v[84:85], off
	v_add_f32_e32 v74, 1.0, v56
	v_lshl_add_u64 v[68:69], s[36:37], 0, v[82:83]
	global_load_dwordx4 v[68:71], v[68:69], off
	v_add_f32_e32 v75, 1.0, v57
	v_add_f32_e32 v76, 1.0, v58
	v_add_f32_e32 v77, 1.0, v59
	v_rcp_f32_e32 v56, v60
	v_rcp_f32_e32 v57, v61
	v_rcp_f32_e32 v58, v62
	v_rcp_f32_e32 v59, v63
	v_rcp_f32_e32 v60, v74
	v_rcp_f32_e32 v61, v75
	v_rcp_f32_e32 v62, v76
	v_rcp_f32_e32 v63, v77
	v_lshl_add_u64 v[72:73], v[80:81], 2, s[58:59]
	v_or_b32_e32 v82, 0x100, v82
	v_lshl_add_u64 v[74:75], s[16:17], 0, v[82:83]
	s_waitcnt vmcnt(1)
	v_lshlrev_b32_e32 v76, 16, v64
	v_and_b32_e32 v77, 0xffff0000, v64
	v_lshlrev_b32_e32 v64, 16, v65
	s_waitcnt vmcnt(0)
	v_lshlrev_b32_e32 v78, 16, v68
	v_and_b32_e32 v79, 0xffff0000, v68
	v_and_b32_e32 v65, 0xffff0000, v65
	v_lshlrev_b32_e32 v68, 16, v69
	v_and_b32_e32 v69, 0xffff0000, v69
	v_lshlrev_b32_e32 v80, 16, v66
	v_and_b32_e32 v81, 0xffff0000, v66
	v_lshlrev_b32_e32 v84, 16, v70
	v_and_b32_e32 v85, 0xffff0000, v70
	v_lshlrev_b32_e32 v66, 16, v67
	v_and_b32_e32 v67, 0xffff0000, v67
	v_lshlrev_b32_e32 v70, 16, v71
	v_and_b32_e32 v71, 0xffff0000, v71
	v_fma_f32 v56, v56, v78, v76
	v_fma_f32 v57, v57, v79, v77
	v_fma_f32 v58, v58, v68, v64
	v_fma_f32 v59, v59, v69, v65
	v_fma_f32 v60, v60, v84, v80
	v_fma_f32 v61, v61, v85, v81
	v_fma_f32 v62, v62, v70, v66
	v_fma_f32 v63, v63, v71, v67
	global_store_dwordx4 v[72:73], v[56:59], off
	global_store_dwordx4 v[72:73], v[60:63], off offset:16
	global_load_dwordx4 v[56:59], v[74:75], off
	v_add_f32_e32 v68, 1.0, v48
	v_lshl_add_u64 v[60:61], s[36:37], 0, v[82:83]
	global_load_dwordx4 v[60:63], v[60:61], off
	v_add_f32_e32 v69, 1.0, v49
	v_add_f32_e32 v70, 1.0, v50
	v_add_f32_e32 v71, 1.0, v51
	v_rcp_f32_e32 v48, v52
	v_rcp_f32_e32 v49, v53
	v_rcp_f32_e32 v50, v54
	v_rcp_f32_e32 v51, v55
	v_rcp_f32_e32 v52, v68
	v_rcp_f32_e32 v53, v69
	v_rcp_f32_e32 v54, v70
	v_rcp_f32_e32 v55, v71
	v_lshl_add_u64 v[64:65], v[144:145], 0, s[14:15]
	v_lshlrev_b64 v[66:67], 1, v[64:65]
	v_lshl_add_u64 v[68:69], s[16:17], 0, v[66:67]
	s_waitcnt vmcnt(1)
; __device__ __forceinline__ float bf_lo(unsigned w) { return __uint_as_float(w << 16); }
; __device__ __forceinline__ float bf_hi(unsigned w) { return __uint_as_float(w & 0xffff0000u); }
; __device__ __forceinline__ float sigmoid_f(float x) { return __builtin_amdgcn_rcpf(1.0f + __builtin_amdgcn_exp2f(-1.4426950408889634f * x)); }
;     __device__ __forceinline__ void operator()(const f32x4 (&acc)[2][2][4][2], const Unit& u, int wr, int wc, int fr, int fq) const {
;     ...
;             for (int m = 0; m < 4; ++m) { const int row = row0 + ai * HALF + m * 16; const size_t off = (size_t)row * 1024 + col0; float rs = 0.f;
; #pragma unroll
;                 for (int bj = 0; bj < 2; ++bj) { const size_t c = off + bj * HALF;
;                     const u32x4 hw = *(const u32x4*)(Hin + c); const u32x4 pw = *(const u32x4*)(PP + c);
;                     float o[8];
; #pragma unroll
;                     for (int n = 0; n < 2; ++n)
; #pragma unroll
;                         for (int w = 0; w < 2; ++w) { const unsigned hh = hw[2 * n + w], pp = pw[2 * n + w]; const f32x4 a = acc[ai][bj][m][n];
;                             o[4 * n + 2 * w] = bf_lo(hh) + bf_lo(pp) * sigmoid_f(a[2 * w]); o[4 * n + 2 * w + 1] = bf_hi(hh) + bf_hi(pp) * sigmoid_f(a[2 * w + 1]); }
;                     if (MODE == 1) { *(f32x4*)(Fout + c) = (f32x4){o[0], o[1], o[2], o[3]}; *(f32x4*)(Fout + c + 4) = (f32x4){o[4], o[5], o[6], o[7]}; }
	v_lshlrev_b32_e32 v70, 16, v56
	v_and_b32_e32 v71, 0xffff0000, v56
	v_lshlrev_b32_e32 v56, 16, v57
	s_waitcnt vmcnt(0)
	v_lshlrev_b32_e32 v74, 16, v60
	v_and_b32_e32 v75, 0xffff0000, v60
	v_and_b32_e32 v57, 0xffff0000, v57
	v_lshlrev_b32_e32 v60, 16, v61
	v_and_b32_e32 v61, 0xffff0000, v61
	v_lshlrev_b32_e32 v76, 16, v58
	v_and_b32_e32 v77, 0xffff0000, v58
	v_lshlrev_b32_e32 v78, 16, v62
	v_and_b32_e32 v79, 0xffff0000, v62
	v_lshlrev_b32_e32 v58, 16, v59
	v_and_b32_e32 v59, 0xffff0000, v59
	v_lshlrev_b32_e32 v62, 16, v63
	v_and_b32_e32 v63, 0xffff0000, v63
	v_fma_f32 v48, v48, v74, v70
	v_fma_f32 v49, v49, v75, v71
	v_fma_f32 v50, v50, v60, v56
	v_fma_f32 v51, v51, v61, v57
	v_fma_f32 v52, v52, v78, v76
	v_fma_f32 v53, v53, v79, v77
	v_fma_f32 v54, v54, v62, v58
	v_fma_f32 v55, v55, v63, v59
	global_store_dwordx4 v[72:73], v[48:51], off offset:512
	global_store_dwordx4 v[72:73], v[52:55], off offset:528
	global_load_dwordx4 v[48:51], v[68:69], off
	v_add_f32_e32 v58, 1.0, v40
	v_lshl_add_u64 v[52:53], s[36:37], 0, v[66:67]
	global_load_dwordx4 v[52:55], v[52:53], off
	v_add_f32_e32 v59, 1.0, v41
	v_add_f32_e32 v60, 1.0, v42
	v_add_f32_e32 v61, 1.0, v43
	v_rcp_f32_e32 v40, v44
	v_rcp_f32_e32 v41, v45
	v_rcp_f32_e32 v42, v46
	v_rcp_f32_e32 v43, v47
	v_rcp_f32_e32 v44, v58
	v_rcp_f32_e32 v45, v59
	v_rcp_f32_e32 v46, v60
	v_rcp_f32_e32 v47, v61
	v_lshl_add_u64 v[56:57], v[64:65], 2, s[58:59]
	v_or_b32_e32 v66, 0x100, v66
	v_lshl_add_u64 v[58:59], s[16:17], 0, v[66:67]
	s_waitcnt vmcnt(1)
	v_lshlrev_b32_e32 v60, 16, v48
	v_and_b32_e32 v61, 0xffff0000, v48
	v_lshlrev_b32_e32 v48, 16, v49
	s_waitcnt vmcnt(0)
	v_lshlrev_b32_e32 v62, 16, v52
	v_and_b32_e32 v63, 0xffff0000, v52
	v_and_b32_e32 v49, 0xffff0000, v49
	v_lshlrev_b32_e32 v52, 16, v53
	v_and_b32_e32 v53, 0xffff0000, v53
	v_lshlrev_b32_e32 v64, 16, v50
	v_and_b32_e32 v65, 0xffff0000, v50
	v_lshlrev_b32_e32 v68, 16, v54
	v_and_b32_e32 v69, 0xffff0000, v54
	v_lshlrev_b32_e32 v50, 16, v51
	v_and_b32_e32 v51, 0xffff0000, v51
	v_lshlrev_b32_e32 v54, 16, v55
	v_and_b32_e32 v55, 0xffff0000, v55
	v_fma_f32 v40, v40, v62, v60
	v_fma_f32 v41, v41, v63, v61
	v_fma_f32 v42, v42, v52, v48
	v_fma_f32 v43, v43, v53, v49
	v_fma_f32 v44, v44, v68, v64
	v_fma_f32 v45, v45, v69, v65
	v_fma_f32 v46, v46, v54, v50
	v_fma_f32 v47, v47, v55, v51
	global_store_dwordx4 v[56:57], v[40:43], off
	global_store_dwordx4 v[56:57], v[44:47], off offset:16
	global_load_dwordx4 v[40:43], v[58:59], off
	v_add_f32_e32 v52, 1.0, v32
	v_lshl_add_u64 v[44:45], s[36:37], 0, v[66:67]
	global_load_dwordx4 v[44:47], v[44:45], off
	v_add_f32_e32 v53, 1.0, v33
	v_add_f32_e32 v54, 1.0, v34
	v_add_f32_e32 v55, 1.0, v35
	v_rcp_f32_e32 v32, v36
	v_rcp_f32_e32 v33, v37
	v_rcp_f32_e32 v34, v38
	v_rcp_f32_e32 v35, v39
	v_rcp_f32_e32 v36, v52
	v_rcp_f32_e32 v37, v53
	v_rcp_f32_e32 v38, v54
	v_rcp_f32_e32 v39, v55
	v_lshl_add_u64 v[48:49], v[144:145], 0, s[18:19]
	v_lshlrev_b64 v[50:51], 1, v[48:49]
	v_lshl_add_u64 v[52:53], s[16:17], 0, v[50:51]
	s_waitcnt vmcnt(1)
	v_lshlrev_b32_e32 v54, 16, v40
	v_and_b32_e32 v55, 0xffff0000, v40
	v_lshlrev_b32_e32 v40, 16, v41
	s_waitcnt vmcnt(0)
	v_lshlrev_b32_e32 v58, 16, v44
	v_and_b32_e32 v59, 0xffff0000, v44
	v_and_b32_e32 v41, 0xffff0000, v41
	v_lshlrev_b32_e32 v44, 16, v45
	v_and_b32_e32 v45, 0xffff0000, v45
	v_lshlrev_b32_e32 v60, 16, v42
	v_and_b32_e32 v61, 0xffff0000, v42
	v_lshlrev_b32_e32 v62, 16, v46
	v_and_b32_e32 v63, 0xffff0000, v46
	v_lshlrev_b32_e32 v42, 16, v43
	v_and_b32_e32 v43, 0xffff0000, v43
	v_lshlrev_b32_e32 v46, 16, v47
	v_and_b32_e32 v47, 0xffff0000, v47
	v_fma_f32 v32, v32, v58, v54
	v_fma_f32 v33, v33, v59, v55
	v_fma_f32 v34, v34, v44, v40
	v_fma_f32 v35, v35, v45, v41
	v_fma_f32 v36, v36, v62, v60
	v_fma_f32 v37, v37, v63, v61
	v_fma_f32 v38, v38, v46, v42
	v_fma_f32 v39, v39, v47, v43
	global_store_dwordx4 v[56:57], v[32:35], off offset:512
	global_store_dwordx4 v[56:57], v[36:39], off offset:528
	global_load_dwordx4 v[32:35], v[52:53], off
	v_add_f32_e32 v42, 1.0, v24
	v_lshl_add_u64 v[36:37], s[36:37], 0, v[50:51]
	global_load_dwordx4 v[36:39], v[36:37], off
	v_add_f32_e32 v43, 1.0, v25
	v_add_f32_e32 v44, 1.0, v26
	v_add_f32_e32 v45, 1.0, v27
	v_rcp_f32_e32 v24, v28
	v_rcp_f32_e32 v25, v29
	v_rcp_f32_e32 v26, v30
	v_rcp_f32_e32 v27, v31
	v_rcp_f32_e32 v28, v42
	v_rcp_f32_e32 v29, v43
	v_rcp_f32_e32 v30, v44
	v_rcp_f32_e32 v31, v45
	v_lshl_add_u64 v[40:41], v[48:49], 2, s[58:59]
	v_or_b32_e32 v50, 0x100, v50
	v_lshl_add_u64 v[42:43], s[16:17], 0, v[50:51]
	s_waitcnt vmcnt(1)
	v_lshlrev_b32_e32 v44, 16, v32
	v_and_b32_e32 v45, 0xffff0000, v32
	v_lshlrev_b32_e32 v32, 16, v33
	s_waitcnt vmcnt(0)
; __device__ __forceinline__ float bf_lo(unsigned w) { return __uint_as_float(w << 16); }
; __device__ __forceinline__ float bf_hi(unsigned w) { return __uint_as_float(w & 0xffff0000u); }
; __device__ __forceinline__ float sigmoid_f(float x) { return __builtin_amdgcn_rcpf(1.0f + __builtin_amdgcn_exp2f(-1.4426950408889634f * x)); }
;     __device__ __forceinline__ void operator()(const f32x4 (&acc)[2][2][4][2], const Unit& u, int wr, int wc, int fr, int fq) const {
;     ...
;             for (int m = 0; m < 4; ++m) { const int row = row0 + ai * HALF + m * 16; const size_t off = (size_t)row * 1024 + col0; float rs = 0.f;
; #pragma unroll
;                 for (int bj = 0; bj < 2; ++bj) { const size_t c = off + bj * HALF;
;                     const u32x4 hw = *(const u32x4*)(Hin + c); const u32x4 pw = *(const u32x4*)(PP + c);
;                     float o[8];
; #pragma unroll
;                     for (int n = 0; n < 2; ++n)
; #pragma unroll
;                         for (int w = 0; w < 2; ++w) { const unsigned hh = hw[2 * n + w], pp = pw[2 * n + w]; const f32x4 a = acc[ai][bj][m][n];
;                             o[4 * n + 2 * w] = bf_lo(hh) + bf_lo(pp) * sigmoid_f(a[2 * w]); o[4 * n + 2 * w + 1] = bf_hi(hh) + bf_hi(pp) * sigmoid_f(a[2 * w + 1]); }
;                     if (MODE == 1) { *(f32x4*)(Fout + c) = (f32x4){o[0], o[1], o[2], o[3]}; *(f32x4*)(Fout + c + 4) = (f32x4){o[4], o[5], o[6], o[7]}; }
	v_lshlrev_b32_e32 v46, 16, v36
	v_and_b32_e32 v47, 0xffff0000, v36
	v_and_b32_e32 v33, 0xffff0000, v33
	v_lshlrev_b32_e32 v36, 16, v37
	v_and_b32_e32 v37, 0xffff0000, v37
	v_lshlrev_b32_e32 v48, 16, v34
	v_and_b32_e32 v49, 0xffff0000, v34
	v_lshlrev_b32_e32 v52, 16, v38
	v_and_b32_e32 v53, 0xffff0000, v38
	v_lshlrev_b32_e32 v34, 16, v35
	v_and_b32_e32 v35, 0xffff0000, v35
	v_lshlrev_b32_e32 v38, 16, v39
	v_and_b32_e32 v39, 0xffff0000, v39
	v_fma_f32 v24, v24, v46, v44
	v_fma_f32 v25, v25, v47, v45
	v_fma_f32 v26, v26, v36, v32
	v_fma_f32 v27, v27, v37, v33
	v_fma_f32 v28, v28, v52, v48
	v_fma_f32 v29, v29, v53, v49
	v_fma_f32 v30, v30, v38, v34
	v_fma_f32 v31, v31, v39, v35
	global_store_dwordx4 v[40:41], v[24:27], off
	global_store_dwordx4 v[40:41], v[28:31], off offset:16
	global_load_dwordx4 v[24:27], v[42:43], off
	v_add_f32_e32 v36, 1.0, v16
	v_lshl_add_u64 v[28:29], s[36:37], 0, v[50:51]
	global_load_dwordx4 v[28:31], v[28:29], off
	v_add_f32_e32 v37, 1.0, v17
	v_add_f32_e32 v38, 1.0, v18
	v_add_f32_e32 v39, 1.0, v19
	v_rcp_f32_e32 v16, v20
	v_rcp_f32_e32 v17, v21
	v_rcp_f32_e32 v18, v22
	v_rcp_f32_e32 v19, v23
	v_rcp_f32_e32 v20, v36
	v_rcp_f32_e32 v21, v37
	v_rcp_f32_e32 v22, v38
	v_rcp_f32_e32 v23, v39
	v_lshl_add_u64 v[32:33], v[144:145], 0, s[20:21]
	v_lshlrev_b64 v[34:35], 1, v[32:33]
	v_lshl_add_u64 v[36:37], s[16:17], 0, v[34:35]
	s_waitcnt vmcnt(1)
	v_lshlrev_b32_e32 v38, 16, v24
	v_and_b32_e32 v39, 0xffff0000, v24
	v_lshlrev_b32_e32 v24, 16, v25
	s_waitcnt vmcnt(0)
	v_lshlrev_b32_e32 v42, 16, v28
	v_and_b32_e32 v43, 0xffff0000, v28
	v_and_b32_e32 v25, 0xffff0000, v25
	v_lshlrev_b32_e32 v28, 16, v29
	v_and_b32_e32 v29, 0xffff0000, v29
	v_lshlrev_b32_e32 v44, 16, v26
	v_and_b32_e32 v45, 0xffff0000, v26
	v_lshlrev_b32_e32 v46, 16, v30
	v_and_b32_e32 v47, 0xffff0000, v30
	v_lshlrev_b32_e32 v26, 16, v27
	v_and_b32_e32 v27, 0xffff0000, v27
	v_lshlrev_b32_e32 v30, 16, v31
	v_and_b32_e32 v31, 0xffff0000, v31
	v_fma_f32 v16, v16, v42, v38
	v_fma_f32 v17, v17, v43, v39
	v_fma_f32 v18, v18, v28, v24
	v_fma_f32 v19, v19, v29, v25
	v_fma_f32 v20, v20, v46, v44
	v_fma_f32 v21, v21, v47, v45
	v_fma_f32 v22, v22, v30, v26
	v_fma_f32 v23, v23, v31, v27
	global_store_dwordx4 v[40:41], v[16:19], off offset:512
	global_store_dwordx4 v[40:41], v[20:23], off offset:528
	global_load_dwordx4 v[16:19], v[36:37], off
	v_add_f32_e32 v26, 1.0, v8
	v_lshl_add_u64 v[20:21], s[36:37], 0, v[34:35]
	global_load_dwordx4 v[20:23], v[20:21], off
	v_add_f32_e32 v27, 1.0, v9
	v_add_f32_e32 v28, 1.0, v10
	v_add_f32_e32 v29, 1.0, v11
	v_rcp_f32_e32 v8, v12
	v_rcp_f32_e32 v9, v13
	v_rcp_f32_e32 v10, v14
	v_rcp_f32_e32 v11, v15
	v_rcp_f32_e32 v12, v26
	v_rcp_f32_e32 v13, v27
	v_rcp_f32_e32 v14, v28
	v_rcp_f32_e32 v15, v29
	v_lshl_add_u64 v[24:25], v[32:33], 2, s[58:59]
	v_or_b32_e32 v34, 0x100, v34
	v_lshl_add_u64 v[26:27], s[16:17], 0, v[34:35]
	s_waitcnt vmcnt(1)
	v_lshlrev_b32_e32 v28, 16, v16
	v_and_b32_e32 v29, 0xffff0000, v16
	v_lshlrev_b32_e32 v16, 16, v17
	s_waitcnt vmcnt(0)
	v_lshlrev_b32_e32 v30, 16, v20
	v_and_b32_e32 v31, 0xffff0000, v20
	v_and_b32_e32 v17, 0xffff0000, v17
	v_lshlrev_b32_e32 v20, 16, v21
	v_and_b32_e32 v21, 0xffff0000, v21
	v_lshlrev_b32_e32 v32, 16, v18
	v_and_b32_e32 v33, 0xffff0000, v18
	v_lshlrev_b32_e32 v36, 16, v22
	v_and_b32_e32 v37, 0xffff0000, v22
	v_lshlrev_b32_e32 v18, 16, v19
	v_and_b32_e32 v19, 0xffff0000, v19
	v_lshlrev_b32_e32 v22, 16, v23
	v_and_b32_e32 v23, 0xffff0000, v23
	v_fma_f32 v8, v8, v30, v28
	v_fma_f32 v9, v9, v31, v29
	v_fma_f32 v10, v10, v20, v16
	v_fma_f32 v11, v11, v21, v17
	v_fma_f32 v12, v12, v36, v32
	v_fma_f32 v13, v13, v37, v33
	v_fma_f32 v14, v14, v22, v18
	v_fma_f32 v15, v15, v23, v19
	global_store_dwordx4 v[24:25], v[8:11], off
	global_store_dwordx4 v[24:25], v[12:15], off offset:16
	global_load_dwordx4 v[8:11], v[26:27], off
	v_add_f32_e32 v16, 1.0, v0
	v_lshl_add_u64 v[12:13], s[36:37], 0, v[34:35]
	global_load_dwordx4 v[12:15], v[12:13], off
	v_add_f32_e32 v17, 1.0, v1
	v_add_f32_e32 v18, 1.0, v2
	v_add_f32_e32 v19, 1.0, v3
	v_rcp_f32_e32 v0, v4
	v_rcp_f32_e32 v1, v5
	v_rcp_f32_e32 v2, v6
	v_rcp_f32_e32 v3, v7
	v_rcp_f32_e32 v4, v16
	v_rcp_f32_e32 v5, v17
	v_rcp_f32_e32 v6, v18
	v_rcp_f32_e32 v7, v19
	s_waitcnt vmcnt(1)
	v_lshlrev_b32_e32 v16, 16, v8
	v_and_b32_e32 v17, 0xffff0000, v8
	v_lshlrev_b32_e32 v8, 16, v9
	s_waitcnt vmcnt(0)
	v_lshlrev_b32_e32 v18, 16, v12
	v_and_b32_e32 v19, 0xffff0000, v12
	v_and_b32_e32 v9, 0xffff0000, v9
	v_lshlrev_b32_e32 v12, 16, v13
	v_and_b32_e32 v13, 0xffff0000, v13
	v_lshlrev_b32_e32 v20, 16, v10
	v_and_b32_e32 v21, 0xffff0000, v10
	v_lshlrev_b32_e32 v22, 16, v14
	v_and_b32_e32 v23, 0xffff0000, v14
	v_lshlrev_b32_e32 v10, 16, v11
	v_and_b32_e32 v11, 0xffff0000, v11
	v_lshlrev_b32_e32 v14, 16, v15
	v_and_b32_e32 v15, 0xffff0000, v15
	v_fma_f32 v0, v0, v18, v16
	v_fma_f32 v1, v1, v19, v17
	v_fma_f32 v2, v2, v12, v8
	v_fma_f32 v3, v3, v13, v9
	v_fma_f32 v4, v4, v22, v20
	v_fma_f32 v5, v5, v23, v21
	v_fma_f32 v6, v6, v14, v10
	v_fma_f32 v7, v7, v15, v11
	global_store_dwordx4 v[24:25], v[0:3], off offset:512
	global_store_dwordx4 v[24:25], v[4:7], off offset:528
	s_cbranch_vccnz .LBB0_1609
	s_andn2_b64 vcc, exec, s[4:5]
	s_cbranch_vccnz .LBB0_1608
	s_barrier
	s_branch .LBB0_1608
